# SSM B*u without permlane swaps: row-masked A operands, two chained 32x32x16 MFMAs per state block
# speedup vs baseline: 1.0084x; 1.0029x over previous
.LBB0_340:
	s_cmp_lt_i32 s96, 4
	s_cselect_b64 s[0:1], -1, 0
	s_and_b64 s[8:9], s[0:1], s[4:5]
	s_andn2_b64 vcc, exec, s[8:9]
	s_cbranch_vccnz .LBB0_393
	v_cmp_gt_u32_e32 vcc, 2, v190
	s_and_saveexec_b64 s[0:1], vcc
	v_lshlrev_b32_e32 v2, 2, v190
	v_add_u32_e32 v2, 0x21000, v2
	v_mov_b32_e32 v3, 0
	ds_write_b32 v2, v3
	s_mov_b64 exec, s[0:1]
	v_and_b32_e32 v172, 31, v191
	v_lshrrev_b32_e32 v173, 5, v191
	v_and_b32_e32 v174, 1, v191
	v_and_b32_e32 v175, 15, v191
	v_lshrrev_b32_e32 v176, 4, v191
	s_mul_i32 s20, s89, 0x3200
	v_lshl_add_u32 v151, v191, 2, s20
	v_mul_u32_u24_e32 v182, 0x110, v175
	v_lshl_add_u32 v182, v176, 4, v182
	v_add_u32_e32 v152, s20, v182
	v_lshlrev_b32_e32 v182, 5, v172
	v_lshl_add_u32 v150, v173, 4, v182
	v_xor_b32_e32 v193, 0x80, v150
	s_mov_b32 s66, 0x0f0f0f0f
	s_mov_b32 s67, 0x0f0f0f0f
	s_mov_b32 s68, 0xf0f0f0f0
	s_mov_b32 s69, 0xf0f0f0f0
	v_lshlrev_b32_e32 v182, 5, v172
	v_lshl_add_u32 v182, v173, 4, v182
	s_add_u32 s22, s20, 0x2200
	v_add_u32_e32 v162, s22, v182
	v_lshlrev_b32_e32 v182, 5, v175
	v_lshl_add_u32 v182, v176, 3, v182
	v_add_u32_e32 v163, s22, v182
	v_mul_u32_u24_e32 v182, 0x1800, v175
	v_lshl_add_u32 v154, v176, 3, v182
	v_add_u32_e32 v158, 0x18000, v154
	v_lshlrev_b32_e32 v182, 12, v175
	v_lshlrev_b32_e32 v182, 6, v175
	v_lshl_add_u32 v153, v176, 4, v182
	v_add_u32_e32 v157, 0x400, v153
	v_lshlrev_b32_e32 v182, 11, v175
	v_lshl_add_u32 v156, v176, 3, v182
	v_add_u32_e32 v159, 0x8000, v156
	s_and_b32 s21, s89, 3
	s_lshl_b32 s21, s21, 13
	s_add_u32 s21, s21, 0x19000
	v_lshlrev_b32_e32 v182, 5, v175
	v_lshl_add_u32 v182, v176, 3, v182
	v_add_u32_e32 v155, s21, v182
	v_lshrrev_b32_e32 v182, 4, v172
	v_lshlrev_b32_e32 v182, 10, v182
	v_lshl_add_u32 v182, v175, 4, v182
	v_lshl_add_u32 v177, v173, 8, v182
	v_lshrrev_b32_e32 v182, 1, v176
	v_lshlrev_b32_e32 v182, 8, v182
	v_and_b32_e32 v183, 1, v176
	v_lshl_add_u32 v182, v183, 3, v182
	v_lshl_add_u32 v178, v175, 4, v182
	v_lshrrev_b32_e32 v182, 1, v172
	v_lshl_add_u32 v182, v173, 5, v182
	v_lshlrev_b32_e32 v179, 3, v182
	v_lshlrev_b32_e32 v183, 14, v174
	v_lshl_add_u32 v180, v182, 2, v183
	v_lshlrev_b32_e32 v181, 4, v176
	s_waitcnt vmcnt(0) lgkmcnt(0)
	s_barrier
	s_cmp_lt_u32 s89, 4
	s_cbranch_scc0 .Lssm_ctx
	s_lshr_b32 s21, s89, 1
	s_and_b32 s22, s2, 7
	s_lshl_b32 s22, s22, 6
	s_lshr_b32 s26, s2, 3
	s_lshl_b32 s26, s26, 1
	s_add_u32 s22, s22, s26
	s_add_u32 s22, s22, s21
	s_lshr_b32 s23, s22, 6
	s_and_b32 s24, s22, 63
	s_lshl_b32 s25, s23, 10
	s_add_u32 s25, s25, 0x2000
	s_and_b32 s26, s89, 1
	s_cmp_eq_u32 s26, 0
	s_cbranch_scc0 .Lssm_lat_bwd
	s_add_u32 s28, s24, 0
	s_lshl_b32 s29, s28, 13
	s_add_u32 s29, s29, 0x200000
	s_add_u32 s10, s62, s29
	s_addc_u32 s11, s63, 0
	global_load_dwordx4 v[84:87], v177, s[10:11]
	global_load_dwordx4 v[88:91], v177, s[10:11] offset:2048
	s_add_u32 s12, s10, 0x1000
	s_addc_u32 s13, s11, 0
	global_load_dwordx4 v[92:95], v177, s[12:13]
	global_load_dwordx4 v[96:99], v177, s[12:13] offset:2048
	s_lshl_b32 s29, s28, 12
	s_add_u32 s29, s29, 0x300000
	s_add_u32 s16, s62, s29
	s_addc_u32 s17, s63, 0
	global_load_dwordx2 v[20:21], v178, s[16:17]
	global_load_dwordx2 v[22:23], v178, s[16:17] offset:1024
	global_load_dwordx2 v[24:25], v178, s[16:17] offset:512
	global_load_dwordx2 v[26:27], v178, s[16:17] offset:1536
	global_load_dwordx2 v[28:29], v178, s[16:17] offset:2048
	global_load_dwordx2 v[30:31], v178, s[16:17] offset:3072
	global_load_dwordx2 v[32:33], v178, s[16:17] offset:2560
	global_load_dwordx2 v[34:35], v178, s[16:17] offset:3584
	s_lshl_b32 s29, s28, 9
	s_add_u32 s29, s29, 0x100000
	s_add_u32 s18, s62, s29
	s_addc_u32 s19, s63, 0
	global_load_dwordx2 v[116:117], v179, s[18:19]
	global_load_dwordx2 v[118:119], v179, s[18:19] offset:128
	s_lshl_b32 s30, s23, 1
	s_lshl_b32 s30, s30, 15
	s_lshl_b32 s31, s24, 8
	s_add_u32 s30, s30, s31
	v_readlane_b32 s34, v254, 10
	v_readlane_b32 s35, v254, 11
	s_nop 3
	s_add_u32 s34, s34, s30
	s_addc_u32 s35, s35, 0
	global_load_dword v120, v180, s[34:35]
	global_load_dword v121, v180, s[34:35] offset:64
	v_readlane_b32 s34, v254, 28
	v_readlane_b32 s35, v254, 29
	s_nop 3
	s_lshl_b32 s31, s24, 6
	s_add_u32 s34, s34, s31
	s_addc_u32 s35, s35, 0
	global_load_dwordx4 v[164:167], v181, s[34:35]
	s_lshl_b32 s31, s25, 5
	s_lshl_b32 s29, s24, 19
	s_add_u32 s31, s31, s29
	s_add_u32 s31, s31, 0x16800000
	s_add_u32 s4, s62, s31
	s_addc_u32 s5, s63, 0
	s_lshl_b32 s31, s22, 1
	s_lshl_b32 s31, s31, 15
	s_add_u32 s31, s31, 0x4800000
	s_add_u32 s6, s62, s31
	s_addc_u32 s7, s63, 0
	s_add_u32 s34, s4, 0
	s_addc_u32 s35, s5, 0
	global_load_dwordx4 v[80:83], v150, s[34:35]
	global_load_dwordx4 v[194:197], v193, s[34:35]
	s_mov_b64 s[10:11], s[34:35]
	s_add_u32 s10, s10, 1024
	s_addc_u32 s11, s11, 0
	global_load_dwordx4 v[144:147], v150, s[10:11]
	global_load_dwordx4 v[168:171], v193, s[10:11]
	s_mov_b64 s[34:35], s[10:11]
	s_add_u32 s10, s10, 1024
	s_addc_u32 s11, s11, 0
	s_add_u32 s12, s6, 0
	s_addc_u32 s13, s7, 0
	s_mov_b32 s14, 0
	s_mov_b32 s40, 0xffff0000
	s_waitcnt vmcnt(0)
	v_and_b32_e32 v182, 0xffff, v20
	v_lshrrev_b32_e32 v183, 16, v20
	v_and_b32_e32 v184, 0xffff, v21
	v_lshrrev_b32_e32 v185, 16, v21
	v_lshl_or_b32 v100, v22, 16, v182
	v_and_or_b32 v101, v22, s40, v183
	v_lshl_or_b32 v102, v23, 16, v184
	v_and_or_b32 v103, v23, s40, v185
	v_and_b32_e32 v182, 0xffff, v24
	v_lshrrev_b32_e32 v183, 16, v24
	v_and_b32_e32 v184, 0xffff, v25
	v_lshrrev_b32_e32 v185, 16, v25
	v_lshl_or_b32 v104, v26, 16, v182
	v_and_or_b32 v105, v26, s40, v183
	v_lshl_or_b32 v106, v27, 16, v184
	v_and_or_b32 v107, v27, s40, v185
	v_and_b32_e32 v182, 0xffff, v28
	v_lshrrev_b32_e32 v183, 16, v28
	v_and_b32_e32 v184, 0xffff, v29
	v_lshrrev_b32_e32 v185, 16, v29
	v_lshl_or_b32 v108, v30, 16, v182
	v_and_or_b32 v109, v30, s40, v183
	v_lshl_or_b32 v110, v31, 16, v184
	v_and_or_b32 v111, v31, s40, v185
	v_and_b32_e32 v182, 0xffff, v32
	v_lshrrev_b32_e32 v183, 16, v32
	v_and_b32_e32 v184, 0xffff, v33
	v_lshrrev_b32_e32 v185, 16, v33
	v_lshl_or_b32 v112, v34, 16, v182
	v_and_or_b32 v113, v34, s40, v183
	v_lshl_or_b32 v114, v35, 16, v184
	v_and_or_b32 v115, v35, s40, v185
	v_cmp_eq_u32_e32 vcc, 1, v174
	v_xor_b32_e32 v182, 0x80000000, v117
	v_xor_b32_e32 v183, 0x80000000, v119
	s_nop 1
	v_cndmask_b32_e32 v122, v182, v117, vcc
	v_cndmask_b32_e32 v123, v183, v119, vcc
.Lssm_tileA_d0m0:
	s_waitcnt vmcnt(6)
	v_cndmask_b32_e64 v124, 0, v80, s[66:67]
	v_cndmask_b32_e64 v125, 0, v81, s[66:67]
	v_cndmask_b32_e64 v126, 0, v82, s[66:67]
	v_cndmask_b32_e64 v127, 0, v83, s[66:67]
	v_cndmask_b32_e64 v132, 0, v194, s[66:67]
	v_cndmask_b32_e64 v133, 0, v195, s[66:67]
	v_cndmask_b32_e64 v134, 0, v196, s[66:67]
	v_cndmask_b32_e64 v135, 0, v197, s[66:67]
	v_mfma_f32_32x32x16_bf16 v[16:31], v[124:127], v[84:87], 0
	v_cndmask_b32_e64 v128, 0, v194, s[68:69]
	v_cndmask_b32_e64 v129, 0, v195, s[68:69]
	v_cndmask_b32_e64 v130, 0, v196, s[68:69]
	v_cndmask_b32_e64 v131, 0, v197, s[68:69]
	v_mfma_f32_32x32x16_bf16 v[32:47], v[124:127], v[88:91], 0
	v_cndmask_b32_e64 v136, 0, v80, s[68:69]
	v_cndmask_b32_e64 v137, 0, v81, s[68:69]
	v_cndmask_b32_e64 v138, 0, v82, s[68:69]
	v_cndmask_b32_e64 v139, 0, v83, s[68:69]
	v_mfma_f32_32x32x16_bf16 v[48:63], v[132:135], v[84:87], 0
	v_mfma_f32_32x32x16_bf16 v[64:79], v[132:135], v[88:91], 0
	v_mfma_f32_32x32x16_bf16 v[16:31], v[128:131], v[92:95], v[16:31]
	v_mfma_f32_32x32x16_bf16 v[32:47], v[128:131], v[96:99], v[32:47]
	v_mfma_f32_32x32x16_bf16 v[48:63], v[136:139], v[92:95], v[48:63]
	v_mfma_f32_32x32x16_bf16 v[64:79], v[136:139], v[96:99], v[64:79]
	s_nop 11
	global_load_dwordx4 v[80:83], v150, s[10:11]
	global_load_dwordx4 v[194:197], v193, s[10:11]
	s_add_u32 s34, s34, 1024
	s_addc_u32 s35, s35, 0
	s_add_u32 s10, s10, 1024
	s_addc_u32 s11, s11, 0
	v_fmac_f32_e32 v16, v116, v120
	v_fmac_f32_e32 v32, v118, v121
	v_fmac_f32_dpp v16, v120, v122 quad_perm:[1,0,3,2] row_mask:0xf bank_mask:0xf
	v_fmac_f32_dpp v32, v121, v123 quad_perm:[1,0,3,2] row_mask:0xf bank_mask:0xf
	v_cvt_pk_bf16_f32 v148, v16, v32
	ds_write_b32 v151, v148
	v_fmac_f32_e32 v17, v116, v16
	v_fmac_f32_e32 v33, v118, v32
	v_fmac_f32_dpp v17, v16, v122 quad_perm:[1,0,3,2] row_mask:0xf bank_mask:0xf
	v_fmac_f32_dpp v33, v32, v123 quad_perm:[1,0,3,2] row_mask:0xf bank_mask:0xf
	v_cvt_pk_bf16_f32 v149, v17, v33
	ds_write_b32 v151, v149 offset:272
	v_fmac_f32_e32 v18, v116, v17
	v_fmac_f32_e32 v34, v118, v33
	v_fmac_f32_dpp v18, v17, v122 quad_perm:[1,0,3,2] row_mask:0xf bank_mask:0xf
	v_fmac_f32_dpp v34, v33, v123 quad_perm:[1,0,3,2] row_mask:0xf bank_mask:0xf
	v_cvt_pk_bf16_f32 v148, v18, v34
	ds_write_b32 v151, v148 offset:544
	v_fmac_f32_e32 v19, v116, v18
	v_fmac_f32_e32 v35, v118, v34
	v_fmac_f32_dpp v19, v18, v122 quad_perm:[1,0,3,2] row_mask:0xf bank_mask:0xf
	v_fmac_f32_dpp v35, v34, v123 quad_perm:[1,0,3,2] row_mask:0xf bank_mask:0xf
	v_cvt_pk_bf16_f32 v149, v19, v35
	ds_write_b32 v151, v149 offset:816
	v_fmac_f32_e32 v48, v116, v19
	v_fmac_f32_e32 v64, v118, v35
	v_fmac_f32_dpp v48, v19, v122 quad_perm:[1,0,3,2] row_mask:0xf bank_mask:0xf
	v_fmac_f32_dpp v64, v35, v123 quad_perm:[1,0,3,2] row_mask:0xf bank_mask:0xf
	v_cvt_pk_bf16_f32 v148, v48, v64
	ds_write_b32 v151, v148 offset:1088
	v_fmac_f32_e32 v49, v116, v48
	v_fmac_f32_e32 v65, v118, v64
	v_fmac_f32_dpp v49, v48, v122 quad_perm:[1,0,3,2] row_mask:0xf bank_mask:0xf
	v_fmac_f32_dpp v65, v64, v123 quad_perm:[1,0,3,2] row_mask:0xf bank_mask:0xf
	v_cvt_pk_bf16_f32 v149, v49, v65
	ds_write_b32 v151, v149 offset:1360
	v_fmac_f32_e32 v50, v116, v49
	v_fmac_f32_e32 v66, v118, v65
	v_fmac_f32_dpp v50, v49, v122 quad_perm:[1,0,3,2] row_mask:0xf bank_mask:0xf
	v_fmac_f32_dpp v66, v65, v123 quad_perm:[1,0,3,2] row_mask:0xf bank_mask:0xf
	v_cvt_pk_bf16_f32 v148, v50, v66
	ds_write_b32 v151, v148 offset:1632
	v_fmac_f32_e32 v51, v116, v50
	v_fmac_f32_e32 v67, v118, v66
	v_fmac_f32_dpp v51, v50, v122 quad_perm:[1,0,3,2] row_mask:0xf bank_mask:0xf
	v_fmac_f32_dpp v67, v66, v123 quad_perm:[1,0,3,2] row_mask:0xf bank_mask:0xf
	v_cvt_pk_bf16_f32 v149, v51, v67
	ds_write_b32 v151, v149 offset:1904
	v_fmac_f32_e32 v20, v116, v51
	v_fmac_f32_e32 v36, v118, v67
	v_fmac_f32_dpp v20, v51, v122 quad_perm:[1,0,3,2] row_mask:0xf bank_mask:0xf
	v_fmac_f32_dpp v36, v67, v123 quad_perm:[1,0,3,2] row_mask:0xf bank_mask:0xf
	v_cvt_pk_bf16_f32 v148, v20, v36
	ds_write_b32 v151, v148 offset:2176
	v_fmac_f32_e32 v21, v116, v20
	v_fmac_f32_e32 v37, v118, v36
	v_fmac_f32_dpp v21, v20, v122 quad_perm:[1,0,3,2] row_mask:0xf bank_mask:0xf
	v_fmac_f32_dpp v37, v36, v123 quad_perm:[1,0,3,2] row_mask:0xf bank_mask:0xf
	v_cvt_pk_bf16_f32 v149, v21, v37
	ds_write_b32 v151, v149 offset:2448
	v_fmac_f32_e32 v22, v116, v21
	v_fmac_f32_e32 v38, v118, v37
	v_fmac_f32_dpp v22, v21, v122 quad_perm:[1,0,3,2] row_mask:0xf bank_mask:0xf
	v_fmac_f32_dpp v38, v37, v123 quad_perm:[1,0,3,2] row_mask:0xf bank_mask:0xf
	v_cvt_pk_bf16_f32 v148, v22, v38
	ds_write_b32 v151, v148 offset:2720
	v_fmac_f32_e32 v23, v116, v22
	v_fmac_f32_e32 v39, v118, v38
	v_fmac_f32_dpp v23, v22, v122 quad_perm:[1,0,3,2] row_mask:0xf bank_mask:0xf
	v_fmac_f32_dpp v39, v38, v123 quad_perm:[1,0,3,2] row_mask:0xf bank_mask:0xf
	v_cvt_pk_bf16_f32 v149, v23, v39
	ds_write_b32 v151, v149 offset:2992
	v_fmac_f32_e32 v52, v116, v23
	v_fmac_f32_e32 v68, v118, v39
	v_fmac_f32_dpp v52, v23, v122 quad_perm:[1,0,3,2] row_mask:0xf bank_mask:0xf
	v_fmac_f32_dpp v68, v39, v123 quad_perm:[1,0,3,2] row_mask:0xf bank_mask:0xf
	v_cvt_pk_bf16_f32 v148, v52, v68
	ds_write_b32 v151, v148 offset:3264
	v_fmac_f32_e32 v53, v116, v52
	v_fmac_f32_e32 v69, v118, v68
	v_fmac_f32_dpp v53, v52, v122 quad_perm:[1,0,3,2] row_mask:0xf bank_mask:0xf
	v_fmac_f32_dpp v69, v68, v123 quad_perm:[1,0,3,2] row_mask:0xf bank_mask:0xf
	v_cvt_pk_bf16_f32 v149, v53, v69
	ds_write_b32 v151, v149 offset:3536
	v_fmac_f32_e32 v54, v116, v53
	v_fmac_f32_e32 v70, v118, v69
	v_fmac_f32_dpp v54, v53, v122 quad_perm:[1,0,3,2] row_mask:0xf bank_mask:0xf
	v_fmac_f32_dpp v70, v69, v123 quad_perm:[1,0,3,2] row_mask:0xf bank_mask:0xf
	v_cvt_pk_bf16_f32 v148, v54, v70
	ds_write_b32 v151, v148 offset:3808
	v_fmac_f32_e32 v55, v116, v54
	v_fmac_f32_e32 v71, v118, v70
	v_fmac_f32_dpp v55, v54, v122 quad_perm:[1,0,3,2] row_mask:0xf bank_mask:0xf
	v_fmac_f32_dpp v71, v70, v123 quad_perm:[1,0,3,2] row_mask:0xf bank_mask:0xf
	v_cvt_pk_bf16_f32 v149, v55, v71
	ds_write_b32 v151, v149 offset:4080
	v_fmac_f32_e32 v24, v116, v55
	v_fmac_f32_e32 v40, v118, v71
	v_fmac_f32_dpp v24, v55, v122 quad_perm:[1,0,3,2] row_mask:0xf bank_mask:0xf
	v_fmac_f32_dpp v40, v71, v123 quad_perm:[1,0,3,2] row_mask:0xf bank_mask:0xf
	v_cvt_pk_bf16_f32 v148, v24, v40
	ds_write_b32 v151, v148 offset:4352
	v_fmac_f32_e32 v25, v116, v24
	v_fmac_f32_e32 v41, v118, v40
	v_fmac_f32_dpp v25, v24, v122 quad_perm:[1,0,3,2] row_mask:0xf bank_mask:0xf
	v_fmac_f32_dpp v41, v40, v123 quad_perm:[1,0,3,2] row_mask:0xf bank_mask:0xf
	v_cvt_pk_bf16_f32 v149, v25, v41
	ds_write_b32 v151, v149 offset:4624
	v_fmac_f32_e32 v26, v116, v25
	v_fmac_f32_e32 v42, v118, v41
	v_fmac_f32_dpp v26, v25, v122 quad_perm:[1,0,3,2] row_mask:0xf bank_mask:0xf
	v_fmac_f32_dpp v42, v41, v123 quad_perm:[1,0,3,2] row_mask:0xf bank_mask:0xf
	v_cvt_pk_bf16_f32 v148, v26, v42
	ds_write_b32 v151, v148 offset:4896
	v_fmac_f32_e32 v27, v116, v26
	v_fmac_f32_e32 v43, v118, v42
	v_fmac_f32_dpp v27, v26, v122 quad_perm:[1,0,3,2] row_mask:0xf bank_mask:0xf
	v_fmac_f32_dpp v43, v42, v123 quad_perm:[1,0,3,2] row_mask:0xf bank_mask:0xf
	v_cvt_pk_bf16_f32 v149, v27, v43
	ds_write_b32 v151, v149 offset:5168
	v_fmac_f32_e32 v56, v116, v27
	v_fmac_f32_e32 v72, v118, v43
	v_fmac_f32_dpp v56, v27, v122 quad_perm:[1,0,3,2] row_mask:0xf bank_mask:0xf
	v_fmac_f32_dpp v72, v43, v123 quad_perm:[1,0,3,2] row_mask:0xf bank_mask:0xf
	v_cvt_pk_bf16_f32 v148, v56, v72
	ds_write_b32 v151, v148 offset:5440
	v_fmac_f32_e32 v57, v116, v56
	v_fmac_f32_e32 v73, v118, v72
	v_fmac_f32_dpp v57, v56, v122 quad_perm:[1,0,3,2] row_mask:0xf bank_mask:0xf
	v_fmac_f32_dpp v73, v72, v123 quad_perm:[1,0,3,2] row_mask:0xf bank_mask:0xf
	v_cvt_pk_bf16_f32 v149, v57, v73
	ds_write_b32 v151, v149 offset:5712
	v_fmac_f32_e32 v58, v116, v57
	v_fmac_f32_e32 v74, v118, v73
	v_fmac_f32_dpp v58, v57, v122 quad_perm:[1,0,3,2] row_mask:0xf bank_mask:0xf
	v_fmac_f32_dpp v74, v73, v123 quad_perm:[1,0,3,2] row_mask:0xf bank_mask:0xf
	v_cvt_pk_bf16_f32 v148, v58, v74
	ds_write_b32 v151, v148 offset:5984
	v_fmac_f32_e32 v59, v116, v58
	v_fmac_f32_e32 v75, v118, v74
	v_fmac_f32_dpp v59, v58, v122 quad_perm:[1,0,3,2] row_mask:0xf bank_mask:0xf
	v_fmac_f32_dpp v75, v74, v123 quad_perm:[1,0,3,2] row_mask:0xf bank_mask:0xf
	v_cvt_pk_bf16_f32 v149, v59, v75
	ds_write_b32 v151, v149 offset:6256
	v_fmac_f32_e32 v28, v116, v59
	v_fmac_f32_e32 v44, v118, v75
	v_fmac_f32_dpp v28, v59, v122 quad_perm:[1,0,3,2] row_mask:0xf bank_mask:0xf
	v_fmac_f32_dpp v44, v75, v123 quad_perm:[1,0,3,2] row_mask:0xf bank_mask:0xf
	v_cvt_pk_bf16_f32 v148, v28, v44
	ds_write_b32 v151, v148 offset:6528
	v_fmac_f32_e32 v29, v116, v28
	v_fmac_f32_e32 v45, v118, v44
	v_fmac_f32_dpp v29, v28, v122 quad_perm:[1,0,3,2] row_mask:0xf bank_mask:0xf
	v_fmac_f32_dpp v45, v44, v123 quad_perm:[1,0,3,2] row_mask:0xf bank_mask:0xf
	v_cvt_pk_bf16_f32 v149, v29, v45
	ds_write_b32 v151, v149 offset:6800
	v_fmac_f32_e32 v30, v116, v29
	v_fmac_f32_e32 v46, v118, v45
	v_fmac_f32_dpp v30, v29, v122 quad_perm:[1,0,3,2] row_mask:0xf bank_mask:0xf
	v_fmac_f32_dpp v46, v45, v123 quad_perm:[1,0,3,2] row_mask:0xf bank_mask:0xf
	v_cvt_pk_bf16_f32 v148, v30, v46
	ds_write_b32 v151, v148 offset:7072
	v_fmac_f32_e32 v31, v116, v30
	v_fmac_f32_e32 v47, v118, v46
	v_fmac_f32_dpp v31, v30, v122 quad_perm:[1,0,3,2] row_mask:0xf bank_mask:0xf
	v_fmac_f32_dpp v47, v46, v123 quad_perm:[1,0,3,2] row_mask:0xf bank_mask:0xf
	v_cvt_pk_bf16_f32 v149, v31, v47
	ds_write_b32 v151, v149 offset:7344
	v_fmac_f32_e32 v60, v116, v31
	v_fmac_f32_e32 v76, v118, v47
	v_fmac_f32_dpp v60, v31, v122 quad_perm:[1,0,3,2] row_mask:0xf bank_mask:0xf
	v_fmac_f32_dpp v76, v47, v123 quad_perm:[1,0,3,2] row_mask:0xf bank_mask:0xf
	v_cvt_pk_bf16_f32 v148, v60, v76
	ds_write_b32 v151, v148 offset:7616
	v_fmac_f32_e32 v61, v116, v60
	v_fmac_f32_e32 v77, v118, v76
	v_fmac_f32_dpp v61, v60, v122 quad_perm:[1,0,3,2] row_mask:0xf bank_mask:0xf
	v_fmac_f32_dpp v77, v76, v123 quad_perm:[1,0,3,2] row_mask:0xf bank_mask:0xf
	v_cvt_pk_bf16_f32 v149, v61, v77
	ds_write_b32 v151, v149 offset:7888
	v_fmac_f32_e32 v62, v116, v61
	v_fmac_f32_e32 v78, v118, v77
	v_fmac_f32_dpp v62, v61, v122 quad_perm:[1,0,3,2] row_mask:0xf bank_mask:0xf
	v_fmac_f32_dpp v78, v77, v123 quad_perm:[1,0,3,2] row_mask:0xf bank_mask:0xf
	v_cvt_pk_bf16_f32 v148, v62, v78
	ds_write_b32 v151, v148 offset:8160
	v_fmac_f32_e32 v63, v116, v62
	v_fmac_f32_e32 v79, v118, v78
	v_fmac_f32_dpp v63, v62, v122 quad_perm:[1,0,3,2] row_mask:0xf bank_mask:0xf
	v_fmac_f32_dpp v79, v78, v123 quad_perm:[1,0,3,2] row_mask:0xf bank_mask:0xf
	v_cvt_pk_bf16_f32 v149, v63, v79
	ds_write_b32 v151, v149 offset:8432
	v_mov_b32_e32 v120, v63
	v_mov_b32_e32 v121, v79
	ds_read_b128 v[124:127], v152
	ds_read_b128 v[128:131], v152 offset:64
	ds_read_b128 v[132:135], v152 offset:128
	ds_read_b128 v[136:139], v152 offset:192
	s_waitcnt lgkmcnt(3)
	v_mfma_f32_16x16x32_bf16 v[140:143], v[100:103], v[124:127], 0
	s_waitcnt lgkmcnt(2)
	v_mfma_f32_16x16x32_bf16 v[140:143], v[104:107], v[128:131], v[140:143]
	s_waitcnt lgkmcnt(1)
	v_mfma_f32_16x16x32_bf16 v[140:143], v[108:111], v[132:135], v[140:143]
	s_waitcnt lgkmcnt(0)
	v_mfma_f32_16x16x32_bf16 v[140:143], v[112:115], v[136:139], v[140:143]
	s_nop 9
	global_store_dwordx4 v153, v[140:143], s[12:13]
	s_nop 1
	ds_read_b128 v[124:127], v152 offset:4352
	ds_read_b128 v[128:131], v152 offset:4416
	ds_read_b128 v[132:135], v152 offset:4480
	ds_read_b128 v[136:139], v152 offset:4544
	s_waitcnt lgkmcnt(3)
	v_mfma_f32_16x16x32_bf16 v[140:143], v[100:103], v[124:127], 0
	s_waitcnt lgkmcnt(2)
	v_mfma_f32_16x16x32_bf16 v[140:143], v[104:107], v[128:131], v[140:143]
	s_waitcnt lgkmcnt(1)
	v_mfma_f32_16x16x32_bf16 v[140:143], v[108:111], v[132:135], v[140:143]
	s_waitcnt lgkmcnt(0)
	v_mfma_f32_16x16x32_bf16 v[140:143], v[112:115], v[136:139], v[140:143]
	s_nop 9
	global_store_dwordx4 v157, v[140:143], s[12:13]
	s_nop 1
	s_add_u32 s12, s12, 2048
	s_addc_u32 s13, s13, 0
	s_waitcnt vmcnt(6)
	v_cndmask_b32_e64 v124, 0, v144, s[66:67]
	v_cndmask_b32_e64 v125, 0, v145, s[66:67]
	v_cndmask_b32_e64 v126, 0, v146, s[66:67]
	v_cndmask_b32_e64 v127, 0, v147, s[66:67]
	v_cndmask_b32_e64 v132, 0, v168, s[66:67]
	v_cndmask_b32_e64 v133, 0, v169, s[66:67]
	v_cndmask_b32_e64 v134, 0, v170, s[66:67]
	v_cndmask_b32_e64 v135, 0, v171, s[66:67]
	v_mfma_f32_32x32x16_bf16 v[16:31], v[124:127], v[84:87], 0
	v_cndmask_b32_e64 v128, 0, v168, s[68:69]
	v_cndmask_b32_e64 v129, 0, v169, s[68:69]
	v_cndmask_b32_e64 v130, 0, v170, s[68:69]
	v_cndmask_b32_e64 v131, 0, v171, s[68:69]
	v_mfma_f32_32x32x16_bf16 v[32:47], v[124:127], v[88:91], 0
	v_cndmask_b32_e64 v136, 0, v144, s[68:69]
	v_cndmask_b32_e64 v137, 0, v145, s[68:69]
	v_cndmask_b32_e64 v138, 0, v146, s[68:69]
	v_cndmask_b32_e64 v139, 0, v147, s[68:69]
	v_mfma_f32_32x32x16_bf16 v[48:63], v[132:135], v[84:87], 0
	v_mfma_f32_32x32x16_bf16 v[64:79], v[132:135], v[88:91], 0
	v_mfma_f32_32x32x16_bf16 v[16:31], v[128:131], v[92:95], v[16:31]
	v_mfma_f32_32x32x16_bf16 v[32:47], v[128:131], v[96:99], v[32:47]
	v_mfma_f32_32x32x16_bf16 v[48:63], v[136:139], v[92:95], v[48:63]
	v_mfma_f32_32x32x16_bf16 v[64:79], v[136:139], v[96:99], v[64:79]
	s_nop 11
	global_load_dwordx4 v[144:147], v150, s[10:11]
	global_load_dwordx4 v[168:171], v193, s[10:11]
	s_add_u32 s34, s34, 1024
	s_addc_u32 s35, s35, 0
	s_add_u32 s10, s10, 1024
	s_addc_u32 s11, s11, 0
	v_fmac_f32_e32 v16, v116, v120
	v_fmac_f32_e32 v32, v118, v121
	v_fmac_f32_dpp v16, v120, v122 quad_perm:[1,0,3,2] row_mask:0xf bank_mask:0xf
	v_fmac_f32_dpp v32, v121, v123 quad_perm:[1,0,3,2] row_mask:0xf bank_mask:0xf
	v_cvt_pk_bf16_f32 v148, v16, v32
	ds_write_b32 v151, v148
	v_fmac_f32_e32 v17, v116, v16
	v_fmac_f32_e32 v33, v118, v32
	v_fmac_f32_dpp v17, v16, v122 quad_perm:[1,0,3,2] row_mask:0xf bank_mask:0xf
	v_fmac_f32_dpp v33, v32, v123 quad_perm:[1,0,3,2] row_mask:0xf bank_mask:0xf
	v_cvt_pk_bf16_f32 v149, v17, v33
	ds_write_b32 v151, v149 offset:272
	v_fmac_f32_e32 v18, v116, v17
	v_fmac_f32_e32 v34, v118, v33
	v_fmac_f32_dpp v18, v17, v122 quad_perm:[1,0,3,2] row_mask:0xf bank_mask:0xf
	v_fmac_f32_dpp v34, v33, v123 quad_perm:[1,0,3,2] row_mask:0xf bank_mask:0xf
	v_cvt_pk_bf16_f32 v148, v18, v34
	ds_write_b32 v151, v148 offset:544
	v_fmac_f32_e32 v19, v116, v18
	v_fmac_f32_e32 v35, v118, v34
	v_fmac_f32_dpp v19, v18, v122 quad_perm:[1,0,3,2] row_mask:0xf bank_mask:0xf
	v_fmac_f32_dpp v35, v34, v123 quad_perm:[1,0,3,2] row_mask:0xf bank_mask:0xf
	v_cvt_pk_bf16_f32 v149, v19, v35
	ds_write_b32 v151, v149 offset:816
	v_fmac_f32_e32 v48, v116, v19
	v_fmac_f32_e32 v64, v118, v35
	v_fmac_f32_dpp v48, v19, v122 quad_perm:[1,0,3,2] row_mask:0xf bank_mask:0xf
	v_fmac_f32_dpp v64, v35, v123 quad_perm:[1,0,3,2] row_mask:0xf bank_mask:0xf
	v_cvt_pk_bf16_f32 v148, v48, v64
	ds_write_b32 v151, v148 offset:1088
	v_fmac_f32_e32 v49, v116, v48
	v_fmac_f32_e32 v65, v118, v64
	v_fmac_f32_dpp v49, v48, v122 quad_perm:[1,0,3,2] row_mask:0xf bank_mask:0xf
	v_fmac_f32_dpp v65, v64, v123 quad_perm:[1,0,3,2] row_mask:0xf bank_mask:0xf
	v_cvt_pk_bf16_f32 v149, v49, v65
	ds_write_b32 v151, v149 offset:1360
	v_fmac_f32_e32 v50, v116, v49
	v_fmac_f32_e32 v66, v118, v65
	v_fmac_f32_dpp v50, v49, v122 quad_perm:[1,0,3,2] row_mask:0xf bank_mask:0xf
	v_fmac_f32_dpp v66, v65, v123 quad_perm:[1,0,3,2] row_mask:0xf bank_mask:0xf
	v_cvt_pk_bf16_f32 v148, v50, v66
	ds_write_b32 v151, v148 offset:1632
	v_fmac_f32_e32 v51, v116, v50
	v_fmac_f32_e32 v67, v118, v66
	v_fmac_f32_dpp v51, v50, v122 quad_perm:[1,0,3,2] row_mask:0xf bank_mask:0xf
	v_fmac_f32_dpp v67, v66, v123 quad_perm:[1,0,3,2] row_mask:0xf bank_mask:0xf
	v_cvt_pk_bf16_f32 v149, v51, v67
	ds_write_b32 v151, v149 offset:1904
	v_fmac_f32_e32 v20, v116, v51
	v_fmac_f32_e32 v36, v118, v67
	v_fmac_f32_dpp v20, v51, v122 quad_perm:[1,0,3,2] row_mask:0xf bank_mask:0xf
	v_fmac_f32_dpp v36, v67, v123 quad_perm:[1,0,3,2] row_mask:0xf bank_mask:0xf
	v_cvt_pk_bf16_f32 v148, v20, v36
	ds_write_b32 v151, v148 offset:2176
	v_fmac_f32_e32 v21, v116, v20
	v_fmac_f32_e32 v37, v118, v36
	v_fmac_f32_dpp v21, v20, v122 quad_perm:[1,0,3,2] row_mask:0xf bank_mask:0xf
	v_fmac_f32_dpp v37, v36, v123 quad_perm:[1,0,3,2] row_mask:0xf bank_mask:0xf
	v_cvt_pk_bf16_f32 v149, v21, v37
	ds_write_b32 v151, v149 offset:2448
	v_fmac_f32_e32 v22, v116, v21
	v_fmac_f32_e32 v38, v118, v37
	v_fmac_f32_dpp v22, v21, v122 quad_perm:[1,0,3,2] row_mask:0xf bank_mask:0xf
	v_fmac_f32_dpp v38, v37, v123 quad_perm:[1,0,3,2] row_mask:0xf bank_mask:0xf
	v_cvt_pk_bf16_f32 v148, v22, v38
	ds_write_b32 v151, v148 offset:2720
	v_fmac_f32_e32 v23, v116, v22
	v_fmac_f32_e32 v39, v118, v38
	v_fmac_f32_dpp v23, v22, v122 quad_perm:[1,0,3,2] row_mask:0xf bank_mask:0xf
	v_fmac_f32_dpp v39, v38, v123 quad_perm:[1,0,3,2] row_mask:0xf bank_mask:0xf
	v_cvt_pk_bf16_f32 v149, v23, v39
	ds_write_b32 v151, v149 offset:2992
	v_fmac_f32_e32 v52, v116, v23
	v_fmac_f32_e32 v68, v118, v39
	v_fmac_f32_dpp v52, v23, v122 quad_perm:[1,0,3,2] row_mask:0xf bank_mask:0xf
	v_fmac_f32_dpp v68, v39, v123 quad_perm:[1,0,3,2] row_mask:0xf bank_mask:0xf
	v_cvt_pk_bf16_f32 v148, v52, v68
	ds_write_b32 v151, v148 offset:3264
	v_fmac_f32_e32 v53, v116, v52
	v_fmac_f32_e32 v69, v118, v68
	v_fmac_f32_dpp v53, v52, v122 quad_perm:[1,0,3,2] row_mask:0xf bank_mask:0xf
	v_fmac_f32_dpp v69, v68, v123 quad_perm:[1,0,3,2] row_mask:0xf bank_mask:0xf
	v_cvt_pk_bf16_f32 v149, v53, v69
	ds_write_b32 v151, v149 offset:3536
	v_fmac_f32_e32 v54, v116, v53
	v_fmac_f32_e32 v70, v118, v69
	v_fmac_f32_dpp v54, v53, v122 quad_perm:[1,0,3,2] row_mask:0xf bank_mask:0xf
	v_fmac_f32_dpp v70, v69, v123 quad_perm:[1,0,3,2] row_mask:0xf bank_mask:0xf
	v_cvt_pk_bf16_f32 v148, v54, v70
	ds_write_b32 v151, v148 offset:3808
	v_fmac_f32_e32 v55, v116, v54
	v_fmac_f32_e32 v71, v118, v70
	v_fmac_f32_dpp v55, v54, v122 quad_perm:[1,0,3,2] row_mask:0xf bank_mask:0xf
	v_fmac_f32_dpp v71, v70, v123 quad_perm:[1,0,3,2] row_mask:0xf bank_mask:0xf
	v_cvt_pk_bf16_f32 v149, v55, v71
	ds_write_b32 v151, v149 offset:4080
	v_fmac_f32_e32 v24, v116, v55
	v_fmac_f32_e32 v40, v118, v71
	v_fmac_f32_dpp v24, v55, v122 quad_perm:[1,0,3,2] row_mask:0xf bank_mask:0xf
	v_fmac_f32_dpp v40, v71, v123 quad_perm:[1,0,3,2] row_mask:0xf bank_mask:0xf
	v_cvt_pk_bf16_f32 v148, v24, v40
	ds_write_b32 v151, v148 offset:4352
	v_fmac_f32_e32 v25, v116, v24
	v_fmac_f32_e32 v41, v118, v40
	v_fmac_f32_dpp v25, v24, v122 quad_perm:[1,0,3,2] row_mask:0xf bank_mask:0xf
	v_fmac_f32_dpp v41, v40, v123 quad_perm:[1,0,3,2] row_mask:0xf bank_mask:0xf
	v_cvt_pk_bf16_f32 v149, v25, v41
	ds_write_b32 v151, v149 offset:4624
	v_fmac_f32_e32 v26, v116, v25
	v_fmac_f32_e32 v42, v118, v41
	v_fmac_f32_dpp v26, v25, v122 quad_perm:[1,0,3,2] row_mask:0xf bank_mask:0xf
	v_fmac_f32_dpp v42, v41, v123 quad_perm:[1,0,3,2] row_mask:0xf bank_mask:0xf
	v_cvt_pk_bf16_f32 v148, v26, v42
	ds_write_b32 v151, v148 offset:4896
	v_fmac_f32_e32 v27, v116, v26
	v_fmac_f32_e32 v43, v118, v42
	v_fmac_f32_dpp v27, v26, v122 quad_perm:[1,0,3,2] row_mask:0xf bank_mask:0xf
	v_fmac_f32_dpp v43, v42, v123 quad_perm:[1,0,3,2] row_mask:0xf bank_mask:0xf
	v_cvt_pk_bf16_f32 v149, v27, v43
	ds_write_b32 v151, v149 offset:5168
	v_fmac_f32_e32 v56, v116, v27
	v_fmac_f32_e32 v72, v118, v43
	v_fmac_f32_dpp v56, v27, v122 quad_perm:[1,0,3,2] row_mask:0xf bank_mask:0xf
	v_fmac_f32_dpp v72, v43, v123 quad_perm:[1,0,3,2] row_mask:0xf bank_mask:0xf
	v_cvt_pk_bf16_f32 v148, v56, v72
	ds_write_b32 v151, v148 offset:5440
	v_fmac_f32_e32 v57, v116, v56
	v_fmac_f32_e32 v73, v118, v72
	v_fmac_f32_dpp v57, v56, v122 quad_perm:[1,0,3,2] row_mask:0xf bank_mask:0xf
	v_fmac_f32_dpp v73, v72, v123 quad_perm:[1,0,3,2] row_mask:0xf bank_mask:0xf
	v_cvt_pk_bf16_f32 v149, v57, v73
	ds_write_b32 v151, v149 offset:5712
	v_fmac_f32_e32 v58, v116, v57
	v_fmac_f32_e32 v74, v118, v73
	v_fmac_f32_dpp v58, v57, v122 quad_perm:[1,0,3,2] row_mask:0xf bank_mask:0xf
	v_fmac_f32_dpp v74, v73, v123 quad_perm:[1,0,3,2] row_mask:0xf bank_mask:0xf
	v_cvt_pk_bf16_f32 v148, v58, v74
	ds_write_b32 v151, v148 offset:5984
	v_fmac_f32_e32 v59, v116, v58
	v_fmac_f32_e32 v75, v118, v74
	v_fmac_f32_dpp v59, v58, v122 quad_perm:[1,0,3,2] row_mask:0xf bank_mask:0xf
	v_fmac_f32_dpp v75, v74, v123 quad_perm:[1,0,3,2] row_mask:0xf bank_mask:0xf
	v_cvt_pk_bf16_f32 v149, v59, v75
	ds_write_b32 v151, v149 offset:6256
	v_fmac_f32_e32 v28, v116, v59
	v_fmac_f32_e32 v44, v118, v75
	v_fmac_f32_dpp v28, v59, v122 quad_perm:[1,0,3,2] row_mask:0xf bank_mask:0xf
	v_fmac_f32_dpp v44, v75, v123 quad_perm:[1,0,3,2] row_mask:0xf bank_mask:0xf
	v_cvt_pk_bf16_f32 v148, v28, v44
	ds_write_b32 v151, v148 offset:6528
	v_fmac_f32_e32 v29, v116, v28
	v_fmac_f32_e32 v45, v118, v44
	v_fmac_f32_dpp v29, v28, v122 quad_perm:[1,0,3,2] row_mask:0xf bank_mask:0xf
	v_fmac_f32_dpp v45, v44, v123 quad_perm:[1,0,3,2] row_mask:0xf bank_mask:0xf
	v_cvt_pk_bf16_f32 v149, v29, v45
	ds_write_b32 v151, v149 offset:6800
	v_fmac_f32_e32 v30, v116, v29
	v_fmac_f32_e32 v46, v118, v45
	v_fmac_f32_dpp v30, v29, v122 quad_perm:[1,0,3,2] row_mask:0xf bank_mask:0xf
	v_fmac_f32_dpp v46, v45, v123 quad_perm:[1,0,3,2] row_mask:0xf bank_mask:0xf
	v_cvt_pk_bf16_f32 v148, v30, v46
	ds_write_b32 v151, v148 offset:7072
	v_fmac_f32_e32 v31, v116, v30
	v_fmac_f32_e32 v47, v118, v46
	v_fmac_f32_dpp v31, v30, v122 quad_perm:[1,0,3,2] row_mask:0xf bank_mask:0xf
	v_fmac_f32_dpp v47, v46, v123 quad_perm:[1,0,3,2] row_mask:0xf bank_mask:0xf
	v_cvt_pk_bf16_f32 v149, v31, v47
	ds_write_b32 v151, v149 offset:7344
	v_fmac_f32_e32 v60, v116, v31
	v_fmac_f32_e32 v76, v118, v47
	v_fmac_f32_dpp v60, v31, v122 quad_perm:[1,0,3,2] row_mask:0xf bank_mask:0xf
	v_fmac_f32_dpp v76, v47, v123 quad_perm:[1,0,3,2] row_mask:0xf bank_mask:0xf
	v_cvt_pk_bf16_f32 v148, v60, v76
	ds_write_b32 v151, v148 offset:7616
	v_fmac_f32_e32 v61, v116, v60
	v_fmac_f32_e32 v77, v118, v76
	v_fmac_f32_dpp v61, v60, v122 quad_perm:[1,0,3,2] row_mask:0xf bank_mask:0xf
	v_fmac_f32_dpp v77, v76, v123 quad_perm:[1,0,3,2] row_mask:0xf bank_mask:0xf
	v_cvt_pk_bf16_f32 v149, v61, v77
	ds_write_b32 v151, v149 offset:7888
	v_fmac_f32_e32 v62, v116, v61
	v_fmac_f32_e32 v78, v118, v77
	v_fmac_f32_dpp v62, v61, v122 quad_perm:[1,0,3,2] row_mask:0xf bank_mask:0xf
	v_fmac_f32_dpp v78, v77, v123 quad_perm:[1,0,3,2] row_mask:0xf bank_mask:0xf
	v_cvt_pk_bf16_f32 v148, v62, v78
	ds_write_b32 v151, v148 offset:8160
	v_fmac_f32_e32 v63, v116, v62
	v_fmac_f32_e32 v79, v118, v78
	v_fmac_f32_dpp v63, v62, v122 quad_perm:[1,0,3,2] row_mask:0xf bank_mask:0xf
	v_fmac_f32_dpp v79, v78, v123 quad_perm:[1,0,3,2] row_mask:0xf bank_mask:0xf
	v_cvt_pk_bf16_f32 v149, v63, v79
	ds_write_b32 v151, v149 offset:8432
	v_mov_b32_e32 v120, v63
	v_mov_b32_e32 v121, v79
	ds_read_b128 v[124:127], v152
	ds_read_b128 v[128:131], v152 offset:64
	ds_read_b128 v[132:135], v152 offset:128
	ds_read_b128 v[136:139], v152 offset:192
	s_waitcnt lgkmcnt(3)
	v_mfma_f32_16x16x32_bf16 v[140:143], v[100:103], v[124:127], 0
	s_waitcnt lgkmcnt(2)
	v_mfma_f32_16x16x32_bf16 v[140:143], v[104:107], v[128:131], v[140:143]
	s_waitcnt lgkmcnt(1)
	v_mfma_f32_16x16x32_bf16 v[140:143], v[108:111], v[132:135], v[140:143]
	s_waitcnt lgkmcnt(0)
	v_mfma_f32_16x16x32_bf16 v[140:143], v[112:115], v[136:139], v[140:143]
	s_nop 9
	global_store_dwordx4 v153, v[140:143], s[12:13]
	s_nop 1
	ds_read_b128 v[124:127], v152 offset:4352
	ds_read_b128 v[128:131], v152 offset:4416
	ds_read_b128 v[132:135], v152 offset:4480
	ds_read_b128 v[136:139], v152 offset:4544
	s_waitcnt lgkmcnt(3)
	v_mfma_f32_16x16x32_bf16 v[140:143], v[100:103], v[124:127], 0
	s_waitcnt lgkmcnt(2)
	v_mfma_f32_16x16x32_bf16 v[140:143], v[104:107], v[128:131], v[140:143]
	s_waitcnt lgkmcnt(1)
	v_mfma_f32_16x16x32_bf16 v[140:143], v[108:111], v[132:135], v[140:143]
	s_waitcnt lgkmcnt(0)
	v_mfma_f32_16x16x32_bf16 v[140:143], v[112:115], v[136:139], v[140:143]
	s_nop 9
	global_store_dwordx4 v157, v[140:143], s[12:13]
	s_nop 1
	s_add_u32 s12, s12, 2048
	s_addc_u32 s13, s13, 0
	s_add_u32 s14, s14, 2
	s_cmp_lt_u32 s14, 16
	s_cbranch_scc1 .Lssm_tileA_d0m0
	s_waitcnt vmcnt(0) lgkmcnt(0)
	s_lshr_b32 s21, s89, 1
	s_lshl_b32 s21, s21, 2
	s_add_u32 s37, s21, 0x21000
	v_mov_b32_e32 v182, s37
	v_mov_b32_e32 v183, 1
	v_cmp_eq_u32_e32 vcc, 0, v191
	s_and_saveexec_b64 s[0:1], vcc
	ds_add_u32 v182, v183
	s_mov_b64 exec, s[0:1]
	s_waitcnt lgkmcnt(0)
	s_mov_b32 s38, 0

.Lssm_tileB_d0m0:
	s_waitcnt vmcnt(8)
	v_cndmask_b32_e64 v124, 0, v80, s[66:67]
	v_cndmask_b32_e64 v125, 0, v81, s[66:67]
	v_cndmask_b32_e64 v126, 0, v82, s[66:67]
	v_cndmask_b32_e64 v127, 0, v83, s[66:67]
	v_cndmask_b32_e64 v132, 0, v194, s[66:67]
	v_cndmask_b32_e64 v133, 0, v195, s[66:67]
	v_cndmask_b32_e64 v134, 0, v196, s[66:67]
	v_cndmask_b32_e64 v135, 0, v197, s[66:67]
	v_mfma_f32_32x32x16_bf16 v[16:31], v[124:127], v[84:87], 0
	v_cndmask_b32_e64 v128, 0, v194, s[68:69]
	v_cndmask_b32_e64 v129, 0, v195, s[68:69]
	v_cndmask_b32_e64 v130, 0, v196, s[68:69]
	v_cndmask_b32_e64 v131, 0, v197, s[68:69]
	v_mfma_f32_32x32x16_bf16 v[32:47], v[124:127], v[88:91], 0
	v_cndmask_b32_e64 v136, 0, v80, s[68:69]
	v_cndmask_b32_e64 v137, 0, v81, s[68:69]
	v_cndmask_b32_e64 v138, 0, v82, s[68:69]
	v_cndmask_b32_e64 v139, 0, v83, s[68:69]
	v_mfma_f32_32x32x16_bf16 v[48:63], v[132:135], v[84:87], 0
	v_mfma_f32_32x32x16_bf16 v[64:79], v[132:135], v[88:91], 0
	v_mfma_f32_32x32x16_bf16 v[16:31], v[128:131], v[92:95], v[16:31]
	v_mfma_f32_32x32x16_bf16 v[32:47], v[128:131], v[96:99], v[32:47]
	v_mfma_f32_32x32x16_bf16 v[48:63], v[136:139], v[92:95], v[48:63]
	v_mfma_f32_32x32x16_bf16 v[64:79], v[136:139], v[96:99], v[64:79]
	ds_write_b128 v162, v[80:83]
	global_load_dwordx4 v[172:175], v153, s[42:43]
	global_load_dwordx4 v[176:179], v157, s[42:43]
	s_add_u32 s42, s42, 2048
	s_addc_u32 s43, s43, 0
	s_nop 11
	global_load_dwordx4 v[80:83], v150, s[10:11]
	global_load_dwordx4 v[194:197], v193, s[10:11]
	s_add_u32 s34, s34, 1024
	s_addc_u32 s35, s35, 0
	s_add_u32 s10, s10, 1024
	s_addc_u32 s11, s11, 0
	v_fmac_f32_e32 v16, v116, v120
	v_fmac_f32_e32 v32, v118, v121
	v_fmac_f32_dpp v16, v120, v122 quad_perm:[1,0,3,2] row_mask:0xf bank_mask:0xf
	v_fmac_f32_dpp v32, v121, v123 quad_perm:[1,0,3,2] row_mask:0xf bank_mask:0xf
	v_cvt_pk_bf16_f32 v148, v16, v32
	ds_write_b32 v151, v148
	v_fmac_f32_e32 v17, v116, v16
	v_fmac_f32_e32 v33, v118, v32
	v_fmac_f32_dpp v17, v16, v122 quad_perm:[1,0,3,2] row_mask:0xf bank_mask:0xf
	v_fmac_f32_dpp v33, v32, v123 quad_perm:[1,0,3,2] row_mask:0xf bank_mask:0xf
	v_cvt_pk_bf16_f32 v149, v17, v33
	ds_write_b32 v151, v149 offset:272
	v_fmac_f32_e32 v18, v116, v17
	v_fmac_f32_e32 v34, v118, v33
	v_fmac_f32_dpp v18, v17, v122 quad_perm:[1,0,3,2] row_mask:0xf bank_mask:0xf
	v_fmac_f32_dpp v34, v33, v123 quad_perm:[1,0,3,2] row_mask:0xf bank_mask:0xf
	v_cvt_pk_bf16_f32 v148, v18, v34
	ds_write_b32 v151, v148 offset:544
	v_fmac_f32_e32 v19, v116, v18
	v_fmac_f32_e32 v35, v118, v34
	v_fmac_f32_dpp v19, v18, v122 quad_perm:[1,0,3,2] row_mask:0xf bank_mask:0xf
	v_fmac_f32_dpp v35, v34, v123 quad_perm:[1,0,3,2] row_mask:0xf bank_mask:0xf
	v_cvt_pk_bf16_f32 v149, v19, v35
	ds_write_b32 v151, v149 offset:816
	v_fmac_f32_e32 v48, v116, v19
	v_fmac_f32_e32 v64, v118, v35
	v_fmac_f32_dpp v48, v19, v122 quad_perm:[1,0,3,2] row_mask:0xf bank_mask:0xf
	v_fmac_f32_dpp v64, v35, v123 quad_perm:[1,0,3,2] row_mask:0xf bank_mask:0xf
	v_cvt_pk_bf16_f32 v148, v48, v64
	ds_write_b32 v151, v148 offset:1088
	v_fmac_f32_e32 v49, v116, v48
	v_fmac_f32_e32 v65, v118, v64
	v_fmac_f32_dpp v49, v48, v122 quad_perm:[1,0,3,2] row_mask:0xf bank_mask:0xf
	v_fmac_f32_dpp v65, v64, v123 quad_perm:[1,0,3,2] row_mask:0xf bank_mask:0xf
	v_cvt_pk_bf16_f32 v149, v49, v65
	ds_write_b32 v151, v149 offset:1360
	v_fmac_f32_e32 v50, v116, v49
	v_fmac_f32_e32 v66, v118, v65
	v_fmac_f32_dpp v50, v49, v122 quad_perm:[1,0,3,2] row_mask:0xf bank_mask:0xf
	v_fmac_f32_dpp v66, v65, v123 quad_perm:[1,0,3,2] row_mask:0xf bank_mask:0xf
	v_cvt_pk_bf16_f32 v148, v50, v66
	ds_write_b32 v151, v148 offset:1632
	v_fmac_f32_e32 v51, v116, v50
	v_fmac_f32_e32 v67, v118, v66
	v_fmac_f32_dpp v51, v50, v122 quad_perm:[1,0,3,2] row_mask:0xf bank_mask:0xf
	v_fmac_f32_dpp v67, v66, v123 quad_perm:[1,0,3,2] row_mask:0xf bank_mask:0xf
	v_cvt_pk_bf16_f32 v149, v51, v67
	ds_write_b32 v151, v149 offset:1904
	v_fmac_f32_e32 v20, v116, v51
	v_fmac_f32_e32 v36, v118, v67
	v_fmac_f32_dpp v20, v51, v122 quad_perm:[1,0,3,2] row_mask:0xf bank_mask:0xf
	v_fmac_f32_dpp v36, v67, v123 quad_perm:[1,0,3,2] row_mask:0xf bank_mask:0xf
	v_cvt_pk_bf16_f32 v148, v20, v36
	ds_write_b32 v151, v148 offset:2176
	v_fmac_f32_e32 v21, v116, v20
	v_fmac_f32_e32 v37, v118, v36
	v_fmac_f32_dpp v21, v20, v122 quad_perm:[1,0,3,2] row_mask:0xf bank_mask:0xf
	v_fmac_f32_dpp v37, v36, v123 quad_perm:[1,0,3,2] row_mask:0xf bank_mask:0xf
	v_cvt_pk_bf16_f32 v149, v21, v37
	ds_write_b32 v151, v149 offset:2448
	v_fmac_f32_e32 v22, v116, v21
	v_fmac_f32_e32 v38, v118, v37
	v_fmac_f32_dpp v22, v21, v122 quad_perm:[1,0,3,2] row_mask:0xf bank_mask:0xf
	v_fmac_f32_dpp v38, v37, v123 quad_perm:[1,0,3,2] row_mask:0xf bank_mask:0xf
	v_cvt_pk_bf16_f32 v148, v22, v38
	ds_write_b32 v151, v148 offset:2720
	v_fmac_f32_e32 v23, v116, v22
	v_fmac_f32_e32 v39, v118, v38
	v_fmac_f32_dpp v23, v22, v122 quad_perm:[1,0,3,2] row_mask:0xf bank_mask:0xf
	v_fmac_f32_dpp v39, v38, v123 quad_perm:[1,0,3,2] row_mask:0xf bank_mask:0xf
	v_cvt_pk_bf16_f32 v149, v23, v39
	ds_write_b32 v151, v149 offset:2992
	v_fmac_f32_e32 v52, v116, v23
	v_fmac_f32_e32 v68, v118, v39
	v_fmac_f32_dpp v52, v23, v122 quad_perm:[1,0,3,2] row_mask:0xf bank_mask:0xf
	v_fmac_f32_dpp v68, v39, v123 quad_perm:[1,0,3,2] row_mask:0xf bank_mask:0xf
	v_cvt_pk_bf16_f32 v148, v52, v68
	ds_write_b32 v151, v148 offset:3264
	v_fmac_f32_e32 v53, v116, v52
	v_fmac_f32_e32 v69, v118, v68
	v_fmac_f32_dpp v53, v52, v122 quad_perm:[1,0,3,2] row_mask:0xf bank_mask:0xf
	v_fmac_f32_dpp v69, v68, v123 quad_perm:[1,0,3,2] row_mask:0xf bank_mask:0xf
	v_cvt_pk_bf16_f32 v149, v53, v69
	ds_write_b32 v151, v149 offset:3536
	v_fmac_f32_e32 v54, v116, v53
	v_fmac_f32_e32 v70, v118, v69
	v_fmac_f32_dpp v54, v53, v122 quad_perm:[1,0,3,2] row_mask:0xf bank_mask:0xf
	v_fmac_f32_dpp v70, v69, v123 quad_perm:[1,0,3,2] row_mask:0xf bank_mask:0xf
	v_cvt_pk_bf16_f32 v148, v54, v70
	ds_write_b32 v151, v148 offset:3808
	v_fmac_f32_e32 v55, v116, v54
	v_fmac_f32_e32 v71, v118, v70
	v_fmac_f32_dpp v55, v54, v122 quad_perm:[1,0,3,2] row_mask:0xf bank_mask:0xf
	v_fmac_f32_dpp v71, v70, v123 quad_perm:[1,0,3,2] row_mask:0xf bank_mask:0xf
	v_cvt_pk_bf16_f32 v149, v55, v71
	ds_write_b32 v151, v149 offset:4080
	v_fmac_f32_e32 v24, v116, v55
	v_fmac_f32_e32 v40, v118, v71
	v_fmac_f32_dpp v24, v55, v122 quad_perm:[1,0,3,2] row_mask:0xf bank_mask:0xf
	v_fmac_f32_dpp v40, v71, v123 quad_perm:[1,0,3,2] row_mask:0xf bank_mask:0xf
	v_cvt_pk_bf16_f32 v148, v24, v40
	ds_write_b32 v151, v148 offset:4352
	v_fmac_f32_e32 v25, v116, v24
	v_fmac_f32_e32 v41, v118, v40
	v_fmac_f32_dpp v25, v24, v122 quad_perm:[1,0,3,2] row_mask:0xf bank_mask:0xf
	v_fmac_f32_dpp v41, v40, v123 quad_perm:[1,0,3,2] row_mask:0xf bank_mask:0xf
	v_cvt_pk_bf16_f32 v149, v25, v41
	ds_write_b32 v151, v149 offset:4624
	v_fmac_f32_e32 v26, v116, v25
	v_fmac_f32_e32 v42, v118, v41
	v_fmac_f32_dpp v26, v25, v122 quad_perm:[1,0,3,2] row_mask:0xf bank_mask:0xf
	v_fmac_f32_dpp v42, v41, v123 quad_perm:[1,0,3,2] row_mask:0xf bank_mask:0xf
	v_cvt_pk_bf16_f32 v148, v26, v42
	ds_write_b32 v151, v148 offset:4896
	v_fmac_f32_e32 v27, v116, v26
	v_fmac_f32_e32 v43, v118, v42
	v_fmac_f32_dpp v27, v26, v122 quad_perm:[1,0,3,2] row_mask:0xf bank_mask:0xf
	v_fmac_f32_dpp v43, v42, v123 quad_perm:[1,0,3,2] row_mask:0xf bank_mask:0xf
	v_cvt_pk_bf16_f32 v149, v27, v43
	ds_write_b32 v151, v149 offset:5168
	v_fmac_f32_e32 v56, v116, v27
	v_fmac_f32_e32 v72, v118, v43
	v_fmac_f32_dpp v56, v27, v122 quad_perm:[1,0,3,2] row_mask:0xf bank_mask:0xf
	v_fmac_f32_dpp v72, v43, v123 quad_perm:[1,0,3,2] row_mask:0xf bank_mask:0xf
	v_cvt_pk_bf16_f32 v148, v56, v72
	ds_write_b32 v151, v148 offset:5440
	v_fmac_f32_e32 v57, v116, v56
	v_fmac_f32_e32 v73, v118, v72
	v_fmac_f32_dpp v57, v56, v122 quad_perm:[1,0,3,2] row_mask:0xf bank_mask:0xf
	v_fmac_f32_dpp v73, v72, v123 quad_perm:[1,0,3,2] row_mask:0xf bank_mask:0xf
	v_cvt_pk_bf16_f32 v149, v57, v73
	ds_write_b32 v151, v149 offset:5712
	v_fmac_f32_e32 v58, v116, v57
	v_fmac_f32_e32 v74, v118, v73
	v_fmac_f32_dpp v58, v57, v122 quad_perm:[1,0,3,2] row_mask:0xf bank_mask:0xf
	v_fmac_f32_dpp v74, v73, v123 quad_perm:[1,0,3,2] row_mask:0xf bank_mask:0xf
	v_cvt_pk_bf16_f32 v148, v58, v74
	ds_write_b32 v151, v148 offset:5984
	v_fmac_f32_e32 v59, v116, v58
	v_fmac_f32_e32 v75, v118, v74
	v_fmac_f32_dpp v59, v58, v122 quad_perm:[1,0,3,2] row_mask:0xf bank_mask:0xf
	v_fmac_f32_dpp v75, v74, v123 quad_perm:[1,0,3,2] row_mask:0xf bank_mask:0xf
	v_cvt_pk_bf16_f32 v149, v59, v75
	ds_write_b32 v151, v149 offset:6256
	v_fmac_f32_e32 v28, v116, v59
	v_fmac_f32_e32 v44, v118, v75
	v_fmac_f32_dpp v28, v59, v122 quad_perm:[1,0,3,2] row_mask:0xf bank_mask:0xf
	v_fmac_f32_dpp v44, v75, v123 quad_perm:[1,0,3,2] row_mask:0xf bank_mask:0xf
	v_cvt_pk_bf16_f32 v148, v28, v44
	ds_write_b32 v151, v148 offset:6528
	v_fmac_f32_e32 v29, v116, v28
	v_fmac_f32_e32 v45, v118, v44
	v_fmac_f32_dpp v29, v28, v122 quad_perm:[1,0,3,2] row_mask:0xf bank_mask:0xf
	v_fmac_f32_dpp v45, v44, v123 quad_perm:[1,0,3,2] row_mask:0xf bank_mask:0xf
	v_cvt_pk_bf16_f32 v149, v29, v45
	ds_write_b32 v151, v149 offset:6800
	v_fmac_f32_e32 v30, v116, v29
	v_fmac_f32_e32 v46, v118, v45
	v_fmac_f32_dpp v30, v29, v122 quad_perm:[1,0,3,2] row_mask:0xf bank_mask:0xf
	v_fmac_f32_dpp v46, v45, v123 quad_perm:[1,0,3,2] row_mask:0xf bank_mask:0xf
	v_cvt_pk_bf16_f32 v148, v30, v46
	ds_write_b32 v151, v148 offset:7072
	v_fmac_f32_e32 v31, v116, v30
	v_fmac_f32_e32 v47, v118, v46
	v_fmac_f32_dpp v31, v30, v122 quad_perm:[1,0,3,2] row_mask:0xf bank_mask:0xf
	v_fmac_f32_dpp v47, v46, v123 quad_perm:[1,0,3,2] row_mask:0xf bank_mask:0xf
	v_cvt_pk_bf16_f32 v149, v31, v47
	ds_write_b32 v151, v149 offset:7344
	v_fmac_f32_e32 v60, v116, v31
	v_fmac_f32_e32 v76, v118, v47
	v_fmac_f32_dpp v60, v31, v122 quad_perm:[1,0,3,2] row_mask:0xf bank_mask:0xf
	v_fmac_f32_dpp v76, v47, v123 quad_perm:[1,0,3,2] row_mask:0xf bank_mask:0xf
	v_cvt_pk_bf16_f32 v148, v60, v76
	ds_write_b32 v151, v148 offset:7616
	v_fmac_f32_e32 v61, v116, v60
	v_fmac_f32_e32 v77, v118, v76
	v_fmac_f32_dpp v61, v60, v122 quad_perm:[1,0,3,2] row_mask:0xf bank_mask:0xf
	v_fmac_f32_dpp v77, v76, v123 quad_perm:[1,0,3,2] row_mask:0xf bank_mask:0xf
	v_cvt_pk_bf16_f32 v149, v61, v77
	ds_write_b32 v151, v149 offset:7888
	v_fmac_f32_e32 v62, v116, v61
	v_fmac_f32_e32 v78, v118, v77
	v_fmac_f32_dpp v62, v61, v122 quad_perm:[1,0,3,2] row_mask:0xf bank_mask:0xf
	v_fmac_f32_dpp v78, v77, v123 quad_perm:[1,0,3,2] row_mask:0xf bank_mask:0xf
	v_cvt_pk_bf16_f32 v148, v62, v78
	ds_write_b32 v151, v148 offset:8160
	v_fmac_f32_e32 v63, v116, v62
	v_fmac_f32_e32 v79, v118, v78
	v_fmac_f32_dpp v63, v62, v122 quad_perm:[1,0,3,2] row_mask:0xf bank_mask:0xf
	v_fmac_f32_dpp v79, v78, v123 quad_perm:[1,0,3,2] row_mask:0xf bank_mask:0xf
	v_cvt_pk_bf16_f32 v149, v63, v79
	ds_write_b32 v151, v149 offset:8432
	v_mov_b32_e32 v120, v63
	v_mov_b32_e32 v121, v79
	ds_read_b128 v[124:127], v152
	ds_read_b128 v[128:131], v152 offset:64
	ds_read_b128 v[132:135], v152 offset:128
	ds_read_b128 v[136:139], v152 offset:192
	ds_read_b64 v[160:161], v163
	s_waitcnt lgkmcnt(4)
	v_mfma_f32_16x16x32_bf16 v[140:143], v[100:103], v[124:127], 0
	s_waitcnt lgkmcnt(3)
	v_mfma_f32_16x16x32_bf16 v[140:143], v[104:107], v[128:131], v[140:143]
	s_waitcnt lgkmcnt(2)
	v_mfma_f32_16x16x32_bf16 v[140:143], v[108:111], v[132:135], v[140:143]
	s_waitcnt lgkmcnt(1)
	v_mfma_f32_16x16x32_bf16 v[140:143], v[112:115], v[136:139], v[140:143]
	s_nop 9
	s_waitcnt vmcnt(9) lgkmcnt(0)
	v_add_f32_e32 v182, v6, v140
	v_add_f32_e32 v183, v7, v141
	v_add_f32_e32 v184, v8, v142
	v_add_f32_e32 v185, v9, v143
	v_lshlrev_b32_e32 v186, 16, v160
	v_and_b32_e32 v187, 0xffff0000, v160
	v_lshlrev_b32_e32 v188, 16, v161
	v_and_b32_e32 v189, 0xffff0000, v161
	v_fmac_f32_e32 v182, v164, v186
	v_fmac_f32_e32 v183, v165, v187
	v_fmac_f32_e32 v184, v166, v188
	v_fmac_f32_e32 v185, v167, v189
	v_mul_f32_e32 v186, 0x3d372713, v182
	v_mul_f32_e32 v187, 0x3d372713, v183
	v_mul_f32_e32 v188, 0x3d372713, v184
	v_mul_f32_e32 v189, 0x3d372713, v185
	v_mul_f32_e32 v186, v182, v186
	v_mul_f32_e32 v187, v183, v187
	v_mul_f32_e32 v188, v184, v188
	v_mul_f32_e32 v189, v185, v189
	v_fma_f32 v186, v182, v186, v182
	v_fma_f32 v187, v183, v187, v183
	v_fma_f32 v188, v184, v188, v184
	v_fma_f32 v189, v185, v189, v185
	v_mul_f32_e32 v186, 0xbfcc422a, v186
	v_mul_f32_e32 v187, 0xbfcc422a, v187
	v_mul_f32_e32 v188, 0xbfcc422a, v188
	v_mul_f32_e32 v189, 0xbfcc422a, v189
	v_mul_f32_e32 v186, 0x3fb8aa3b, v186
	v_mul_f32_e32 v187, 0x3fb8aa3b, v187
	v_mul_f32_e32 v188, 0x3fb8aa3b, v188
	v_mul_f32_e32 v189, 0x3fb8aa3b, v189
	v_exp_f32_e32 v186, v186
	v_exp_f32_e32 v187, v187
	v_exp_f32_e32 v188, v188
	v_exp_f32_e32 v189, v189
	v_add_f32_e32 v186, 1.0, v186
	v_add_f32_e32 v187, 1.0, v187
	v_add_f32_e32 v188, 1.0, v188
	v_add_f32_e32 v189, 1.0, v189
	v_rcp_f32_e32 v186, v186
	v_rcp_f32_e32 v187, v187
	v_rcp_f32_e32 v188, v188
	v_rcp_f32_e32 v189, v189
	v_mul_f32_e32 v182, v182, v186
	v_mul_f32_e32 v183, v183, v187
	v_mul_f32_e32 v184, v184, v188
	v_mul_f32_e32 v185, v185, v189
	v_cvt_pk_bf16_f32 v148, v182, v183
	v_cvt_pk_bf16_f32 v149, v184, v185
	global_store_dwordx2 v156, v[148:149], s[12:13]
	ds_read_b128 v[124:127], v152 offset:4352
	ds_read_b128 v[128:131], v152 offset:4416
	ds_read_b128 v[132:135], v152 offset:4480
	ds_read_b128 v[136:139], v152 offset:4544
	ds_read_b64 v[160:161], v163 offset:512
	s_waitcnt lgkmcnt(4)
	v_mfma_f32_16x16x32_bf16 v[140:143], v[100:103], v[124:127], 0
	s_waitcnt lgkmcnt(3)
	v_mfma_f32_16x16x32_bf16 v[140:143], v[104:107], v[128:131], v[140:143]
	s_waitcnt lgkmcnt(2)
	v_mfma_f32_16x16x32_bf16 v[140:143], v[108:111], v[132:135], v[140:143]
	s_waitcnt lgkmcnt(1)
	v_mfma_f32_16x16x32_bf16 v[140:143], v[112:115], v[136:139], v[140:143]
	s_nop 9
	s_waitcnt vmcnt(9) lgkmcnt(0)
	v_add_f32_e32 v182, v10, v140
	v_add_f32_e32 v183, v11, v141
	v_add_f32_e32 v184, v12, v142
	v_add_f32_e32 v185, v13, v143
	v_lshlrev_b32_e32 v186, 16, v160
	v_and_b32_e32 v187, 0xffff0000, v160
	v_lshlrev_b32_e32 v188, 16, v161
	v_and_b32_e32 v189, 0xffff0000, v161
	v_fmac_f32_e32 v182, v164, v186
	v_fmac_f32_e32 v183, v165, v187
	v_fmac_f32_e32 v184, v166, v188
	v_fmac_f32_e32 v185, v167, v189
	v_mul_f32_e32 v186, 0x3d372713, v182
	v_mul_f32_e32 v187, 0x3d372713, v183
	v_mul_f32_e32 v188, 0x3d372713, v184
	v_mul_f32_e32 v189, 0x3d372713, v185
	v_mul_f32_e32 v186, v182, v186
	v_mul_f32_e32 v187, v183, v187
	v_mul_f32_e32 v188, v184, v188
	v_mul_f32_e32 v189, v185, v189
	v_fma_f32 v186, v182, v186, v182
	v_fma_f32 v187, v183, v187, v183
	v_fma_f32 v188, v184, v188, v184
	v_fma_f32 v189, v185, v189, v185
	v_mul_f32_e32 v186, 0xbfcc422a, v186
	v_mul_f32_e32 v187, 0xbfcc422a, v187
	v_mul_f32_e32 v188, 0xbfcc422a, v188
	v_mul_f32_e32 v189, 0xbfcc422a, v189
	v_mul_f32_e32 v186, 0x3fb8aa3b, v186
	v_mul_f32_e32 v187, 0x3fb8aa3b, v187
	v_mul_f32_e32 v188, 0x3fb8aa3b, v188
	v_mul_f32_e32 v189, 0x3fb8aa3b, v189
	v_exp_f32_e32 v186, v186
	v_exp_f32_e32 v187, v187
	v_exp_f32_e32 v188, v188
	v_exp_f32_e32 v189, v189
	v_add_f32_e32 v186, 1.0, v186
	v_add_f32_e32 v187, 1.0, v187
	v_add_f32_e32 v188, 1.0, v188
	v_add_f32_e32 v189, 1.0, v189
	v_rcp_f32_e32 v186, v186
	v_rcp_f32_e32 v187, v187
	v_rcp_f32_e32 v188, v188
	v_rcp_f32_e32 v189, v189
	v_mul_f32_e32 v182, v182, v186
	v_mul_f32_e32 v183, v183, v187
	v_mul_f32_e32 v184, v184, v188
	v_mul_f32_e32 v185, v185, v189
	v_cvt_pk_bf16_f32 v148, v182, v183
	v_cvt_pk_bf16_f32 v149, v184, v185
	global_store_dwordx2 v159, v[148:149], s[12:13]
	s_add_u32 s12, s12, 65536
	s_addc_u32 s13, s13, 0
	s_waitcnt vmcnt(8)
	v_cndmask_b32_e64 v124, 0, v144, s[66:67]
	v_cndmask_b32_e64 v125, 0, v145, s[66:67]
	v_cndmask_b32_e64 v126, 0, v146, s[66:67]
	v_cndmask_b32_e64 v127, 0, v147, s[66:67]
	v_cndmask_b32_e64 v132, 0, v168, s[66:67]
	v_cndmask_b32_e64 v133, 0, v169, s[66:67]
	v_cndmask_b32_e64 v134, 0, v170, s[66:67]
	v_cndmask_b32_e64 v135, 0, v171, s[66:67]
	v_mfma_f32_32x32x16_bf16 v[16:31], v[124:127], v[84:87], 0
	v_cndmask_b32_e64 v128, 0, v168, s[68:69]
	v_cndmask_b32_e64 v129, 0, v169, s[68:69]
	v_cndmask_b32_e64 v130, 0, v170, s[68:69]
	v_cndmask_b32_e64 v131, 0, v171, s[68:69]
	v_mfma_f32_32x32x16_bf16 v[32:47], v[124:127], v[88:91], 0
	v_cndmask_b32_e64 v136, 0, v144, s[68:69]
	v_cndmask_b32_e64 v137, 0, v145, s[68:69]
	v_cndmask_b32_e64 v138, 0, v146, s[68:69]
	v_cndmask_b32_e64 v139, 0, v147, s[68:69]
	v_mfma_f32_32x32x16_bf16 v[48:63], v[132:135], v[84:87], 0
	v_mfma_f32_32x32x16_bf16 v[64:79], v[132:135], v[88:91], 0
	v_mfma_f32_32x32x16_bf16 v[16:31], v[128:131], v[92:95], v[16:31]
	v_mfma_f32_32x32x16_bf16 v[32:47], v[128:131], v[96:99], v[32:47]
	v_mfma_f32_32x32x16_bf16 v[48:63], v[136:139], v[92:95], v[48:63]
	v_mfma_f32_32x32x16_bf16 v[64:79], v[136:139], v[96:99], v[64:79]
	ds_write_b128 v162, v[144:147]
	global_load_dwordx4 v[6:9], v153, s[42:43]
	global_load_dwordx4 v[10:13], v157, s[42:43]
	s_add_u32 s42, s42, 2048
	s_addc_u32 s43, s43, 0
	s_nop 11
	global_load_dwordx4 v[144:147], v150, s[10:11]
	global_load_dwordx4 v[168:171], v193, s[10:11]
	s_add_u32 s34, s34, 1024
	s_addc_u32 s35, s35, 0
	s_add_u32 s10, s10, 1024
	s_addc_u32 s11, s11, 0
	v_fmac_f32_e32 v16, v116, v120
	v_fmac_f32_e32 v32, v118, v121
	v_fmac_f32_dpp v16, v120, v122 quad_perm:[1,0,3,2] row_mask:0xf bank_mask:0xf
	v_fmac_f32_dpp v32, v121, v123 quad_perm:[1,0,3,2] row_mask:0xf bank_mask:0xf
	v_cvt_pk_bf16_f32 v148, v16, v32
	ds_write_b32 v151, v148
	v_fmac_f32_e32 v17, v116, v16
	v_fmac_f32_e32 v33, v118, v32
	v_fmac_f32_dpp v17, v16, v122 quad_perm:[1,0,3,2] row_mask:0xf bank_mask:0xf
	v_fmac_f32_dpp v33, v32, v123 quad_perm:[1,0,3,2] row_mask:0xf bank_mask:0xf
	v_cvt_pk_bf16_f32 v149, v17, v33
	ds_write_b32 v151, v149 offset:272
	v_fmac_f32_e32 v18, v116, v17
	v_fmac_f32_e32 v34, v118, v33
	v_fmac_f32_dpp v18, v17, v122 quad_perm:[1,0,3,2] row_mask:0xf bank_mask:0xf
	v_fmac_f32_dpp v34, v33, v123 quad_perm:[1,0,3,2] row_mask:0xf bank_mask:0xf
	v_cvt_pk_bf16_f32 v148, v18, v34
	ds_write_b32 v151, v148 offset:544
	v_fmac_f32_e32 v19, v116, v18
	v_fmac_f32_e32 v35, v118, v34
	v_fmac_f32_dpp v19, v18, v122 quad_perm:[1,0,3,2] row_mask:0xf bank_mask:0xf
	v_fmac_f32_dpp v35, v34, v123 quad_perm:[1,0,3,2] row_mask:0xf bank_mask:0xf
	v_cvt_pk_bf16_f32 v149, v19, v35
	ds_write_b32 v151, v149 offset:816
	v_fmac_f32_e32 v48, v116, v19
	v_fmac_f32_e32 v64, v118, v35
	v_fmac_f32_dpp v48, v19, v122 quad_perm:[1,0,3,2] row_mask:0xf bank_mask:0xf
	v_fmac_f32_dpp v64, v35, v123 quad_perm:[1,0,3,2] row_mask:0xf bank_mask:0xf
	v_cvt_pk_bf16_f32 v148, v48, v64
	ds_write_b32 v151, v148 offset:1088
	v_fmac_f32_e32 v49, v116, v48
	v_fmac_f32_e32 v65, v118, v64
	v_fmac_f32_dpp v49, v48, v122 quad_perm:[1,0,3,2] row_mask:0xf bank_mask:0xf
	v_fmac_f32_dpp v65, v64, v123 quad_perm:[1,0,3,2] row_mask:0xf bank_mask:0xf
	v_cvt_pk_bf16_f32 v149, v49, v65
	ds_write_b32 v151, v149 offset:1360
	v_fmac_f32_e32 v50, v116, v49
	v_fmac_f32_e32 v66, v118, v65
	v_fmac_f32_dpp v50, v49, v122 quad_perm:[1,0,3,2] row_mask:0xf bank_mask:0xf
	v_fmac_f32_dpp v66, v65, v123 quad_perm:[1,0,3,2] row_mask:0xf bank_mask:0xf
	v_cvt_pk_bf16_f32 v148, v50, v66
	ds_write_b32 v151, v148 offset:1632
	v_fmac_f32_e32 v51, v116, v50
	v_fmac_f32_e32 v67, v118, v66
	v_fmac_f32_dpp v51, v50, v122 quad_perm:[1,0,3,2] row_mask:0xf bank_mask:0xf
	v_fmac_f32_dpp v67, v66, v123 quad_perm:[1,0,3,2] row_mask:0xf bank_mask:0xf
	v_cvt_pk_bf16_f32 v149, v51, v67
	ds_write_b32 v151, v149 offset:1904
	v_fmac_f32_e32 v20, v116, v51
	v_fmac_f32_e32 v36, v118, v67
	v_fmac_f32_dpp v20, v51, v122 quad_perm:[1,0,3,2] row_mask:0xf bank_mask:0xf
	v_fmac_f32_dpp v36, v67, v123 quad_perm:[1,0,3,2] row_mask:0xf bank_mask:0xf
	v_cvt_pk_bf16_f32 v148, v20, v36
	ds_write_b32 v151, v148 offset:2176
	v_fmac_f32_e32 v21, v116, v20
	v_fmac_f32_e32 v37, v118, v36
	v_fmac_f32_dpp v21, v20, v122 quad_perm:[1,0,3,2] row_mask:0xf bank_mask:0xf
	v_fmac_f32_dpp v37, v36, v123 quad_perm:[1,0,3,2] row_mask:0xf bank_mask:0xf
	v_cvt_pk_bf16_f32 v149, v21, v37
	ds_write_b32 v151, v149 offset:2448
	v_fmac_f32_e32 v22, v116, v21
	v_fmac_f32_e32 v38, v118, v37
	v_fmac_f32_dpp v22, v21, v122 quad_perm:[1,0,3,2] row_mask:0xf bank_mask:0xf
	v_fmac_f32_dpp v38, v37, v123 quad_perm:[1,0,3,2] row_mask:0xf bank_mask:0xf
	v_cvt_pk_bf16_f32 v148, v22, v38
	ds_write_b32 v151, v148 offset:2720
	v_fmac_f32_e32 v23, v116, v22
	v_fmac_f32_e32 v39, v118, v38
	v_fmac_f32_dpp v23, v22, v122 quad_perm:[1,0,3,2] row_mask:0xf bank_mask:0xf
	v_fmac_f32_dpp v39, v38, v123 quad_perm:[1,0,3,2] row_mask:0xf bank_mask:0xf
	v_cvt_pk_bf16_f32 v149, v23, v39
	ds_write_b32 v151, v149 offset:2992
	v_fmac_f32_e32 v52, v116, v23
	v_fmac_f32_e32 v68, v118, v39
	v_fmac_f32_dpp v52, v23, v122 quad_perm:[1,0,3,2] row_mask:0xf bank_mask:0xf
	v_fmac_f32_dpp v68, v39, v123 quad_perm:[1,0,3,2] row_mask:0xf bank_mask:0xf
	v_cvt_pk_bf16_f32 v148, v52, v68
	ds_write_b32 v151, v148 offset:3264
	v_fmac_f32_e32 v53, v116, v52
	v_fmac_f32_e32 v69, v118, v68
	v_fmac_f32_dpp v53, v52, v122 quad_perm:[1,0,3,2] row_mask:0xf bank_mask:0xf
	v_fmac_f32_dpp v69, v68, v123 quad_perm:[1,0,3,2] row_mask:0xf bank_mask:0xf
	v_cvt_pk_bf16_f32 v149, v53, v69
	ds_write_b32 v151, v149 offset:3536
	v_fmac_f32_e32 v54, v116, v53
	v_fmac_f32_e32 v70, v118, v69
	v_fmac_f32_dpp v54, v53, v122 quad_perm:[1,0,3,2] row_mask:0xf bank_mask:0xf
	v_fmac_f32_dpp v70, v69, v123 quad_perm:[1,0,3,2] row_mask:0xf bank_mask:0xf
	v_cvt_pk_bf16_f32 v148, v54, v70
	ds_write_b32 v151, v148 offset:3808
	v_fmac_f32_e32 v55, v116, v54
	v_fmac_f32_e32 v71, v118, v70
	v_fmac_f32_dpp v55, v54, v122 quad_perm:[1,0,3,2] row_mask:0xf bank_mask:0xf
	v_fmac_f32_dpp v71, v70, v123 quad_perm:[1,0,3,2] row_mask:0xf bank_mask:0xf
	v_cvt_pk_bf16_f32 v149, v55, v71
	ds_write_b32 v151, v149 offset:4080
	v_fmac_f32_e32 v24, v116, v55
	v_fmac_f32_e32 v40, v118, v71
	v_fmac_f32_dpp v24, v55, v122 quad_perm:[1,0,3,2] row_mask:0xf bank_mask:0xf
	v_fmac_f32_dpp v40, v71, v123 quad_perm:[1,0,3,2] row_mask:0xf bank_mask:0xf
	v_cvt_pk_bf16_f32 v148, v24, v40
	ds_write_b32 v151, v148 offset:4352
	v_fmac_f32_e32 v25, v116, v24
	v_fmac_f32_e32 v41, v118, v40
	v_fmac_f32_dpp v25, v24, v122 quad_perm:[1,0,3,2] row_mask:0xf bank_mask:0xf
	v_fmac_f32_dpp v41, v40, v123 quad_perm:[1,0,3,2] row_mask:0xf bank_mask:0xf
	v_cvt_pk_bf16_f32 v149, v25, v41
	ds_write_b32 v151, v149 offset:4624
	v_fmac_f32_e32 v26, v116, v25
	v_fmac_f32_e32 v42, v118, v41
	v_fmac_f32_dpp v26, v25, v122 quad_perm:[1,0,3,2] row_mask:0xf bank_mask:0xf
	v_fmac_f32_dpp v42, v41, v123 quad_perm:[1,0,3,2] row_mask:0xf bank_mask:0xf
	v_cvt_pk_bf16_f32 v148, v26, v42
	ds_write_b32 v151, v148 offset:4896
	v_fmac_f32_e32 v27, v116, v26
	v_fmac_f32_e32 v43, v118, v42
	v_fmac_f32_dpp v27, v26, v122 quad_perm:[1,0,3,2] row_mask:0xf bank_mask:0xf
	v_fmac_f32_dpp v43, v42, v123 quad_perm:[1,0,3,2] row_mask:0xf bank_mask:0xf
	v_cvt_pk_bf16_f32 v149, v27, v43
	ds_write_b32 v151, v149 offset:5168
	v_fmac_f32_e32 v56, v116, v27
	v_fmac_f32_e32 v72, v118, v43
	v_fmac_f32_dpp v56, v27, v122 quad_perm:[1,0,3,2] row_mask:0xf bank_mask:0xf
	v_fmac_f32_dpp v72, v43, v123 quad_perm:[1,0,3,2] row_mask:0xf bank_mask:0xf
	v_cvt_pk_bf16_f32 v148, v56, v72
	ds_write_b32 v151, v148 offset:5440
	v_fmac_f32_e32 v57, v116, v56
	v_fmac_f32_e32 v73, v118, v72
	v_fmac_f32_dpp v57, v56, v122 quad_perm:[1,0,3,2] row_mask:0xf bank_mask:0xf
	v_fmac_f32_dpp v73, v72, v123 quad_perm:[1,0,3,2] row_mask:0xf bank_mask:0xf
	v_cvt_pk_bf16_f32 v149, v57, v73
	ds_write_b32 v151, v149 offset:5712
	v_fmac_f32_e32 v58, v116, v57
	v_fmac_f32_e32 v74, v118, v73
	v_fmac_f32_dpp v58, v57, v122 quad_perm:[1,0,3,2] row_mask:0xf bank_mask:0xf
	v_fmac_f32_dpp v74, v73, v123 quad_perm:[1,0,3,2] row_mask:0xf bank_mask:0xf
	v_cvt_pk_bf16_f32 v148, v58, v74
	ds_write_b32 v151, v148 offset:5984
	v_fmac_f32_e32 v59, v116, v58
	v_fmac_f32_e32 v75, v118, v74
	v_fmac_f32_dpp v59, v58, v122 quad_perm:[1,0,3,2] row_mask:0xf bank_mask:0xf
	v_fmac_f32_dpp v75, v74, v123 quad_perm:[1,0,3,2] row_mask:0xf bank_mask:0xf
	v_cvt_pk_bf16_f32 v149, v59, v75
	ds_write_b32 v151, v149 offset:6256
	v_fmac_f32_e32 v28, v116, v59
	v_fmac_f32_e32 v44, v118, v75
	v_fmac_f32_dpp v28, v59, v122 quad_perm:[1,0,3,2] row_mask:0xf bank_mask:0xf
	v_fmac_f32_dpp v44, v75, v123 quad_perm:[1,0,3,2] row_mask:0xf bank_mask:0xf
	v_cvt_pk_bf16_f32 v148, v28, v44
	ds_write_b32 v151, v148 offset:6528
	v_fmac_f32_e32 v29, v116, v28
	v_fmac_f32_e32 v45, v118, v44
	v_fmac_f32_dpp v29, v28, v122 quad_perm:[1,0,3,2] row_mask:0xf bank_mask:0xf
	v_fmac_f32_dpp v45, v44, v123 quad_perm:[1,0,3,2] row_mask:0xf bank_mask:0xf
	v_cvt_pk_bf16_f32 v149, v29, v45
	ds_write_b32 v151, v149 offset:6800
	v_fmac_f32_e32 v30, v116, v29
	v_fmac_f32_e32 v46, v118, v45
	v_fmac_f32_dpp v30, v29, v122 quad_perm:[1,0,3,2] row_mask:0xf bank_mask:0xf
	v_fmac_f32_dpp v46, v45, v123 quad_perm:[1,0,3,2] row_mask:0xf bank_mask:0xf
	v_cvt_pk_bf16_f32 v148, v30, v46
	ds_write_b32 v151, v148 offset:7072
	v_fmac_f32_e32 v31, v116, v30
	v_fmac_f32_e32 v47, v118, v46
	v_fmac_f32_dpp v31, v30, v122 quad_perm:[1,0,3,2] row_mask:0xf bank_mask:0xf
	v_fmac_f32_dpp v47, v46, v123 quad_perm:[1,0,3,2] row_mask:0xf bank_mask:0xf
	v_cvt_pk_bf16_f32 v149, v31, v47
	ds_write_b32 v151, v149 offset:7344
	v_fmac_f32_e32 v60, v116, v31
	v_fmac_f32_e32 v76, v118, v47
	v_fmac_f32_dpp v60, v31, v122 quad_perm:[1,0,3,2] row_mask:0xf bank_mask:0xf
	v_fmac_f32_dpp v76, v47, v123 quad_perm:[1,0,3,2] row_mask:0xf bank_mask:0xf
	v_cvt_pk_bf16_f32 v148, v60, v76
	ds_write_b32 v151, v148 offset:7616
	v_fmac_f32_e32 v61, v116, v60
	v_fmac_f32_e32 v77, v118, v76
	v_fmac_f32_dpp v61, v60, v122 quad_perm:[1,0,3,2] row_mask:0xf bank_mask:0xf
	v_fmac_f32_dpp v77, v76, v123 quad_perm:[1,0,3,2] row_mask:0xf bank_mask:0xf
	v_cvt_pk_bf16_f32 v149, v61, v77
	ds_write_b32 v151, v149 offset:7888
	v_fmac_f32_e32 v62, v116, v61
	v_fmac_f32_e32 v78, v118, v77
	v_fmac_f32_dpp v62, v61, v122 quad_perm:[1,0,3,2] row_mask:0xf bank_mask:0xf
	v_fmac_f32_dpp v78, v77, v123 quad_perm:[1,0,3,2] row_mask:0xf bank_mask:0xf
	v_cvt_pk_bf16_f32 v148, v62, v78
	ds_write_b32 v151, v148 offset:8160
	v_fmac_f32_e32 v63, v116, v62
	v_fmac_f32_e32 v79, v118, v78
	v_fmac_f32_dpp v63, v62, v122 quad_perm:[1,0,3,2] row_mask:0xf bank_mask:0xf
	v_fmac_f32_dpp v79, v78, v123 quad_perm:[1,0,3,2] row_mask:0xf bank_mask:0xf
	v_cvt_pk_bf16_f32 v149, v63, v79
	ds_write_b32 v151, v149 offset:8432
	v_mov_b32_e32 v120, v63
	v_mov_b32_e32 v121, v79
	ds_read_b128 v[124:127], v152
	ds_read_b128 v[128:131], v152 offset:64
	ds_read_b128 v[132:135], v152 offset:128
	ds_read_b128 v[136:139], v152 offset:192
	ds_read_b64 v[160:161], v163
	s_waitcnt lgkmcnt(4)
	v_mfma_f32_16x16x32_bf16 v[140:143], v[100:103], v[124:127], 0
	s_waitcnt lgkmcnt(3)
	v_mfma_f32_16x16x32_bf16 v[140:143], v[104:107], v[128:131], v[140:143]
	s_waitcnt lgkmcnt(2)
	v_mfma_f32_16x16x32_bf16 v[140:143], v[108:111], v[132:135], v[140:143]
	s_waitcnt lgkmcnt(1)
	v_mfma_f32_16x16x32_bf16 v[140:143], v[112:115], v[136:139], v[140:143]
	s_nop 9
	s_waitcnt vmcnt(9) lgkmcnt(0)
	v_add_f32_e32 v182, v172, v140
	v_add_f32_e32 v183, v173, v141
	v_add_f32_e32 v184, v174, v142
	v_add_f32_e32 v185, v175, v143
	v_lshlrev_b32_e32 v186, 16, v160
	v_and_b32_e32 v187, 0xffff0000, v160
	v_lshlrev_b32_e32 v188, 16, v161
	v_and_b32_e32 v189, 0xffff0000, v161
	v_fmac_f32_e32 v182, v164, v186
	v_fmac_f32_e32 v183, v165, v187
	v_fmac_f32_e32 v184, v166, v188
	v_fmac_f32_e32 v185, v167, v189
	v_mul_f32_e32 v186, 0x3d372713, v182
	v_mul_f32_e32 v187, 0x3d372713, v183
	v_mul_f32_e32 v188, 0x3d372713, v184
	v_mul_f32_e32 v189, 0x3d372713, v185
	v_mul_f32_e32 v186, v182, v186
	v_mul_f32_e32 v187, v183, v187
	v_mul_f32_e32 v188, v184, v188
	v_mul_f32_e32 v189, v185, v189
	v_fma_f32 v186, v182, v186, v182
	v_fma_f32 v187, v183, v187, v183
	v_fma_f32 v188, v184, v188, v184
	v_fma_f32 v189, v185, v189, v185
	v_mul_f32_e32 v186, 0xbfcc422a, v186
	v_mul_f32_e32 v187, 0xbfcc422a, v187
	v_mul_f32_e32 v188, 0xbfcc422a, v188
	v_mul_f32_e32 v189, 0xbfcc422a, v189
	v_mul_f32_e32 v186, 0x3fb8aa3b, v186
	v_mul_f32_e32 v187, 0x3fb8aa3b, v187
	v_mul_f32_e32 v188, 0x3fb8aa3b, v188
	v_mul_f32_e32 v189, 0x3fb8aa3b, v189
	v_exp_f32_e32 v186, v186
	v_exp_f32_e32 v187, v187
	v_exp_f32_e32 v188, v188
	v_exp_f32_e32 v189, v189
	v_add_f32_e32 v186, 1.0, v186
	v_add_f32_e32 v187, 1.0, v187
	v_add_f32_e32 v188, 1.0, v188
	v_add_f32_e32 v189, 1.0, v189
	v_rcp_f32_e32 v186, v186
	v_rcp_f32_e32 v187, v187
	v_rcp_f32_e32 v188, v188
	v_rcp_f32_e32 v189, v189
	v_mul_f32_e32 v182, v182, v186
	v_mul_f32_e32 v183, v183, v187
	v_mul_f32_e32 v184, v184, v188
	v_mul_f32_e32 v185, v185, v189
	v_cvt_pk_bf16_f32 v148, v182, v183
	v_cvt_pk_bf16_f32 v149, v184, v185
	global_store_dwordx2 v156, v[148:149], s[12:13]
	ds_read_b128 v[124:127], v152 offset:4352
	ds_read_b128 v[128:131], v152 offset:4416
	ds_read_b128 v[132:135], v152 offset:4480
	ds_read_b128 v[136:139], v152 offset:4544
	ds_read_b64 v[160:161], v163 offset:512
	s_waitcnt lgkmcnt(4)
	v_mfma_f32_16x16x32_bf16 v[140:143], v[100:103], v[124:127], 0
	s_waitcnt lgkmcnt(3)
	v_mfma_f32_16x16x32_bf16 v[140:143], v[104:107], v[128:131], v[140:143]
	s_waitcnt lgkmcnt(2)
	v_mfma_f32_16x16x32_bf16 v[140:143], v[108:111], v[132:135], v[140:143]
	s_waitcnt lgkmcnt(1)
	v_mfma_f32_16x16x32_bf16 v[140:143], v[112:115], v[136:139], v[140:143]
	s_nop 9
	s_waitcnt vmcnt(9) lgkmcnt(0)
	v_add_f32_e32 v182, v176, v140
	v_add_f32_e32 v183, v177, v141
	v_add_f32_e32 v184, v178, v142
	v_add_f32_e32 v185, v179, v143
	v_lshlrev_b32_e32 v186, 16, v160
	v_and_b32_e32 v187, 0xffff0000, v160
	v_lshlrev_b32_e32 v188, 16, v161
	v_and_b32_e32 v189, 0xffff0000, v161
	v_fmac_f32_e32 v182, v164, v186
	v_fmac_f32_e32 v183, v165, v187
	v_fmac_f32_e32 v184, v166, v188
	v_fmac_f32_e32 v185, v167, v189
	v_mul_f32_e32 v186, 0x3d372713, v182
	v_mul_f32_e32 v187, 0x3d372713, v183
	v_mul_f32_e32 v188, 0x3d372713, v184
	v_mul_f32_e32 v189, 0x3d372713, v185
	v_mul_f32_e32 v186, v182, v186
	v_mul_f32_e32 v187, v183, v187
	v_mul_f32_e32 v188, v184, v188
	v_mul_f32_e32 v189, v185, v189
	v_fma_f32 v186, v182, v186, v182
	v_fma_f32 v187, v183, v187, v183
	v_fma_f32 v188, v184, v188, v184
	v_fma_f32 v189, v185, v189, v185
	v_mul_f32_e32 v186, 0xbfcc422a, v186
	v_mul_f32_e32 v187, 0xbfcc422a, v187
	v_mul_f32_e32 v188, 0xbfcc422a, v188
	v_mul_f32_e32 v189, 0xbfcc422a, v189
	v_mul_f32_e32 v186, 0x3fb8aa3b, v186
	v_mul_f32_e32 v187, 0x3fb8aa3b, v187
	v_mul_f32_e32 v188, 0x3fb8aa3b, v188
	v_mul_f32_e32 v189, 0x3fb8aa3b, v189
	v_exp_f32_e32 v186, v186
	v_exp_f32_e32 v187, v187
	v_exp_f32_e32 v188, v188
	v_exp_f32_e32 v189, v189
	v_add_f32_e32 v186, 1.0, v186
	v_add_f32_e32 v187, 1.0, v187
	v_add_f32_e32 v188, 1.0, v188
	v_add_f32_e32 v189, 1.0, v189
	v_rcp_f32_e32 v186, v186
	v_rcp_f32_e32 v187, v187
	v_rcp_f32_e32 v188, v188
	v_rcp_f32_e32 v189, v189
	v_mul_f32_e32 v182, v182, v186
	v_mul_f32_e32 v183, v183, v187
	v_mul_f32_e32 v184, v184, v188
	v_mul_f32_e32 v185, v185, v189
	v_cvt_pk_bf16_f32 v148, v182, v183
	v_cvt_pk_bf16_f32 v149, v184, v185
	global_store_dwordx2 v159, v[148:149], s[12:13]
	s_add_u32 s12, s12, 65536
	s_addc_u32 s13, s13, 0
	s_add_u32 s14, s14, 2
	s_cmp_lt_u32 s14, 32
	s_cbranch_scc1 .Lssm_tileB_d0m0
	s_waitcnt vmcnt(0) lgkmcnt(0)
	s_branch .Lssm_lat_join
.Lssm_lat_bwd:
	s_add_u32 s28, s24, 64
	s_lshl_b32 s29, s28, 13
	s_add_u32 s29, s29, 0x200000
	s_add_u32 s10, s62, s29
	s_addc_u32 s11, s63, 0
	global_load_dwordx4 v[84:87], v177, s[10:11]
	global_load_dwordx4 v[88:91], v177, s[10:11] offset:2048
	s_add_u32 s12, s10, 0x1000
	s_addc_u32 s13, s11, 0
	global_load_dwordx4 v[92:95], v177, s[12:13]
	global_load_dwordx4 v[96:99], v177, s[12:13] offset:2048
	s_lshl_b32 s29, s28, 12
	s_add_u32 s29, s29, 0x300000
	s_add_u32 s16, s62, s29
	s_addc_u32 s17, s63, 0
	global_load_dwordx2 v[20:21], v178, s[16:17]
	global_load_dwordx2 v[22:23], v178, s[16:17] offset:1024
	global_load_dwordx2 v[24:25], v178, s[16:17] offset:512
	global_load_dwordx2 v[26:27], v178, s[16:17] offset:1536
	global_load_dwordx2 v[28:29], v178, s[16:17] offset:2048
	global_load_dwordx2 v[30:31], v178, s[16:17] offset:3072
	global_load_dwordx2 v[32:33], v178, s[16:17] offset:2560
	global_load_dwordx2 v[34:35], v178, s[16:17] offset:3584
	s_lshl_b32 s29, s28, 9
	s_add_u32 s29, s29, 0x100000
	s_add_u32 s18, s62, s29
	s_addc_u32 s19, s63, 0
	global_load_dwordx2 v[116:117], v179, s[18:19]
	global_load_dwordx2 v[118:119], v179, s[18:19] offset:128
	s_lshl_b32 s30, s23, 1
	s_add_u32 s30, s30, 1
	s_lshl_b32 s30, s30, 15
	s_lshl_b32 s31, s24, 8
	s_add_u32 s30, s30, s31
	v_readlane_b32 s34, v254, 10
	v_readlane_b32 s35, v254, 11
	s_nop 3
	s_add_u32 s34, s34, s30
	s_addc_u32 s35, s35, 0
	global_load_dword v120, v180, s[34:35]
	global_load_dword v121, v180, s[34:35] offset:64
	v_readlane_b32 s34, v254, 28
	v_readlane_b32 s35, v254, 29
	s_nop 3
	s_lshl_b32 s31, s24, 6
	s_add_u32 s34, s34, s31
	s_addc_u32 s35, s35, 0
	global_load_dwordx4 v[164:167], v181, s[34:35]
	s_lshl_b32 s31, s25, 5
	s_lshl_b32 s29, s24, 19
	s_add_u32 s31, s31, s29
	s_add_u32 s31, s31, 0x16800000
	s_add_u32 s4, s62, s31
	s_addc_u32 s5, s63, 0
	s_lshl_b32 s31, s22, 1
	s_add_u32 s31, s31, 1
	s_lshl_b32 s31, s31, 15
	s_add_u32 s31, s31, 0x4800000
	s_add_u32 s6, s62, s31
	s_addc_u32 s7, s63, 0
	s_add_u32 s34, s4, 31744
	s_addc_u32 s35, s5, 0
	global_load_dwordx4 v[80:83], v150, s[34:35]
	global_load_dwordx4 v[194:197], v193, s[34:35]
	s_mov_b64 s[10:11], s[34:35]
	s_sub_u32 s10, s10, 1024
	s_subb_u32 s11, s11, 0
	global_load_dwordx4 v[144:147], v150, s[10:11]
	global_load_dwordx4 v[168:171], v193, s[10:11]
	s_mov_b64 s[34:35], s[10:11]
	s_sub_u32 s10, s10, 1024
	s_subb_u32 s11, s11, 0
	s_add_u32 s12, s6, 30720
	s_addc_u32 s13, s7, 0
	s_mov_b32 s14, 0
	s_mov_b32 s40, 0xffff0000
	s_waitcnt vmcnt(0)
	v_and_b32_e32 v182, 0xffff, v20
	v_lshrrev_b32_e32 v183, 16, v20
	v_and_b32_e32 v184, 0xffff, v21
	v_lshrrev_b32_e32 v185, 16, v21
	v_lshl_or_b32 v100, v22, 16, v182
	v_and_or_b32 v101, v22, s40, v183
	v_lshl_or_b32 v102, v23, 16, v184
	v_and_or_b32 v103, v23, s40, v185
	v_and_b32_e32 v182, 0xffff, v24
	v_lshrrev_b32_e32 v183, 16, v24
	v_and_b32_e32 v184, 0xffff, v25
	v_lshrrev_b32_e32 v185, 16, v25
	v_lshl_or_b32 v104, v26, 16, v182
	v_and_or_b32 v105, v26, s40, v183
	v_lshl_or_b32 v106, v27, 16, v184
	v_and_or_b32 v107, v27, s40, v185
	v_and_b32_e32 v182, 0xffff, v28
	v_lshrrev_b32_e32 v183, 16, v28
	v_and_b32_e32 v184, 0xffff, v29
	v_lshrrev_b32_e32 v185, 16, v29
	v_lshl_or_b32 v108, v30, 16, v182
	v_and_or_b32 v109, v30, s40, v183
	v_lshl_or_b32 v110, v31, 16, v184
	v_and_or_b32 v111, v31, s40, v185
	v_and_b32_e32 v182, 0xffff, v32
	v_lshrrev_b32_e32 v183, 16, v32
	v_and_b32_e32 v184, 0xffff, v33
	v_lshrrev_b32_e32 v185, 16, v33
	v_lshl_or_b32 v112, v34, 16, v182
	v_and_or_b32 v113, v34, s40, v183
	v_lshl_or_b32 v114, v35, 16, v184
	v_and_or_b32 v115, v35, s40, v185
	v_cmp_eq_u32_e32 vcc, 1, v174
	v_xor_b32_e32 v182, 0x80000000, v117
	v_xor_b32_e32 v183, 0x80000000, v119
	s_nop 1
	v_cndmask_b32_e32 v122, v182, v117, vcc
	v_cndmask_b32_e32 v123, v183, v119, vcc
.Lssm_tileA_d1m0:
	s_waitcnt vmcnt(6)
	v_cndmask_b32_e64 v124, 0, v80, s[66:67]
	v_cndmask_b32_e64 v125, 0, v81, s[66:67]
	v_cndmask_b32_e64 v126, 0, v82, s[66:67]
	v_cndmask_b32_e64 v127, 0, v83, s[66:67]
	v_cndmask_b32_e64 v132, 0, v194, s[66:67]
	v_cndmask_b32_e64 v133, 0, v195, s[66:67]
	v_cndmask_b32_e64 v134, 0, v196, s[66:67]
	v_cndmask_b32_e64 v135, 0, v197, s[66:67]
	v_mfma_f32_32x32x16_bf16 v[16:31], v[124:127], v[84:87], 0
	v_cndmask_b32_e64 v128, 0, v194, s[68:69]
	v_cndmask_b32_e64 v129, 0, v195, s[68:69]
	v_cndmask_b32_e64 v130, 0, v196, s[68:69]
	v_cndmask_b32_e64 v131, 0, v197, s[68:69]
	v_mfma_f32_32x32x16_bf16 v[32:47], v[124:127], v[88:91], 0
	v_cndmask_b32_e64 v136, 0, v80, s[68:69]
	v_cndmask_b32_e64 v137, 0, v81, s[68:69]
	v_cndmask_b32_e64 v138, 0, v82, s[68:69]
	v_cndmask_b32_e64 v139, 0, v83, s[68:69]
	v_mfma_f32_32x32x16_bf16 v[48:63], v[132:135], v[84:87], 0
	v_mfma_f32_32x32x16_bf16 v[64:79], v[132:135], v[88:91], 0
	v_mfma_f32_32x32x16_bf16 v[16:31], v[128:131], v[92:95], v[16:31]
	v_mfma_f32_32x32x16_bf16 v[32:47], v[128:131], v[96:99], v[32:47]
	v_mfma_f32_32x32x16_bf16 v[48:63], v[136:139], v[92:95], v[48:63]
	v_mfma_f32_32x32x16_bf16 v[64:79], v[136:139], v[96:99], v[64:79]
	s_nop 11
	global_load_dwordx4 v[80:83], v150, s[10:11]
	global_load_dwordx4 v[194:197], v193, s[10:11]
	s_sub_u32 s34, s34, 1024
	s_subb_u32 s35, s35, 0
	s_sub_u32 s10, s10, 1024
	s_subb_u32 s11, s11, 0
	v_fmac_f32_e32 v63, v116, v120
	v_fmac_f32_e32 v79, v118, v121
	v_fmac_f32_dpp v63, v120, v122 quad_perm:[1,0,3,2] row_mask:0xf bank_mask:0xf
	v_fmac_f32_dpp v79, v121, v123 quad_perm:[1,0,3,2] row_mask:0xf bank_mask:0xf
	v_cvt_pk_bf16_f32 v148, v63, v79
	ds_write_b32 v151, v148 offset:8432
	v_fmac_f32_e32 v62, v116, v63
	v_fmac_f32_e32 v78, v118, v79
	v_fmac_f32_dpp v62, v63, v122 quad_perm:[1,0,3,2] row_mask:0xf bank_mask:0xf
	v_fmac_f32_dpp v78, v79, v123 quad_perm:[1,0,3,2] row_mask:0xf bank_mask:0xf
	v_cvt_pk_bf16_f32 v149, v62, v78
	ds_write_b32 v151, v149 offset:8160
	v_fmac_f32_e32 v61, v116, v62
	v_fmac_f32_e32 v77, v118, v78
	v_fmac_f32_dpp v61, v62, v122 quad_perm:[1,0,3,2] row_mask:0xf bank_mask:0xf
	v_fmac_f32_dpp v77, v78, v123 quad_perm:[1,0,3,2] row_mask:0xf bank_mask:0xf
	v_cvt_pk_bf16_f32 v148, v61, v77
	ds_write_b32 v151, v148 offset:7888
	v_fmac_f32_e32 v60, v116, v61
	v_fmac_f32_e32 v76, v118, v77
	v_fmac_f32_dpp v60, v61, v122 quad_perm:[1,0,3,2] row_mask:0xf bank_mask:0xf
	v_fmac_f32_dpp v76, v77, v123 quad_perm:[1,0,3,2] row_mask:0xf bank_mask:0xf
	v_cvt_pk_bf16_f32 v149, v60, v76
	ds_write_b32 v151, v149 offset:7616
	v_fmac_f32_e32 v31, v116, v60
	v_fmac_f32_e32 v47, v118, v76
	v_fmac_f32_dpp v31, v60, v122 quad_perm:[1,0,3,2] row_mask:0xf bank_mask:0xf
	v_fmac_f32_dpp v47, v76, v123 quad_perm:[1,0,3,2] row_mask:0xf bank_mask:0xf
	v_cvt_pk_bf16_f32 v148, v31, v47
	ds_write_b32 v151, v148 offset:7344
	v_fmac_f32_e32 v30, v116, v31
	v_fmac_f32_e32 v46, v118, v47
	v_fmac_f32_dpp v30, v31, v122 quad_perm:[1,0,3,2] row_mask:0xf bank_mask:0xf
	v_fmac_f32_dpp v46, v47, v123 quad_perm:[1,0,3,2] row_mask:0xf bank_mask:0xf
	v_cvt_pk_bf16_f32 v149, v30, v46
	ds_write_b32 v151, v149 offset:7072
	v_fmac_f32_e32 v29, v116, v30
	v_fmac_f32_e32 v45, v118, v46
	v_fmac_f32_dpp v29, v30, v122 quad_perm:[1,0,3,2] row_mask:0xf bank_mask:0xf
	v_fmac_f32_dpp v45, v46, v123 quad_perm:[1,0,3,2] row_mask:0xf bank_mask:0xf
	v_cvt_pk_bf16_f32 v148, v29, v45
	ds_write_b32 v151, v148 offset:6800
	v_fmac_f32_e32 v28, v116, v29
	v_fmac_f32_e32 v44, v118, v45
	v_fmac_f32_dpp v28, v29, v122 quad_perm:[1,0,3,2] row_mask:0xf bank_mask:0xf
	v_fmac_f32_dpp v44, v45, v123 quad_perm:[1,0,3,2] row_mask:0xf bank_mask:0xf
	v_cvt_pk_bf16_f32 v149, v28, v44
	ds_write_b32 v151, v149 offset:6528
	v_fmac_f32_e32 v59, v116, v28
	v_fmac_f32_e32 v75, v118, v44
	v_fmac_f32_dpp v59, v28, v122 quad_perm:[1,0,3,2] row_mask:0xf bank_mask:0xf
	v_fmac_f32_dpp v75, v44, v123 quad_perm:[1,0,3,2] row_mask:0xf bank_mask:0xf
	v_cvt_pk_bf16_f32 v148, v59, v75
	ds_write_b32 v151, v148 offset:6256
	v_fmac_f32_e32 v58, v116, v59
	v_fmac_f32_e32 v74, v118, v75
	v_fmac_f32_dpp v58, v59, v122 quad_perm:[1,0,3,2] row_mask:0xf bank_mask:0xf
	v_fmac_f32_dpp v74, v75, v123 quad_perm:[1,0,3,2] row_mask:0xf bank_mask:0xf
	v_cvt_pk_bf16_f32 v149, v58, v74
	ds_write_b32 v151, v149 offset:5984
	v_fmac_f32_e32 v57, v116, v58
	v_fmac_f32_e32 v73, v118, v74
	v_fmac_f32_dpp v57, v58, v122 quad_perm:[1,0,3,2] row_mask:0xf bank_mask:0xf
	v_fmac_f32_dpp v73, v74, v123 quad_perm:[1,0,3,2] row_mask:0xf bank_mask:0xf
	v_cvt_pk_bf16_f32 v148, v57, v73
	ds_write_b32 v151, v148 offset:5712
	v_fmac_f32_e32 v56, v116, v57
	v_fmac_f32_e32 v72, v118, v73
	v_fmac_f32_dpp v56, v57, v122 quad_perm:[1,0,3,2] row_mask:0xf bank_mask:0xf
	v_fmac_f32_dpp v72, v73, v123 quad_perm:[1,0,3,2] row_mask:0xf bank_mask:0xf
	v_cvt_pk_bf16_f32 v149, v56, v72
	ds_write_b32 v151, v149 offset:5440
	v_fmac_f32_e32 v27, v116, v56
	v_fmac_f32_e32 v43, v118, v72
	v_fmac_f32_dpp v27, v56, v122 quad_perm:[1,0,3,2] row_mask:0xf bank_mask:0xf
	v_fmac_f32_dpp v43, v72, v123 quad_perm:[1,0,3,2] row_mask:0xf bank_mask:0xf
	v_cvt_pk_bf16_f32 v148, v27, v43
	ds_write_b32 v151, v148 offset:5168
	v_fmac_f32_e32 v26, v116, v27
	v_fmac_f32_e32 v42, v118, v43
	v_fmac_f32_dpp v26, v27, v122 quad_perm:[1,0,3,2] row_mask:0xf bank_mask:0xf
	v_fmac_f32_dpp v42, v43, v123 quad_perm:[1,0,3,2] row_mask:0xf bank_mask:0xf
	v_cvt_pk_bf16_f32 v149, v26, v42
	ds_write_b32 v151, v149 offset:4896
	v_fmac_f32_e32 v25, v116, v26
	v_fmac_f32_e32 v41, v118, v42
	v_fmac_f32_dpp v25, v26, v122 quad_perm:[1,0,3,2] row_mask:0xf bank_mask:0xf
	v_fmac_f32_dpp v41, v42, v123 quad_perm:[1,0,3,2] row_mask:0xf bank_mask:0xf
	v_cvt_pk_bf16_f32 v148, v25, v41
	ds_write_b32 v151, v148 offset:4624
	v_fmac_f32_e32 v24, v116, v25
	v_fmac_f32_e32 v40, v118, v41
	v_fmac_f32_dpp v24, v25, v122 quad_perm:[1,0,3,2] row_mask:0xf bank_mask:0xf
	v_fmac_f32_dpp v40, v41, v123 quad_perm:[1,0,3,2] row_mask:0xf bank_mask:0xf
	v_cvt_pk_bf16_f32 v149, v24, v40
	ds_write_b32 v151, v149 offset:4352
	v_fmac_f32_e32 v55, v116, v24
	v_fmac_f32_e32 v71, v118, v40
	v_fmac_f32_dpp v55, v24, v122 quad_perm:[1,0,3,2] row_mask:0xf bank_mask:0xf
	v_fmac_f32_dpp v71, v40, v123 quad_perm:[1,0,3,2] row_mask:0xf bank_mask:0xf
	v_cvt_pk_bf16_f32 v148, v55, v71
	ds_write_b32 v151, v148 offset:4080
	v_fmac_f32_e32 v54, v116, v55
	v_fmac_f32_e32 v70, v118, v71
	v_fmac_f32_dpp v54, v55, v122 quad_perm:[1,0,3,2] row_mask:0xf bank_mask:0xf
	v_fmac_f32_dpp v70, v71, v123 quad_perm:[1,0,3,2] row_mask:0xf bank_mask:0xf
	v_cvt_pk_bf16_f32 v149, v54, v70
	ds_write_b32 v151, v149 offset:3808
	v_fmac_f32_e32 v53, v116, v54
	v_fmac_f32_e32 v69, v118, v70
	v_fmac_f32_dpp v53, v54, v122 quad_perm:[1,0,3,2] row_mask:0xf bank_mask:0xf
	v_fmac_f32_dpp v69, v70, v123 quad_perm:[1,0,3,2] row_mask:0xf bank_mask:0xf
	v_cvt_pk_bf16_f32 v148, v53, v69
	ds_write_b32 v151, v148 offset:3536
	v_fmac_f32_e32 v52, v116, v53
	v_fmac_f32_e32 v68, v118, v69
	v_fmac_f32_dpp v52, v53, v122 quad_perm:[1,0,3,2] row_mask:0xf bank_mask:0xf
	v_fmac_f32_dpp v68, v69, v123 quad_perm:[1,0,3,2] row_mask:0xf bank_mask:0xf
	v_cvt_pk_bf16_f32 v149, v52, v68
	ds_write_b32 v151, v149 offset:3264
	v_fmac_f32_e32 v23, v116, v52
	v_fmac_f32_e32 v39, v118, v68
	v_fmac_f32_dpp v23, v52, v122 quad_perm:[1,0,3,2] row_mask:0xf bank_mask:0xf
	v_fmac_f32_dpp v39, v68, v123 quad_perm:[1,0,3,2] row_mask:0xf bank_mask:0xf
	v_cvt_pk_bf16_f32 v148, v23, v39
	ds_write_b32 v151, v148 offset:2992
	v_fmac_f32_e32 v22, v116, v23
	v_fmac_f32_e32 v38, v118, v39
	v_fmac_f32_dpp v22, v23, v122 quad_perm:[1,0,3,2] row_mask:0xf bank_mask:0xf
	v_fmac_f32_dpp v38, v39, v123 quad_perm:[1,0,3,2] row_mask:0xf bank_mask:0xf
	v_cvt_pk_bf16_f32 v149, v22, v38
	ds_write_b32 v151, v149 offset:2720
	v_fmac_f32_e32 v21, v116, v22
	v_fmac_f32_e32 v37, v118, v38
	v_fmac_f32_dpp v21, v22, v122 quad_perm:[1,0,3,2] row_mask:0xf bank_mask:0xf
	v_fmac_f32_dpp v37, v38, v123 quad_perm:[1,0,3,2] row_mask:0xf bank_mask:0xf
	v_cvt_pk_bf16_f32 v148, v21, v37
	ds_write_b32 v151, v148 offset:2448
	v_fmac_f32_e32 v20, v116, v21
	v_fmac_f32_e32 v36, v118, v37
	v_fmac_f32_dpp v20, v21, v122 quad_perm:[1,0,3,2] row_mask:0xf bank_mask:0xf
	v_fmac_f32_dpp v36, v37, v123 quad_perm:[1,0,3,2] row_mask:0xf bank_mask:0xf
	v_cvt_pk_bf16_f32 v149, v20, v36
	ds_write_b32 v151, v149 offset:2176
	v_fmac_f32_e32 v51, v116, v20
	v_fmac_f32_e32 v67, v118, v36
	v_fmac_f32_dpp v51, v20, v122 quad_perm:[1,0,3,2] row_mask:0xf bank_mask:0xf
	v_fmac_f32_dpp v67, v36, v123 quad_perm:[1,0,3,2] row_mask:0xf bank_mask:0xf
	v_cvt_pk_bf16_f32 v148, v51, v67
	ds_write_b32 v151, v148 offset:1904
	v_fmac_f32_e32 v50, v116, v51
	v_fmac_f32_e32 v66, v118, v67
	v_fmac_f32_dpp v50, v51, v122 quad_perm:[1,0,3,2] row_mask:0xf bank_mask:0xf
	v_fmac_f32_dpp v66, v67, v123 quad_perm:[1,0,3,2] row_mask:0xf bank_mask:0xf
	v_cvt_pk_bf16_f32 v149, v50, v66
	ds_write_b32 v151, v149 offset:1632
	v_fmac_f32_e32 v49, v116, v50
	v_fmac_f32_e32 v65, v118, v66
	v_fmac_f32_dpp v49, v50, v122 quad_perm:[1,0,3,2] row_mask:0xf bank_mask:0xf
	v_fmac_f32_dpp v65, v66, v123 quad_perm:[1,0,3,2] row_mask:0xf bank_mask:0xf
	v_cvt_pk_bf16_f32 v148, v49, v65
	ds_write_b32 v151, v148 offset:1360
	v_fmac_f32_e32 v48, v116, v49
	v_fmac_f32_e32 v64, v118, v65
	v_fmac_f32_dpp v48, v49, v122 quad_perm:[1,0,3,2] row_mask:0xf bank_mask:0xf
	v_fmac_f32_dpp v64, v65, v123 quad_perm:[1,0,3,2] row_mask:0xf bank_mask:0xf
	v_cvt_pk_bf16_f32 v149, v48, v64
	ds_write_b32 v151, v149 offset:1088
	v_fmac_f32_e32 v19, v116, v48
	v_fmac_f32_e32 v35, v118, v64
	v_fmac_f32_dpp v19, v48, v122 quad_perm:[1,0,3,2] row_mask:0xf bank_mask:0xf
	v_fmac_f32_dpp v35, v64, v123 quad_perm:[1,0,3,2] row_mask:0xf bank_mask:0xf
	v_cvt_pk_bf16_f32 v148, v19, v35
	ds_write_b32 v151, v148 offset:816
	v_fmac_f32_e32 v18, v116, v19
	v_fmac_f32_e32 v34, v118, v35
	v_fmac_f32_dpp v18, v19, v122 quad_perm:[1,0,3,2] row_mask:0xf bank_mask:0xf
	v_fmac_f32_dpp v34, v35, v123 quad_perm:[1,0,3,2] row_mask:0xf bank_mask:0xf
	v_cvt_pk_bf16_f32 v149, v18, v34
	ds_write_b32 v151, v149 offset:544
	v_fmac_f32_e32 v17, v116, v18
	v_fmac_f32_e32 v33, v118, v34
	v_fmac_f32_dpp v17, v18, v122 quad_perm:[1,0,3,2] row_mask:0xf bank_mask:0xf
	v_fmac_f32_dpp v33, v34, v123 quad_perm:[1,0,3,2] row_mask:0xf bank_mask:0xf
	v_cvt_pk_bf16_f32 v148, v17, v33
	ds_write_b32 v151, v148 offset:272
	v_fmac_f32_e32 v16, v116, v17
	v_fmac_f32_e32 v32, v118, v33
	v_fmac_f32_dpp v16, v17, v122 quad_perm:[1,0,3,2] row_mask:0xf bank_mask:0xf
	v_fmac_f32_dpp v32, v33, v123 quad_perm:[1,0,3,2] row_mask:0xf bank_mask:0xf
	v_cvt_pk_bf16_f32 v149, v16, v32
	ds_write_b32 v151, v149
	v_mov_b32_e32 v120, v16
	v_mov_b32_e32 v121, v32
	ds_read_b128 v[124:127], v152
	ds_read_b128 v[128:131], v152 offset:64
	ds_read_b128 v[132:135], v152 offset:128
	ds_read_b128 v[136:139], v152 offset:192
	s_waitcnt lgkmcnt(3)
	v_mfma_f32_16x16x32_bf16 v[140:143], v[100:103], v[124:127], 0
	s_waitcnt lgkmcnt(2)
	v_mfma_f32_16x16x32_bf16 v[140:143], v[104:107], v[128:131], v[140:143]
	s_waitcnt lgkmcnt(1)
	v_mfma_f32_16x16x32_bf16 v[140:143], v[108:111], v[132:135], v[140:143]
	s_waitcnt lgkmcnt(0)
	v_mfma_f32_16x16x32_bf16 v[140:143], v[112:115], v[136:139], v[140:143]
	s_nop 9
	global_store_dwordx4 v153, v[140:143], s[12:13]
	s_nop 1
	ds_read_b128 v[124:127], v152 offset:4352
	ds_read_b128 v[128:131], v152 offset:4416
	ds_read_b128 v[132:135], v152 offset:4480
	ds_read_b128 v[136:139], v152 offset:4544
	s_waitcnt lgkmcnt(3)
	v_mfma_f32_16x16x32_bf16 v[140:143], v[100:103], v[124:127], 0
	s_waitcnt lgkmcnt(2)
	v_mfma_f32_16x16x32_bf16 v[140:143], v[104:107], v[128:131], v[140:143]
	s_waitcnt lgkmcnt(1)
	v_mfma_f32_16x16x32_bf16 v[140:143], v[108:111], v[132:135], v[140:143]
	s_waitcnt lgkmcnt(0)
	v_mfma_f32_16x16x32_bf16 v[140:143], v[112:115], v[136:139], v[140:143]
	s_nop 9
	global_store_dwordx4 v157, v[140:143], s[12:13]
	s_nop 1
	s_sub_u32 s12, s12, 2048
	s_subb_u32 s13, s13, 0
	s_waitcnt vmcnt(6)
	v_cndmask_b32_e64 v124, 0, v144, s[66:67]
	v_cndmask_b32_e64 v125, 0, v145, s[66:67]
	v_cndmask_b32_e64 v126, 0, v146, s[66:67]
	v_cndmask_b32_e64 v127, 0, v147, s[66:67]
	v_cndmask_b32_e64 v132, 0, v168, s[66:67]
	v_cndmask_b32_e64 v133, 0, v169, s[66:67]
	v_cndmask_b32_e64 v134, 0, v170, s[66:67]
	v_cndmask_b32_e64 v135, 0, v171, s[66:67]
	v_mfma_f32_32x32x16_bf16 v[16:31], v[124:127], v[84:87], 0
	v_cndmask_b32_e64 v128, 0, v168, s[68:69]
	v_cndmask_b32_e64 v129, 0, v169, s[68:69]
	v_cndmask_b32_e64 v130, 0, v170, s[68:69]
	v_cndmask_b32_e64 v131, 0, v171, s[68:69]
	v_mfma_f32_32x32x16_bf16 v[32:47], v[124:127], v[88:91], 0
	v_cndmask_b32_e64 v136, 0, v144, s[68:69]
	v_cndmask_b32_e64 v137, 0, v145, s[68:69]
	v_cndmask_b32_e64 v138, 0, v146, s[68:69]
	v_cndmask_b32_e64 v139, 0, v147, s[68:69]
	v_mfma_f32_32x32x16_bf16 v[48:63], v[132:135], v[84:87], 0
	v_mfma_f32_32x32x16_bf16 v[64:79], v[132:135], v[88:91], 0
	v_mfma_f32_32x32x16_bf16 v[16:31], v[128:131], v[92:95], v[16:31]
	v_mfma_f32_32x32x16_bf16 v[32:47], v[128:131], v[96:99], v[32:47]
	v_mfma_f32_32x32x16_bf16 v[48:63], v[136:139], v[92:95], v[48:63]
	v_mfma_f32_32x32x16_bf16 v[64:79], v[136:139], v[96:99], v[64:79]
	s_nop 11
	global_load_dwordx4 v[144:147], v150, s[10:11]
	global_load_dwordx4 v[168:171], v193, s[10:11]
	s_sub_u32 s34, s34, 1024
	s_subb_u32 s35, s35, 0
	s_sub_u32 s10, s10, 1024
	s_subb_u32 s11, s11, 0
	v_fmac_f32_e32 v63, v116, v120
	v_fmac_f32_e32 v79, v118, v121
	v_fmac_f32_dpp v63, v120, v122 quad_perm:[1,0,3,2] row_mask:0xf bank_mask:0xf
	v_fmac_f32_dpp v79, v121, v123 quad_perm:[1,0,3,2] row_mask:0xf bank_mask:0xf
	v_cvt_pk_bf16_f32 v148, v63, v79
	ds_write_b32 v151, v148 offset:8432
	v_fmac_f32_e32 v62, v116, v63
	v_fmac_f32_e32 v78, v118, v79
	v_fmac_f32_dpp v62, v63, v122 quad_perm:[1,0,3,2] row_mask:0xf bank_mask:0xf
	v_fmac_f32_dpp v78, v79, v123 quad_perm:[1,0,3,2] row_mask:0xf bank_mask:0xf
	v_cvt_pk_bf16_f32 v149, v62, v78
	ds_write_b32 v151, v149 offset:8160
	v_fmac_f32_e32 v61, v116, v62
	v_fmac_f32_e32 v77, v118, v78
	v_fmac_f32_dpp v61, v62, v122 quad_perm:[1,0,3,2] row_mask:0xf bank_mask:0xf
	v_fmac_f32_dpp v77, v78, v123 quad_perm:[1,0,3,2] row_mask:0xf bank_mask:0xf
	v_cvt_pk_bf16_f32 v148, v61, v77
	ds_write_b32 v151, v148 offset:7888
	v_fmac_f32_e32 v60, v116, v61
	v_fmac_f32_e32 v76, v118, v77
	v_fmac_f32_dpp v60, v61, v122 quad_perm:[1,0,3,2] row_mask:0xf bank_mask:0xf
	v_fmac_f32_dpp v76, v77, v123 quad_perm:[1,0,3,2] row_mask:0xf bank_mask:0xf
	v_cvt_pk_bf16_f32 v149, v60, v76
	ds_write_b32 v151, v149 offset:7616
	v_fmac_f32_e32 v31, v116, v60
	v_fmac_f32_e32 v47, v118, v76
	v_fmac_f32_dpp v31, v60, v122 quad_perm:[1,0,3,2] row_mask:0xf bank_mask:0xf
	v_fmac_f32_dpp v47, v76, v123 quad_perm:[1,0,3,2] row_mask:0xf bank_mask:0xf
	v_cvt_pk_bf16_f32 v148, v31, v47
	ds_write_b32 v151, v148 offset:7344
	v_fmac_f32_e32 v30, v116, v31
	v_fmac_f32_e32 v46, v118, v47
	v_fmac_f32_dpp v30, v31, v122 quad_perm:[1,0,3,2] row_mask:0xf bank_mask:0xf
	v_fmac_f32_dpp v46, v47, v123 quad_perm:[1,0,3,2] row_mask:0xf bank_mask:0xf
	v_cvt_pk_bf16_f32 v149, v30, v46
	ds_write_b32 v151, v149 offset:7072
	v_fmac_f32_e32 v29, v116, v30
	v_fmac_f32_e32 v45, v118, v46
	v_fmac_f32_dpp v29, v30, v122 quad_perm:[1,0,3,2] row_mask:0xf bank_mask:0xf
	v_fmac_f32_dpp v45, v46, v123 quad_perm:[1,0,3,2] row_mask:0xf bank_mask:0xf
	v_cvt_pk_bf16_f32 v148, v29, v45
	ds_write_b32 v151, v148 offset:6800
	v_fmac_f32_e32 v28, v116, v29
	v_fmac_f32_e32 v44, v118, v45
	v_fmac_f32_dpp v28, v29, v122 quad_perm:[1,0,3,2] row_mask:0xf bank_mask:0xf
	v_fmac_f32_dpp v44, v45, v123 quad_perm:[1,0,3,2] row_mask:0xf bank_mask:0xf
	v_cvt_pk_bf16_f32 v149, v28, v44
	ds_write_b32 v151, v149 offset:6528
	v_fmac_f32_e32 v59, v116, v28
	v_fmac_f32_e32 v75, v118, v44
	v_fmac_f32_dpp v59, v28, v122 quad_perm:[1,0,3,2] row_mask:0xf bank_mask:0xf
	v_fmac_f32_dpp v75, v44, v123 quad_perm:[1,0,3,2] row_mask:0xf bank_mask:0xf
	v_cvt_pk_bf16_f32 v148, v59, v75
	ds_write_b32 v151, v148 offset:6256
	v_fmac_f32_e32 v58, v116, v59
	v_fmac_f32_e32 v74, v118, v75
	v_fmac_f32_dpp v58, v59, v122 quad_perm:[1,0,3,2] row_mask:0xf bank_mask:0xf
	v_fmac_f32_dpp v74, v75, v123 quad_perm:[1,0,3,2] row_mask:0xf bank_mask:0xf
	v_cvt_pk_bf16_f32 v149, v58, v74
	ds_write_b32 v151, v149 offset:5984
	v_fmac_f32_e32 v57, v116, v58
	v_fmac_f32_e32 v73, v118, v74
	v_fmac_f32_dpp v57, v58, v122 quad_perm:[1,0,3,2] row_mask:0xf bank_mask:0xf
	v_fmac_f32_dpp v73, v74, v123 quad_perm:[1,0,3,2] row_mask:0xf bank_mask:0xf
	v_cvt_pk_bf16_f32 v148, v57, v73
	ds_write_b32 v151, v148 offset:5712
	v_fmac_f32_e32 v56, v116, v57
	v_fmac_f32_e32 v72, v118, v73
	v_fmac_f32_dpp v56, v57, v122 quad_perm:[1,0,3,2] row_mask:0xf bank_mask:0xf
	v_fmac_f32_dpp v72, v73, v123 quad_perm:[1,0,3,2] row_mask:0xf bank_mask:0xf
	v_cvt_pk_bf16_f32 v149, v56, v72
	ds_write_b32 v151, v149 offset:5440
	v_fmac_f32_e32 v27, v116, v56
	v_fmac_f32_e32 v43, v118, v72
	v_fmac_f32_dpp v27, v56, v122 quad_perm:[1,0,3,2] row_mask:0xf bank_mask:0xf
	v_fmac_f32_dpp v43, v72, v123 quad_perm:[1,0,3,2] row_mask:0xf bank_mask:0xf
	v_cvt_pk_bf16_f32 v148, v27, v43
	ds_write_b32 v151, v148 offset:5168
	v_fmac_f32_e32 v26, v116, v27
	v_fmac_f32_e32 v42, v118, v43
	v_fmac_f32_dpp v26, v27, v122 quad_perm:[1,0,3,2] row_mask:0xf bank_mask:0xf
	v_fmac_f32_dpp v42, v43, v123 quad_perm:[1,0,3,2] row_mask:0xf bank_mask:0xf
	v_cvt_pk_bf16_f32 v149, v26, v42
	ds_write_b32 v151, v149 offset:4896
	v_fmac_f32_e32 v25, v116, v26
	v_fmac_f32_e32 v41, v118, v42
	v_fmac_f32_dpp v25, v26, v122 quad_perm:[1,0,3,2] row_mask:0xf bank_mask:0xf
	v_fmac_f32_dpp v41, v42, v123 quad_perm:[1,0,3,2] row_mask:0xf bank_mask:0xf
	v_cvt_pk_bf16_f32 v148, v25, v41
	ds_write_b32 v151, v148 offset:4624
	v_fmac_f32_e32 v24, v116, v25
	v_fmac_f32_e32 v40, v118, v41
	v_fmac_f32_dpp v24, v25, v122 quad_perm:[1,0,3,2] row_mask:0xf bank_mask:0xf
	v_fmac_f32_dpp v40, v41, v123 quad_perm:[1,0,3,2] row_mask:0xf bank_mask:0xf
	v_cvt_pk_bf16_f32 v149, v24, v40
	ds_write_b32 v151, v149 offset:4352
	v_fmac_f32_e32 v55, v116, v24
	v_fmac_f32_e32 v71, v118, v40
	v_fmac_f32_dpp v55, v24, v122 quad_perm:[1,0,3,2] row_mask:0xf bank_mask:0xf
	v_fmac_f32_dpp v71, v40, v123 quad_perm:[1,0,3,2] row_mask:0xf bank_mask:0xf
	v_cvt_pk_bf16_f32 v148, v55, v71
	ds_write_b32 v151, v148 offset:4080
	v_fmac_f32_e32 v54, v116, v55
	v_fmac_f32_e32 v70, v118, v71
	v_fmac_f32_dpp v54, v55, v122 quad_perm:[1,0,3,2] row_mask:0xf bank_mask:0xf
	v_fmac_f32_dpp v70, v71, v123 quad_perm:[1,0,3,2] row_mask:0xf bank_mask:0xf
	v_cvt_pk_bf16_f32 v149, v54, v70
	ds_write_b32 v151, v149 offset:3808
	v_fmac_f32_e32 v53, v116, v54
	v_fmac_f32_e32 v69, v118, v70
	v_fmac_f32_dpp v53, v54, v122 quad_perm:[1,0,3,2] row_mask:0xf bank_mask:0xf
	v_fmac_f32_dpp v69, v70, v123 quad_perm:[1,0,3,2] row_mask:0xf bank_mask:0xf
	v_cvt_pk_bf16_f32 v148, v53, v69
	ds_write_b32 v151, v148 offset:3536
	v_fmac_f32_e32 v52, v116, v53
	v_fmac_f32_e32 v68, v118, v69
	v_fmac_f32_dpp v52, v53, v122 quad_perm:[1,0,3,2] row_mask:0xf bank_mask:0xf
	v_fmac_f32_dpp v68, v69, v123 quad_perm:[1,0,3,2] row_mask:0xf bank_mask:0xf
	v_cvt_pk_bf16_f32 v149, v52, v68
	ds_write_b32 v151, v149 offset:3264
	v_fmac_f32_e32 v23, v116, v52
	v_fmac_f32_e32 v39, v118, v68
	v_fmac_f32_dpp v23, v52, v122 quad_perm:[1,0,3,2] row_mask:0xf bank_mask:0xf
	v_fmac_f32_dpp v39, v68, v123 quad_perm:[1,0,3,2] row_mask:0xf bank_mask:0xf
	v_cvt_pk_bf16_f32 v148, v23, v39
	ds_write_b32 v151, v148 offset:2992
	v_fmac_f32_e32 v22, v116, v23
	v_fmac_f32_e32 v38, v118, v39
	v_fmac_f32_dpp v22, v23, v122 quad_perm:[1,0,3,2] row_mask:0xf bank_mask:0xf
	v_fmac_f32_dpp v38, v39, v123 quad_perm:[1,0,3,2] row_mask:0xf bank_mask:0xf
	v_cvt_pk_bf16_f32 v149, v22, v38
	ds_write_b32 v151, v149 offset:2720
	v_fmac_f32_e32 v21, v116, v22
	v_fmac_f32_e32 v37, v118, v38
	v_fmac_f32_dpp v21, v22, v122 quad_perm:[1,0,3,2] row_mask:0xf bank_mask:0xf
	v_fmac_f32_dpp v37, v38, v123 quad_perm:[1,0,3,2] row_mask:0xf bank_mask:0xf
	v_cvt_pk_bf16_f32 v148, v21, v37
	ds_write_b32 v151, v148 offset:2448
	v_fmac_f32_e32 v20, v116, v21
	v_fmac_f32_e32 v36, v118, v37
	v_fmac_f32_dpp v20, v21, v122 quad_perm:[1,0,3,2] row_mask:0xf bank_mask:0xf
	v_fmac_f32_dpp v36, v37, v123 quad_perm:[1,0,3,2] row_mask:0xf bank_mask:0xf
	v_cvt_pk_bf16_f32 v149, v20, v36
	ds_write_b32 v151, v149 offset:2176
	v_fmac_f32_e32 v51, v116, v20
	v_fmac_f32_e32 v67, v118, v36
	v_fmac_f32_dpp v51, v20, v122 quad_perm:[1,0,3,2] row_mask:0xf bank_mask:0xf
	v_fmac_f32_dpp v67, v36, v123 quad_perm:[1,0,3,2] row_mask:0xf bank_mask:0xf
	v_cvt_pk_bf16_f32 v148, v51, v67
	ds_write_b32 v151, v148 offset:1904
	v_fmac_f32_e32 v50, v116, v51
	v_fmac_f32_e32 v66, v118, v67
	v_fmac_f32_dpp v50, v51, v122 quad_perm:[1,0,3,2] row_mask:0xf bank_mask:0xf
	v_fmac_f32_dpp v66, v67, v123 quad_perm:[1,0,3,2] row_mask:0xf bank_mask:0xf
	v_cvt_pk_bf16_f32 v149, v50, v66
	ds_write_b32 v151, v149 offset:1632
	v_fmac_f32_e32 v49, v116, v50
	v_fmac_f32_e32 v65, v118, v66
	v_fmac_f32_dpp v49, v50, v122 quad_perm:[1,0,3,2] row_mask:0xf bank_mask:0xf
	v_fmac_f32_dpp v65, v66, v123 quad_perm:[1,0,3,2] row_mask:0xf bank_mask:0xf
	v_cvt_pk_bf16_f32 v148, v49, v65
	ds_write_b32 v151, v148 offset:1360
	v_fmac_f32_e32 v48, v116, v49
	v_fmac_f32_e32 v64, v118, v65
	v_fmac_f32_dpp v48, v49, v122 quad_perm:[1,0,3,2] row_mask:0xf bank_mask:0xf
	v_fmac_f32_dpp v64, v65, v123 quad_perm:[1,0,3,2] row_mask:0xf bank_mask:0xf
	v_cvt_pk_bf16_f32 v149, v48, v64
	ds_write_b32 v151, v149 offset:1088
	v_fmac_f32_e32 v19, v116, v48
	v_fmac_f32_e32 v35, v118, v64
	v_fmac_f32_dpp v19, v48, v122 quad_perm:[1,0,3,2] row_mask:0xf bank_mask:0xf
	v_fmac_f32_dpp v35, v64, v123 quad_perm:[1,0,3,2] row_mask:0xf bank_mask:0xf
	v_cvt_pk_bf16_f32 v148, v19, v35
	ds_write_b32 v151, v148 offset:816
	v_fmac_f32_e32 v18, v116, v19
	v_fmac_f32_e32 v34, v118, v35
	v_fmac_f32_dpp v18, v19, v122 quad_perm:[1,0,3,2] row_mask:0xf bank_mask:0xf
	v_fmac_f32_dpp v34, v35, v123 quad_perm:[1,0,3,2] row_mask:0xf bank_mask:0xf
	v_cvt_pk_bf16_f32 v149, v18, v34
	ds_write_b32 v151, v149 offset:544
	v_fmac_f32_e32 v17, v116, v18
	v_fmac_f32_e32 v33, v118, v34
	v_fmac_f32_dpp v17, v18, v122 quad_perm:[1,0,3,2] row_mask:0xf bank_mask:0xf
	v_fmac_f32_dpp v33, v34, v123 quad_perm:[1,0,3,2] row_mask:0xf bank_mask:0xf
	v_cvt_pk_bf16_f32 v148, v17, v33
	ds_write_b32 v151, v148 offset:272
	v_fmac_f32_e32 v16, v116, v17
	v_fmac_f32_e32 v32, v118, v33
	v_fmac_f32_dpp v16, v17, v122 quad_perm:[1,0,3,2] row_mask:0xf bank_mask:0xf
	v_fmac_f32_dpp v32, v33, v123 quad_perm:[1,0,3,2] row_mask:0xf bank_mask:0xf
	v_cvt_pk_bf16_f32 v149, v16, v32
	ds_write_b32 v151, v149
	v_mov_b32_e32 v120, v16
	v_mov_b32_e32 v121, v32
	ds_read_b128 v[124:127], v152
	ds_read_b128 v[128:131], v152 offset:64
	ds_read_b128 v[132:135], v152 offset:128
	ds_read_b128 v[136:139], v152 offset:192
	s_waitcnt lgkmcnt(3)
	v_mfma_f32_16x16x32_bf16 v[140:143], v[100:103], v[124:127], 0
	s_waitcnt lgkmcnt(2)
	v_mfma_f32_16x16x32_bf16 v[140:143], v[104:107], v[128:131], v[140:143]
	s_waitcnt lgkmcnt(1)
	v_mfma_f32_16x16x32_bf16 v[140:143], v[108:111], v[132:135], v[140:143]
	s_waitcnt lgkmcnt(0)
	v_mfma_f32_16x16x32_bf16 v[140:143], v[112:115], v[136:139], v[140:143]
	s_nop 9
	global_store_dwordx4 v153, v[140:143], s[12:13]
	s_nop 1
	ds_read_b128 v[124:127], v152 offset:4352
	ds_read_b128 v[128:131], v152 offset:4416
	ds_read_b128 v[132:135], v152 offset:4480
	ds_read_b128 v[136:139], v152 offset:4544
	s_waitcnt lgkmcnt(3)
	v_mfma_f32_16x16x32_bf16 v[140:143], v[100:103], v[124:127], 0
	s_waitcnt lgkmcnt(2)
	v_mfma_f32_16x16x32_bf16 v[140:143], v[104:107], v[128:131], v[140:143]
	s_waitcnt lgkmcnt(1)
	v_mfma_f32_16x16x32_bf16 v[140:143], v[108:111], v[132:135], v[140:143]
	s_waitcnt lgkmcnt(0)
	v_mfma_f32_16x16x32_bf16 v[140:143], v[112:115], v[136:139], v[140:143]
	s_nop 9
	global_store_dwordx4 v157, v[140:143], s[12:13]
	s_nop 1
	s_sub_u32 s12, s12, 2048
	s_subb_u32 s13, s13, 0
	s_add_u32 s14, s14, 2
	s_cmp_lt_u32 s14, 16
	s_cbranch_scc1 .Lssm_tileA_d1m0
	s_waitcnt vmcnt(0) lgkmcnt(0)
	s_lshr_b32 s21, s89, 1
	s_lshl_b32 s21, s21, 2
	s_add_u32 s37, s21, 0x21000
	v_mov_b32_e32 v182, s37
	v_mov_b32_e32 v183, 1
	v_cmp_eq_u32_e32 vcc, 0, v191
	s_and_saveexec_b64 s[0:1], vcc
	ds_add_u32 v182, v183
	s_mov_b64 exec, s[0:1]
	s_waitcnt lgkmcnt(0)
	s_mov_b32 s38, 0

.Lssm_tileB_d1m0:
	s_waitcnt vmcnt(8)
	v_cndmask_b32_e64 v124, 0, v80, s[66:67]
	v_cndmask_b32_e64 v125, 0, v81, s[66:67]
	v_cndmask_b32_e64 v126, 0, v82, s[66:67]
	v_cndmask_b32_e64 v127, 0, v83, s[66:67]
	v_cndmask_b32_e64 v132, 0, v194, s[66:67]
	v_cndmask_b32_e64 v133, 0, v195, s[66:67]
	v_cndmask_b32_e64 v134, 0, v196, s[66:67]
	v_cndmask_b32_e64 v135, 0, v197, s[66:67]
	v_mfma_f32_32x32x16_bf16 v[16:31], v[124:127], v[84:87], 0
	v_cndmask_b32_e64 v128, 0, v194, s[68:69]
	v_cndmask_b32_e64 v129, 0, v195, s[68:69]
	v_cndmask_b32_e64 v130, 0, v196, s[68:69]
	v_cndmask_b32_e64 v131, 0, v197, s[68:69]
	v_mfma_f32_32x32x16_bf16 v[32:47], v[124:127], v[88:91], 0
	v_cndmask_b32_e64 v136, 0, v80, s[68:69]
	v_cndmask_b32_e64 v137, 0, v81, s[68:69]
	v_cndmask_b32_e64 v138, 0, v82, s[68:69]
	v_cndmask_b32_e64 v139, 0, v83, s[68:69]
	v_mfma_f32_32x32x16_bf16 v[48:63], v[132:135], v[84:87], 0
	v_mfma_f32_32x32x16_bf16 v[64:79], v[132:135], v[88:91], 0
	v_mfma_f32_32x32x16_bf16 v[16:31], v[128:131], v[92:95], v[16:31]
	v_mfma_f32_32x32x16_bf16 v[32:47], v[128:131], v[96:99], v[32:47]
	v_mfma_f32_32x32x16_bf16 v[48:63], v[136:139], v[92:95], v[48:63]
	v_mfma_f32_32x32x16_bf16 v[64:79], v[136:139], v[96:99], v[64:79]
	ds_write_b128 v162, v[80:83]
	global_load_dwordx4 v[172:175], v153, s[42:43]
	global_load_dwordx4 v[176:179], v157, s[42:43]
	s_sub_u32 s42, s42, 2048
	s_subb_u32 s43, s43, 0
	s_nop 11
	global_load_dwordx4 v[80:83], v150, s[10:11]
	global_load_dwordx4 v[194:197], v193, s[10:11]
	s_sub_u32 s34, s34, 1024
	s_subb_u32 s35, s35, 0
	s_sub_u32 s10, s10, 1024
	s_subb_u32 s11, s11, 0
	v_fmac_f32_e32 v63, v116, v120
	v_fmac_f32_e32 v79, v118, v121
	v_fmac_f32_dpp v63, v120, v122 quad_perm:[1,0,3,2] row_mask:0xf bank_mask:0xf
	v_fmac_f32_dpp v79, v121, v123 quad_perm:[1,0,3,2] row_mask:0xf bank_mask:0xf
	v_cvt_pk_bf16_f32 v148, v63, v79
	ds_write_b32 v151, v148 offset:8432
	v_fmac_f32_e32 v62, v116, v63
	v_fmac_f32_e32 v78, v118, v79
	v_fmac_f32_dpp v62, v63, v122 quad_perm:[1,0,3,2] row_mask:0xf bank_mask:0xf
	v_fmac_f32_dpp v78, v79, v123 quad_perm:[1,0,3,2] row_mask:0xf bank_mask:0xf
	v_cvt_pk_bf16_f32 v149, v62, v78
	ds_write_b32 v151, v149 offset:8160
	v_fmac_f32_e32 v61, v116, v62
	v_fmac_f32_e32 v77, v118, v78
	v_fmac_f32_dpp v61, v62, v122 quad_perm:[1,0,3,2] row_mask:0xf bank_mask:0xf
	v_fmac_f32_dpp v77, v78, v123 quad_perm:[1,0,3,2] row_mask:0xf bank_mask:0xf
	v_cvt_pk_bf16_f32 v148, v61, v77
	ds_write_b32 v151, v148 offset:7888
	v_fmac_f32_e32 v60, v116, v61
	v_fmac_f32_e32 v76, v118, v77
	v_fmac_f32_dpp v60, v61, v122 quad_perm:[1,0,3,2] row_mask:0xf bank_mask:0xf
	v_fmac_f32_dpp v76, v77, v123 quad_perm:[1,0,3,2] row_mask:0xf bank_mask:0xf
	v_cvt_pk_bf16_f32 v149, v60, v76
	ds_write_b32 v151, v149 offset:7616
	v_fmac_f32_e32 v31, v116, v60
	v_fmac_f32_e32 v47, v118, v76
	v_fmac_f32_dpp v31, v60, v122 quad_perm:[1,0,3,2] row_mask:0xf bank_mask:0xf
	v_fmac_f32_dpp v47, v76, v123 quad_perm:[1,0,3,2] row_mask:0xf bank_mask:0xf
	v_cvt_pk_bf16_f32 v148, v31, v47
	ds_write_b32 v151, v148 offset:7344
	v_fmac_f32_e32 v30, v116, v31
	v_fmac_f32_e32 v46, v118, v47
	v_fmac_f32_dpp v30, v31, v122 quad_perm:[1,0,3,2] row_mask:0xf bank_mask:0xf
	v_fmac_f32_dpp v46, v47, v123 quad_perm:[1,0,3,2] row_mask:0xf bank_mask:0xf
	v_cvt_pk_bf16_f32 v149, v30, v46
	ds_write_b32 v151, v149 offset:7072
	v_fmac_f32_e32 v29, v116, v30
	v_fmac_f32_e32 v45, v118, v46
	v_fmac_f32_dpp v29, v30, v122 quad_perm:[1,0,3,2] row_mask:0xf bank_mask:0xf
	v_fmac_f32_dpp v45, v46, v123 quad_perm:[1,0,3,2] row_mask:0xf bank_mask:0xf
	v_cvt_pk_bf16_f32 v148, v29, v45
	ds_write_b32 v151, v148 offset:6800
	v_fmac_f32_e32 v28, v116, v29
	v_fmac_f32_e32 v44, v118, v45
	v_fmac_f32_dpp v28, v29, v122 quad_perm:[1,0,3,2] row_mask:0xf bank_mask:0xf
	v_fmac_f32_dpp v44, v45, v123 quad_perm:[1,0,3,2] row_mask:0xf bank_mask:0xf
	v_cvt_pk_bf16_f32 v149, v28, v44
	ds_write_b32 v151, v149 offset:6528
	v_fmac_f32_e32 v59, v116, v28
	v_fmac_f32_e32 v75, v118, v44
	v_fmac_f32_dpp v59, v28, v122 quad_perm:[1,0,3,2] row_mask:0xf bank_mask:0xf
	v_fmac_f32_dpp v75, v44, v123 quad_perm:[1,0,3,2] row_mask:0xf bank_mask:0xf
	v_cvt_pk_bf16_f32 v148, v59, v75
	ds_write_b32 v151, v148 offset:6256
	v_fmac_f32_e32 v58, v116, v59
	v_fmac_f32_e32 v74, v118, v75
	v_fmac_f32_dpp v58, v59, v122 quad_perm:[1,0,3,2] row_mask:0xf bank_mask:0xf
	v_fmac_f32_dpp v74, v75, v123 quad_perm:[1,0,3,2] row_mask:0xf bank_mask:0xf
	v_cvt_pk_bf16_f32 v149, v58, v74
	ds_write_b32 v151, v149 offset:5984
	v_fmac_f32_e32 v57, v116, v58
	v_fmac_f32_e32 v73, v118, v74
	v_fmac_f32_dpp v57, v58, v122 quad_perm:[1,0,3,2] row_mask:0xf bank_mask:0xf
	v_fmac_f32_dpp v73, v74, v123 quad_perm:[1,0,3,2] row_mask:0xf bank_mask:0xf
	v_cvt_pk_bf16_f32 v148, v57, v73
	ds_write_b32 v151, v148 offset:5712
	v_fmac_f32_e32 v56, v116, v57
	v_fmac_f32_e32 v72, v118, v73
	v_fmac_f32_dpp v56, v57, v122 quad_perm:[1,0,3,2] row_mask:0xf bank_mask:0xf
	v_fmac_f32_dpp v72, v73, v123 quad_perm:[1,0,3,2] row_mask:0xf bank_mask:0xf
	v_cvt_pk_bf16_f32 v149, v56, v72
	ds_write_b32 v151, v149 offset:5440
	v_fmac_f32_e32 v27, v116, v56
	v_fmac_f32_e32 v43, v118, v72
	v_fmac_f32_dpp v27, v56, v122 quad_perm:[1,0,3,2] row_mask:0xf bank_mask:0xf
	v_fmac_f32_dpp v43, v72, v123 quad_perm:[1,0,3,2] row_mask:0xf bank_mask:0xf
	v_cvt_pk_bf16_f32 v148, v27, v43
	ds_write_b32 v151, v148 offset:5168
	v_fmac_f32_e32 v26, v116, v27
	v_fmac_f32_e32 v42, v118, v43
	v_fmac_f32_dpp v26, v27, v122 quad_perm:[1,0,3,2] row_mask:0xf bank_mask:0xf
	v_fmac_f32_dpp v42, v43, v123 quad_perm:[1,0,3,2] row_mask:0xf bank_mask:0xf
	v_cvt_pk_bf16_f32 v149, v26, v42
	ds_write_b32 v151, v149 offset:4896
	v_fmac_f32_e32 v25, v116, v26
	v_fmac_f32_e32 v41, v118, v42
	v_fmac_f32_dpp v25, v26, v122 quad_perm:[1,0,3,2] row_mask:0xf bank_mask:0xf
	v_fmac_f32_dpp v41, v42, v123 quad_perm:[1,0,3,2] row_mask:0xf bank_mask:0xf
	v_cvt_pk_bf16_f32 v148, v25, v41
	ds_write_b32 v151, v148 offset:4624
	v_fmac_f32_e32 v24, v116, v25
	v_fmac_f32_e32 v40, v118, v41
	v_fmac_f32_dpp v24, v25, v122 quad_perm:[1,0,3,2] row_mask:0xf bank_mask:0xf
	v_fmac_f32_dpp v40, v41, v123 quad_perm:[1,0,3,2] row_mask:0xf bank_mask:0xf
	v_cvt_pk_bf16_f32 v149, v24, v40
	ds_write_b32 v151, v149 offset:4352
	v_fmac_f32_e32 v55, v116, v24
	v_fmac_f32_e32 v71, v118, v40
	v_fmac_f32_dpp v55, v24, v122 quad_perm:[1,0,3,2] row_mask:0xf bank_mask:0xf
	v_fmac_f32_dpp v71, v40, v123 quad_perm:[1,0,3,2] row_mask:0xf bank_mask:0xf
	v_cvt_pk_bf16_f32 v148, v55, v71
	ds_write_b32 v151, v148 offset:4080
	v_fmac_f32_e32 v54, v116, v55
	v_fmac_f32_e32 v70, v118, v71
	v_fmac_f32_dpp v54, v55, v122 quad_perm:[1,0,3,2] row_mask:0xf bank_mask:0xf
	v_fmac_f32_dpp v70, v71, v123 quad_perm:[1,0,3,2] row_mask:0xf bank_mask:0xf
	v_cvt_pk_bf16_f32 v149, v54, v70
	ds_write_b32 v151, v149 offset:3808
	v_fmac_f32_e32 v53, v116, v54
	v_fmac_f32_e32 v69, v118, v70
	v_fmac_f32_dpp v53, v54, v122 quad_perm:[1,0,3,2] row_mask:0xf bank_mask:0xf
	v_fmac_f32_dpp v69, v70, v123 quad_perm:[1,0,3,2] row_mask:0xf bank_mask:0xf
	v_cvt_pk_bf16_f32 v148, v53, v69
	ds_write_b32 v151, v148 offset:3536
	v_fmac_f32_e32 v52, v116, v53
	v_fmac_f32_e32 v68, v118, v69
	v_fmac_f32_dpp v52, v53, v122 quad_perm:[1,0,3,2] row_mask:0xf bank_mask:0xf
	v_fmac_f32_dpp v68, v69, v123 quad_perm:[1,0,3,2] row_mask:0xf bank_mask:0xf
	v_cvt_pk_bf16_f32 v149, v52, v68
	ds_write_b32 v151, v149 offset:3264
	v_fmac_f32_e32 v23, v116, v52
	v_fmac_f32_e32 v39, v118, v68
	v_fmac_f32_dpp v23, v52, v122 quad_perm:[1,0,3,2] row_mask:0xf bank_mask:0xf
	v_fmac_f32_dpp v39, v68, v123 quad_perm:[1,0,3,2] row_mask:0xf bank_mask:0xf
	v_cvt_pk_bf16_f32 v148, v23, v39
	ds_write_b32 v151, v148 offset:2992
	v_fmac_f32_e32 v22, v116, v23
	v_fmac_f32_e32 v38, v118, v39
	v_fmac_f32_dpp v22, v23, v122 quad_perm:[1,0,3,2] row_mask:0xf bank_mask:0xf
	v_fmac_f32_dpp v38, v39, v123 quad_perm:[1,0,3,2] row_mask:0xf bank_mask:0xf
	v_cvt_pk_bf16_f32 v149, v22, v38
	ds_write_b32 v151, v149 offset:2720
	v_fmac_f32_e32 v21, v116, v22
	v_fmac_f32_e32 v37, v118, v38
	v_fmac_f32_dpp v21, v22, v122 quad_perm:[1,0,3,2] row_mask:0xf bank_mask:0xf
	v_fmac_f32_dpp v37, v38, v123 quad_perm:[1,0,3,2] row_mask:0xf bank_mask:0xf
	v_cvt_pk_bf16_f32 v148, v21, v37
	ds_write_b32 v151, v148 offset:2448
	v_fmac_f32_e32 v20, v116, v21
	v_fmac_f32_e32 v36, v118, v37
	v_fmac_f32_dpp v20, v21, v122 quad_perm:[1,0,3,2] row_mask:0xf bank_mask:0xf
	v_fmac_f32_dpp v36, v37, v123 quad_perm:[1,0,3,2] row_mask:0xf bank_mask:0xf
	v_cvt_pk_bf16_f32 v149, v20, v36
	ds_write_b32 v151, v149 offset:2176
	v_fmac_f32_e32 v51, v116, v20
	v_fmac_f32_e32 v67, v118, v36
	v_fmac_f32_dpp v51, v20, v122 quad_perm:[1,0,3,2] row_mask:0xf bank_mask:0xf
	v_fmac_f32_dpp v67, v36, v123 quad_perm:[1,0,3,2] row_mask:0xf bank_mask:0xf
	v_cvt_pk_bf16_f32 v148, v51, v67
	ds_write_b32 v151, v148 offset:1904
	v_fmac_f32_e32 v50, v116, v51
	v_fmac_f32_e32 v66, v118, v67
	v_fmac_f32_dpp v50, v51, v122 quad_perm:[1,0,3,2] row_mask:0xf bank_mask:0xf
	v_fmac_f32_dpp v66, v67, v123 quad_perm:[1,0,3,2] row_mask:0xf bank_mask:0xf
	v_cvt_pk_bf16_f32 v149, v50, v66
	ds_write_b32 v151, v149 offset:1632
	v_fmac_f32_e32 v49, v116, v50
	v_fmac_f32_e32 v65, v118, v66
	v_fmac_f32_dpp v49, v50, v122 quad_perm:[1,0,3,2] row_mask:0xf bank_mask:0xf
	v_fmac_f32_dpp v65, v66, v123 quad_perm:[1,0,3,2] row_mask:0xf bank_mask:0xf
	v_cvt_pk_bf16_f32 v148, v49, v65
	ds_write_b32 v151, v148 offset:1360
	v_fmac_f32_e32 v48, v116, v49
	v_fmac_f32_e32 v64, v118, v65
	v_fmac_f32_dpp v48, v49, v122 quad_perm:[1,0,3,2] row_mask:0xf bank_mask:0xf
	v_fmac_f32_dpp v64, v65, v123 quad_perm:[1,0,3,2] row_mask:0xf bank_mask:0xf
	v_cvt_pk_bf16_f32 v149, v48, v64
	ds_write_b32 v151, v149 offset:1088
	v_fmac_f32_e32 v19, v116, v48
	v_fmac_f32_e32 v35, v118, v64
	v_fmac_f32_dpp v19, v48, v122 quad_perm:[1,0,3,2] row_mask:0xf bank_mask:0xf
	v_fmac_f32_dpp v35, v64, v123 quad_perm:[1,0,3,2] row_mask:0xf bank_mask:0xf
	v_cvt_pk_bf16_f32 v148, v19, v35
	ds_write_b32 v151, v148 offset:816
	v_fmac_f32_e32 v18, v116, v19
	v_fmac_f32_e32 v34, v118, v35
	v_fmac_f32_dpp v18, v19, v122 quad_perm:[1,0,3,2] row_mask:0xf bank_mask:0xf
	v_fmac_f32_dpp v34, v35, v123 quad_perm:[1,0,3,2] row_mask:0xf bank_mask:0xf
	v_cvt_pk_bf16_f32 v149, v18, v34
	ds_write_b32 v151, v149 offset:544
	v_fmac_f32_e32 v17, v116, v18
	v_fmac_f32_e32 v33, v118, v34
	v_fmac_f32_dpp v17, v18, v122 quad_perm:[1,0,3,2] row_mask:0xf bank_mask:0xf
	v_fmac_f32_dpp v33, v34, v123 quad_perm:[1,0,3,2] row_mask:0xf bank_mask:0xf
	v_cvt_pk_bf16_f32 v148, v17, v33
	ds_write_b32 v151, v148 offset:272
	v_fmac_f32_e32 v16, v116, v17
	v_fmac_f32_e32 v32, v118, v33
	v_fmac_f32_dpp v16, v17, v122 quad_perm:[1,0,3,2] row_mask:0xf bank_mask:0xf
	v_fmac_f32_dpp v32, v33, v123 quad_perm:[1,0,3,2] row_mask:0xf bank_mask:0xf
	v_cvt_pk_bf16_f32 v149, v16, v32
	ds_write_b32 v151, v149
	v_mov_b32_e32 v120, v16
	v_mov_b32_e32 v121, v32
	ds_read_b128 v[124:127], v152
	ds_read_b128 v[128:131], v152 offset:64
	ds_read_b128 v[132:135], v152 offset:128
	ds_read_b128 v[136:139], v152 offset:192
	ds_read_b64 v[160:161], v163
	s_waitcnt lgkmcnt(4)
	v_mfma_f32_16x16x32_bf16 v[140:143], v[100:103], v[124:127], 0
	s_waitcnt lgkmcnt(3)
	v_mfma_f32_16x16x32_bf16 v[140:143], v[104:107], v[128:131], v[140:143]
	s_waitcnt lgkmcnt(2)
	v_mfma_f32_16x16x32_bf16 v[140:143], v[108:111], v[132:135], v[140:143]
	s_waitcnt lgkmcnt(1)
	v_mfma_f32_16x16x32_bf16 v[140:143], v[112:115], v[136:139], v[140:143]
	s_nop 9
	s_waitcnt vmcnt(9) lgkmcnt(0)
	v_add_f32_e32 v182, v6, v140
	v_add_f32_e32 v183, v7, v141
	v_add_f32_e32 v184, v8, v142
	v_add_f32_e32 v185, v9, v143
	v_lshlrev_b32_e32 v186, 16, v160
	v_and_b32_e32 v187, 0xffff0000, v160
	v_lshlrev_b32_e32 v188, 16, v161
	v_and_b32_e32 v189, 0xffff0000, v161
	v_fmac_f32_e32 v182, v164, v186
	v_fmac_f32_e32 v183, v165, v187
	v_fmac_f32_e32 v184, v166, v188
	v_fmac_f32_e32 v185, v167, v189
	v_mul_f32_e32 v186, 0x3d372713, v182
	v_mul_f32_e32 v187, 0x3d372713, v183
	v_mul_f32_e32 v188, 0x3d372713, v184
	v_mul_f32_e32 v189, 0x3d372713, v185
	v_mul_f32_e32 v186, v182, v186
	v_mul_f32_e32 v187, v183, v187
	v_mul_f32_e32 v188, v184, v188
	v_mul_f32_e32 v189, v185, v189
	v_fma_f32 v186, v182, v186, v182
	v_fma_f32 v187, v183, v187, v183
	v_fma_f32 v188, v184, v188, v184
	v_fma_f32 v189, v185, v189, v185
	v_mul_f32_e32 v186, 0xbfcc422a, v186
	v_mul_f32_e32 v187, 0xbfcc422a, v187
	v_mul_f32_e32 v188, 0xbfcc422a, v188
	v_mul_f32_e32 v189, 0xbfcc422a, v189
	v_mul_f32_e32 v186, 0x3fb8aa3b, v186
	v_mul_f32_e32 v187, 0x3fb8aa3b, v187
	v_mul_f32_e32 v188, 0x3fb8aa3b, v188
	v_mul_f32_e32 v189, 0x3fb8aa3b, v189
	v_exp_f32_e32 v186, v186
	v_exp_f32_e32 v187, v187
	v_exp_f32_e32 v188, v188
	v_exp_f32_e32 v189, v189
	v_add_f32_e32 v186, 1.0, v186
	v_add_f32_e32 v187, 1.0, v187
	v_add_f32_e32 v188, 1.0, v188
	v_add_f32_e32 v189, 1.0, v189
	v_rcp_f32_e32 v186, v186
	v_rcp_f32_e32 v187, v187
	v_rcp_f32_e32 v188, v188
	v_rcp_f32_e32 v189, v189
	v_mul_f32_e32 v182, v182, v186
	v_mul_f32_e32 v183, v183, v187
	v_mul_f32_e32 v184, v184, v188
	v_mul_f32_e32 v185, v185, v189
	v_cvt_pk_bf16_f32 v148, v182, v183
	v_cvt_pk_bf16_f32 v149, v184, v185
	global_store_dwordx2 v156, v[148:149], s[12:13]
	ds_read_b128 v[124:127], v152 offset:4352
	ds_read_b128 v[128:131], v152 offset:4416
	ds_read_b128 v[132:135], v152 offset:4480
	ds_read_b128 v[136:139], v152 offset:4544
	ds_read_b64 v[160:161], v163 offset:512
	s_waitcnt lgkmcnt(4)
	v_mfma_f32_16x16x32_bf16 v[140:143], v[100:103], v[124:127], 0
	s_waitcnt lgkmcnt(3)
	v_mfma_f32_16x16x32_bf16 v[140:143], v[104:107], v[128:131], v[140:143]
	s_waitcnt lgkmcnt(2)
	v_mfma_f32_16x16x32_bf16 v[140:143], v[108:111], v[132:135], v[140:143]
	s_waitcnt lgkmcnt(1)
	v_mfma_f32_16x16x32_bf16 v[140:143], v[112:115], v[136:139], v[140:143]
	s_nop 9
	s_waitcnt vmcnt(9) lgkmcnt(0)
	v_add_f32_e32 v182, v10, v140
	v_add_f32_e32 v183, v11, v141
	v_add_f32_e32 v184, v12, v142
	v_add_f32_e32 v185, v13, v143
	v_lshlrev_b32_e32 v186, 16, v160
	v_and_b32_e32 v187, 0xffff0000, v160
	v_lshlrev_b32_e32 v188, 16, v161
	v_and_b32_e32 v189, 0xffff0000, v161
	v_fmac_f32_e32 v182, v164, v186
	v_fmac_f32_e32 v183, v165, v187
	v_fmac_f32_e32 v184, v166, v188
	v_fmac_f32_e32 v185, v167, v189
	v_mul_f32_e32 v186, 0x3d372713, v182
	v_mul_f32_e32 v187, 0x3d372713, v183
	v_mul_f32_e32 v188, 0x3d372713, v184
	v_mul_f32_e32 v189, 0x3d372713, v185
	v_mul_f32_e32 v186, v182, v186
	v_mul_f32_e32 v187, v183, v187
	v_mul_f32_e32 v188, v184, v188
	v_mul_f32_e32 v189, v185, v189
	v_fma_f32 v186, v182, v186, v182
	v_fma_f32 v187, v183, v187, v183
	v_fma_f32 v188, v184, v188, v184
	v_fma_f32 v189, v185, v189, v185
	v_mul_f32_e32 v186, 0xbfcc422a, v186
	v_mul_f32_e32 v187, 0xbfcc422a, v187
	v_mul_f32_e32 v188, 0xbfcc422a, v188
	v_mul_f32_e32 v189, 0xbfcc422a, v189
	v_mul_f32_e32 v186, 0x3fb8aa3b, v186
	v_mul_f32_e32 v187, 0x3fb8aa3b, v187
	v_mul_f32_e32 v188, 0x3fb8aa3b, v188
	v_mul_f32_e32 v189, 0x3fb8aa3b, v189
	v_exp_f32_e32 v186, v186
	v_exp_f32_e32 v187, v187
	v_exp_f32_e32 v188, v188
	v_exp_f32_e32 v189, v189
	v_add_f32_e32 v186, 1.0, v186
	v_add_f32_e32 v187, 1.0, v187
	v_add_f32_e32 v188, 1.0, v188
	v_add_f32_e32 v189, 1.0, v189
	v_rcp_f32_e32 v186, v186
	v_rcp_f32_e32 v187, v187
	v_rcp_f32_e32 v188, v188
	v_rcp_f32_e32 v189, v189
	v_mul_f32_e32 v182, v182, v186
	v_mul_f32_e32 v183, v183, v187
	v_mul_f32_e32 v184, v184, v188
	v_mul_f32_e32 v185, v185, v189
	v_cvt_pk_bf16_f32 v148, v182, v183
	v_cvt_pk_bf16_f32 v149, v184, v185
	global_store_dwordx2 v159, v[148:149], s[12:13]
	s_sub_u32 s12, s12, 65536
	s_subb_u32 s13, s13, 0
	s_waitcnt vmcnt(8)
	v_cndmask_b32_e64 v124, 0, v144, s[66:67]
	v_cndmask_b32_e64 v125, 0, v145, s[66:67]
	v_cndmask_b32_e64 v126, 0, v146, s[66:67]
	v_cndmask_b32_e64 v127, 0, v147, s[66:67]
	v_cndmask_b32_e64 v132, 0, v168, s[66:67]
	v_cndmask_b32_e64 v133, 0, v169, s[66:67]
	v_cndmask_b32_e64 v134, 0, v170, s[66:67]
	v_cndmask_b32_e64 v135, 0, v171, s[66:67]
	v_mfma_f32_32x32x16_bf16 v[16:31], v[124:127], v[84:87], 0
	v_cndmask_b32_e64 v128, 0, v168, s[68:69]
	v_cndmask_b32_e64 v129, 0, v169, s[68:69]
	v_cndmask_b32_e64 v130, 0, v170, s[68:69]
	v_cndmask_b32_e64 v131, 0, v171, s[68:69]
	v_mfma_f32_32x32x16_bf16 v[32:47], v[124:127], v[88:91], 0
	v_cndmask_b32_e64 v136, 0, v144, s[68:69]
	v_cndmask_b32_e64 v137, 0, v145, s[68:69]
	v_cndmask_b32_e64 v138, 0, v146, s[68:69]
	v_cndmask_b32_e64 v139, 0, v147, s[68:69]
	v_mfma_f32_32x32x16_bf16 v[48:63], v[132:135], v[84:87], 0
	v_mfma_f32_32x32x16_bf16 v[64:79], v[132:135], v[88:91], 0
	v_mfma_f32_32x32x16_bf16 v[16:31], v[128:131], v[92:95], v[16:31]
	v_mfma_f32_32x32x16_bf16 v[32:47], v[128:131], v[96:99], v[32:47]
	v_mfma_f32_32x32x16_bf16 v[48:63], v[136:139], v[92:95], v[48:63]
	v_mfma_f32_32x32x16_bf16 v[64:79], v[136:139], v[96:99], v[64:79]
	ds_write_b128 v162, v[144:147]
	global_load_dwordx4 v[6:9], v153, s[42:43]
	global_load_dwordx4 v[10:13], v157, s[42:43]
	s_sub_u32 s42, s42, 2048
	s_subb_u32 s43, s43, 0
	s_nop 11
	global_load_dwordx4 v[144:147], v150, s[10:11]
	global_load_dwordx4 v[168:171], v193, s[10:11]
	s_sub_u32 s34, s34, 1024
	s_subb_u32 s35, s35, 0
	s_sub_u32 s10, s10, 1024
	s_subb_u32 s11, s11, 0
	v_fmac_f32_e32 v63, v116, v120
	v_fmac_f32_e32 v79, v118, v121
	v_fmac_f32_dpp v63, v120, v122 quad_perm:[1,0,3,2] row_mask:0xf bank_mask:0xf
	v_fmac_f32_dpp v79, v121, v123 quad_perm:[1,0,3,2] row_mask:0xf bank_mask:0xf
	v_cvt_pk_bf16_f32 v148, v63, v79
	ds_write_b32 v151, v148 offset:8432
	v_fmac_f32_e32 v62, v116, v63
	v_fmac_f32_e32 v78, v118, v79
	v_fmac_f32_dpp v62, v63, v122 quad_perm:[1,0,3,2] row_mask:0xf bank_mask:0xf
	v_fmac_f32_dpp v78, v79, v123 quad_perm:[1,0,3,2] row_mask:0xf bank_mask:0xf
	v_cvt_pk_bf16_f32 v149, v62, v78
	ds_write_b32 v151, v149 offset:8160
	v_fmac_f32_e32 v61, v116, v62
	v_fmac_f32_e32 v77, v118, v78
	v_fmac_f32_dpp v61, v62, v122 quad_perm:[1,0,3,2] row_mask:0xf bank_mask:0xf
	v_fmac_f32_dpp v77, v78, v123 quad_perm:[1,0,3,2] row_mask:0xf bank_mask:0xf
	v_cvt_pk_bf16_f32 v148, v61, v77
	ds_write_b32 v151, v148 offset:7888
	v_fmac_f32_e32 v60, v116, v61
	v_fmac_f32_e32 v76, v118, v77
	v_fmac_f32_dpp v60, v61, v122 quad_perm:[1,0,3,2] row_mask:0xf bank_mask:0xf
	v_fmac_f32_dpp v76, v77, v123 quad_perm:[1,0,3,2] row_mask:0xf bank_mask:0xf
	v_cvt_pk_bf16_f32 v149, v60, v76
	ds_write_b32 v151, v149 offset:7616
	v_fmac_f32_e32 v31, v116, v60
	v_fmac_f32_e32 v47, v118, v76
	v_fmac_f32_dpp v31, v60, v122 quad_perm:[1,0,3,2] row_mask:0xf bank_mask:0xf
	v_fmac_f32_dpp v47, v76, v123 quad_perm:[1,0,3,2] row_mask:0xf bank_mask:0xf
	v_cvt_pk_bf16_f32 v148, v31, v47
	ds_write_b32 v151, v148 offset:7344
	v_fmac_f32_e32 v30, v116, v31
	v_fmac_f32_e32 v46, v118, v47
	v_fmac_f32_dpp v30, v31, v122 quad_perm:[1,0,3,2] row_mask:0xf bank_mask:0xf
	v_fmac_f32_dpp v46, v47, v123 quad_perm:[1,0,3,2] row_mask:0xf bank_mask:0xf
	v_cvt_pk_bf16_f32 v149, v30, v46
	ds_write_b32 v151, v149 offset:7072
	v_fmac_f32_e32 v29, v116, v30
	v_fmac_f32_e32 v45, v118, v46
	v_fmac_f32_dpp v29, v30, v122 quad_perm:[1,0,3,2] row_mask:0xf bank_mask:0xf
	v_fmac_f32_dpp v45, v46, v123 quad_perm:[1,0,3,2] row_mask:0xf bank_mask:0xf
	v_cvt_pk_bf16_f32 v148, v29, v45
	ds_write_b32 v151, v148 offset:6800
	v_fmac_f32_e32 v28, v116, v29
	v_fmac_f32_e32 v44, v118, v45
	v_fmac_f32_dpp v28, v29, v122 quad_perm:[1,0,3,2] row_mask:0xf bank_mask:0xf
	v_fmac_f32_dpp v44, v45, v123 quad_perm:[1,0,3,2] row_mask:0xf bank_mask:0xf
	v_cvt_pk_bf16_f32 v149, v28, v44
	ds_write_b32 v151, v149 offset:6528
	v_fmac_f32_e32 v59, v116, v28
	v_fmac_f32_e32 v75, v118, v44
	v_fmac_f32_dpp v59, v28, v122 quad_perm:[1,0,3,2] row_mask:0xf bank_mask:0xf
	v_fmac_f32_dpp v75, v44, v123 quad_perm:[1,0,3,2] row_mask:0xf bank_mask:0xf
	v_cvt_pk_bf16_f32 v148, v59, v75
	ds_write_b32 v151, v148 offset:6256
	v_fmac_f32_e32 v58, v116, v59
	v_fmac_f32_e32 v74, v118, v75
	v_fmac_f32_dpp v58, v59, v122 quad_perm:[1,0,3,2] row_mask:0xf bank_mask:0xf
	v_fmac_f32_dpp v74, v75, v123 quad_perm:[1,0,3,2] row_mask:0xf bank_mask:0xf
	v_cvt_pk_bf16_f32 v149, v58, v74
	ds_write_b32 v151, v149 offset:5984
	v_fmac_f32_e32 v57, v116, v58
	v_fmac_f32_e32 v73, v118, v74
	v_fmac_f32_dpp v57, v58, v122 quad_perm:[1,0,3,2] row_mask:0xf bank_mask:0xf
	v_fmac_f32_dpp v73, v74, v123 quad_perm:[1,0,3,2] row_mask:0xf bank_mask:0xf
	v_cvt_pk_bf16_f32 v148, v57, v73
	ds_write_b32 v151, v148 offset:5712
	v_fmac_f32_e32 v56, v116, v57
	v_fmac_f32_e32 v72, v118, v73
	v_fmac_f32_dpp v56, v57, v122 quad_perm:[1,0,3,2] row_mask:0xf bank_mask:0xf
	v_fmac_f32_dpp v72, v73, v123 quad_perm:[1,0,3,2] row_mask:0xf bank_mask:0xf
	v_cvt_pk_bf16_f32 v149, v56, v72
	ds_write_b32 v151, v149 offset:5440
	v_fmac_f32_e32 v27, v116, v56
	v_fmac_f32_e32 v43, v118, v72
	v_fmac_f32_dpp v27, v56, v122 quad_perm:[1,0,3,2] row_mask:0xf bank_mask:0xf
	v_fmac_f32_dpp v43, v72, v123 quad_perm:[1,0,3,2] row_mask:0xf bank_mask:0xf
	v_cvt_pk_bf16_f32 v148, v27, v43
	ds_write_b32 v151, v148 offset:5168
	v_fmac_f32_e32 v26, v116, v27
	v_fmac_f32_e32 v42, v118, v43
	v_fmac_f32_dpp v26, v27, v122 quad_perm:[1,0,3,2] row_mask:0xf bank_mask:0xf
	v_fmac_f32_dpp v42, v43, v123 quad_perm:[1,0,3,2] row_mask:0xf bank_mask:0xf
	v_cvt_pk_bf16_f32 v149, v26, v42
	ds_write_b32 v151, v149 offset:4896
	v_fmac_f32_e32 v25, v116, v26
	v_fmac_f32_e32 v41, v118, v42
	v_fmac_f32_dpp v25, v26, v122 quad_perm:[1,0,3,2] row_mask:0xf bank_mask:0xf
	v_fmac_f32_dpp v41, v42, v123 quad_perm:[1,0,3,2] row_mask:0xf bank_mask:0xf
	v_cvt_pk_bf16_f32 v148, v25, v41
	ds_write_b32 v151, v148 offset:4624
	v_fmac_f32_e32 v24, v116, v25
	v_fmac_f32_e32 v40, v118, v41
	v_fmac_f32_dpp v24, v25, v122 quad_perm:[1,0,3,2] row_mask:0xf bank_mask:0xf
	v_fmac_f32_dpp v40, v41, v123 quad_perm:[1,0,3,2] row_mask:0xf bank_mask:0xf
	v_cvt_pk_bf16_f32 v149, v24, v40
	ds_write_b32 v151, v149 offset:4352
	v_fmac_f32_e32 v55, v116, v24
	v_fmac_f32_e32 v71, v118, v40
	v_fmac_f32_dpp v55, v24, v122 quad_perm:[1,0,3,2] row_mask:0xf bank_mask:0xf
	v_fmac_f32_dpp v71, v40, v123 quad_perm:[1,0,3,2] row_mask:0xf bank_mask:0xf
	v_cvt_pk_bf16_f32 v148, v55, v71
	ds_write_b32 v151, v148 offset:4080
	v_fmac_f32_e32 v54, v116, v55
	v_fmac_f32_e32 v70, v118, v71
	v_fmac_f32_dpp v54, v55, v122 quad_perm:[1,0,3,2] row_mask:0xf bank_mask:0xf
	v_fmac_f32_dpp v70, v71, v123 quad_perm:[1,0,3,2] row_mask:0xf bank_mask:0xf
	v_cvt_pk_bf16_f32 v149, v54, v70
	ds_write_b32 v151, v149 offset:3808
	v_fmac_f32_e32 v53, v116, v54
	v_fmac_f32_e32 v69, v118, v70
	v_fmac_f32_dpp v53, v54, v122 quad_perm:[1,0,3,2] row_mask:0xf bank_mask:0xf
	v_fmac_f32_dpp v69, v70, v123 quad_perm:[1,0,3,2] row_mask:0xf bank_mask:0xf
	v_cvt_pk_bf16_f32 v148, v53, v69
	ds_write_b32 v151, v148 offset:3536
	v_fmac_f32_e32 v52, v116, v53
	v_fmac_f32_e32 v68, v118, v69
	v_fmac_f32_dpp v52, v53, v122 quad_perm:[1,0,3,2] row_mask:0xf bank_mask:0xf
	v_fmac_f32_dpp v68, v69, v123 quad_perm:[1,0,3,2] row_mask:0xf bank_mask:0xf
	v_cvt_pk_bf16_f32 v149, v52, v68
	ds_write_b32 v151, v149 offset:3264
	v_fmac_f32_e32 v23, v116, v52
	v_fmac_f32_e32 v39, v118, v68
	v_fmac_f32_dpp v23, v52, v122 quad_perm:[1,0,3,2] row_mask:0xf bank_mask:0xf
	v_fmac_f32_dpp v39, v68, v123 quad_perm:[1,0,3,2] row_mask:0xf bank_mask:0xf
	v_cvt_pk_bf16_f32 v148, v23, v39
	ds_write_b32 v151, v148 offset:2992
	v_fmac_f32_e32 v22, v116, v23
	v_fmac_f32_e32 v38, v118, v39
	v_fmac_f32_dpp v22, v23, v122 quad_perm:[1,0,3,2] row_mask:0xf bank_mask:0xf
	v_fmac_f32_dpp v38, v39, v123 quad_perm:[1,0,3,2] row_mask:0xf bank_mask:0xf
	v_cvt_pk_bf16_f32 v149, v22, v38
	ds_write_b32 v151, v149 offset:2720
	v_fmac_f32_e32 v21, v116, v22
	v_fmac_f32_e32 v37, v118, v38
	v_fmac_f32_dpp v21, v22, v122 quad_perm:[1,0,3,2] row_mask:0xf bank_mask:0xf
	v_fmac_f32_dpp v37, v38, v123 quad_perm:[1,0,3,2] row_mask:0xf bank_mask:0xf
	v_cvt_pk_bf16_f32 v148, v21, v37
	ds_write_b32 v151, v148 offset:2448
	v_fmac_f32_e32 v20, v116, v21
	v_fmac_f32_e32 v36, v118, v37
	v_fmac_f32_dpp v20, v21, v122 quad_perm:[1,0,3,2] row_mask:0xf bank_mask:0xf
	v_fmac_f32_dpp v36, v37, v123 quad_perm:[1,0,3,2] row_mask:0xf bank_mask:0xf
	v_cvt_pk_bf16_f32 v149, v20, v36
	ds_write_b32 v151, v149 offset:2176
	v_fmac_f32_e32 v51, v116, v20
	v_fmac_f32_e32 v67, v118, v36
	v_fmac_f32_dpp v51, v20, v122 quad_perm:[1,0,3,2] row_mask:0xf bank_mask:0xf
	v_fmac_f32_dpp v67, v36, v123 quad_perm:[1,0,3,2] row_mask:0xf bank_mask:0xf
	v_cvt_pk_bf16_f32 v148, v51, v67
	ds_write_b32 v151, v148 offset:1904
	v_fmac_f32_e32 v50, v116, v51
	v_fmac_f32_e32 v66, v118, v67
	v_fmac_f32_dpp v50, v51, v122 quad_perm:[1,0,3,2] row_mask:0xf bank_mask:0xf
	v_fmac_f32_dpp v66, v67, v123 quad_perm:[1,0,3,2] row_mask:0xf bank_mask:0xf
	v_cvt_pk_bf16_f32 v149, v50, v66
	ds_write_b32 v151, v149 offset:1632
	v_fmac_f32_e32 v49, v116, v50
	v_fmac_f32_e32 v65, v118, v66
	v_fmac_f32_dpp v49, v50, v122 quad_perm:[1,0,3,2] row_mask:0xf bank_mask:0xf
	v_fmac_f32_dpp v65, v66, v123 quad_perm:[1,0,3,2] row_mask:0xf bank_mask:0xf
	v_cvt_pk_bf16_f32 v148, v49, v65
	ds_write_b32 v151, v148 offset:1360
	v_fmac_f32_e32 v48, v116, v49
	v_fmac_f32_e32 v64, v118, v65
	v_fmac_f32_dpp v48, v49, v122 quad_perm:[1,0,3,2] row_mask:0xf bank_mask:0xf
	v_fmac_f32_dpp v64, v65, v123 quad_perm:[1,0,3,2] row_mask:0xf bank_mask:0xf
	v_cvt_pk_bf16_f32 v149, v48, v64
	ds_write_b32 v151, v149 offset:1088
	v_fmac_f32_e32 v19, v116, v48
	v_fmac_f32_e32 v35, v118, v64
	v_fmac_f32_dpp v19, v48, v122 quad_perm:[1,0,3,2] row_mask:0xf bank_mask:0xf
	v_fmac_f32_dpp v35, v64, v123 quad_perm:[1,0,3,2] row_mask:0xf bank_mask:0xf
	v_cvt_pk_bf16_f32 v148, v19, v35
	ds_write_b32 v151, v148 offset:816
	v_fmac_f32_e32 v18, v116, v19
	v_fmac_f32_e32 v34, v118, v35
	v_fmac_f32_dpp v18, v19, v122 quad_perm:[1,0,3,2] row_mask:0xf bank_mask:0xf
	v_fmac_f32_dpp v34, v35, v123 quad_perm:[1,0,3,2] row_mask:0xf bank_mask:0xf
	v_cvt_pk_bf16_f32 v149, v18, v34
	ds_write_b32 v151, v149 offset:544
	v_fmac_f32_e32 v17, v116, v18
	v_fmac_f32_e32 v33, v118, v34
	v_fmac_f32_dpp v17, v18, v122 quad_perm:[1,0,3,2] row_mask:0xf bank_mask:0xf
	v_fmac_f32_dpp v33, v34, v123 quad_perm:[1,0,3,2] row_mask:0xf bank_mask:0xf
	v_cvt_pk_bf16_f32 v148, v17, v33
	ds_write_b32 v151, v148 offset:272
	v_fmac_f32_e32 v16, v116, v17
	v_fmac_f32_e32 v32, v118, v33
	v_fmac_f32_dpp v16, v17, v122 quad_perm:[1,0,3,2] row_mask:0xf bank_mask:0xf
	v_fmac_f32_dpp v32, v33, v123 quad_perm:[1,0,3,2] row_mask:0xf bank_mask:0xf
	v_cvt_pk_bf16_f32 v149, v16, v32
	ds_write_b32 v151, v149
	v_mov_b32_e32 v120, v16
	v_mov_b32_e32 v121, v32
	ds_read_b128 v[124:127], v152
	ds_read_b128 v[128:131], v152 offset:64
	ds_read_b128 v[132:135], v152 offset:128
	ds_read_b128 v[136:139], v152 offset:192
	ds_read_b64 v[160:161], v163
	s_waitcnt lgkmcnt(4)
	v_mfma_f32_16x16x32_bf16 v[140:143], v[100:103], v[124:127], 0
	s_waitcnt lgkmcnt(3)
	v_mfma_f32_16x16x32_bf16 v[140:143], v[104:107], v[128:131], v[140:143]
	s_waitcnt lgkmcnt(2)
	v_mfma_f32_16x16x32_bf16 v[140:143], v[108:111], v[132:135], v[140:143]
	s_waitcnt lgkmcnt(1)
	v_mfma_f32_16x16x32_bf16 v[140:143], v[112:115], v[136:139], v[140:143]
	s_nop 9
	s_waitcnt vmcnt(9) lgkmcnt(0)
	v_add_f32_e32 v182, v172, v140
	v_add_f32_e32 v183, v173, v141
	v_add_f32_e32 v184, v174, v142
	v_add_f32_e32 v185, v175, v143
	v_lshlrev_b32_e32 v186, 16, v160
	v_and_b32_e32 v187, 0xffff0000, v160
	v_lshlrev_b32_e32 v188, 16, v161
	v_and_b32_e32 v189, 0xffff0000, v161
	v_fmac_f32_e32 v182, v164, v186
	v_fmac_f32_e32 v183, v165, v187
	v_fmac_f32_e32 v184, v166, v188
	v_fmac_f32_e32 v185, v167, v189
	v_mul_f32_e32 v186, 0x3d372713, v182
	v_mul_f32_e32 v187, 0x3d372713, v183
	v_mul_f32_e32 v188, 0x3d372713, v184
	v_mul_f32_e32 v189, 0x3d372713, v185
	v_mul_f32_e32 v186, v182, v186
	v_mul_f32_e32 v187, v183, v187
	v_mul_f32_e32 v188, v184, v188
	v_mul_f32_e32 v189, v185, v189
	v_fma_f32 v186, v182, v186, v182
	v_fma_f32 v187, v183, v187, v183
	v_fma_f32 v188, v184, v188, v184
	v_fma_f32 v189, v185, v189, v185
	v_mul_f32_e32 v186, 0xbfcc422a, v186
	v_mul_f32_e32 v187, 0xbfcc422a, v187
	v_mul_f32_e32 v188, 0xbfcc422a, v188
	v_mul_f32_e32 v189, 0xbfcc422a, v189
	v_mul_f32_e32 v186, 0x3fb8aa3b, v186
	v_mul_f32_e32 v187, 0x3fb8aa3b, v187
	v_mul_f32_e32 v188, 0x3fb8aa3b, v188
	v_mul_f32_e32 v189, 0x3fb8aa3b, v189
	v_exp_f32_e32 v186, v186
	v_exp_f32_e32 v187, v187
	v_exp_f32_e32 v188, v188
	v_exp_f32_e32 v189, v189
	v_add_f32_e32 v186, 1.0, v186
	v_add_f32_e32 v187, 1.0, v187
	v_add_f32_e32 v188, 1.0, v188
	v_add_f32_e32 v189, 1.0, v189
	v_rcp_f32_e32 v186, v186
	v_rcp_f32_e32 v187, v187
	v_rcp_f32_e32 v188, v188
	v_rcp_f32_e32 v189, v189
	v_mul_f32_e32 v182, v182, v186
	v_mul_f32_e32 v183, v183, v187
	v_mul_f32_e32 v184, v184, v188
	v_mul_f32_e32 v185, v185, v189
	v_cvt_pk_bf16_f32 v148, v182, v183
	v_cvt_pk_bf16_f32 v149, v184, v185
	global_store_dwordx2 v156, v[148:149], s[12:13]
	ds_read_b128 v[124:127], v152 offset:4352
	ds_read_b128 v[128:131], v152 offset:4416
	ds_read_b128 v[132:135], v152 offset:4480
	ds_read_b128 v[136:139], v152 offset:4544
	ds_read_b64 v[160:161], v163 offset:512
	s_waitcnt lgkmcnt(4)
	v_mfma_f32_16x16x32_bf16 v[140:143], v[100:103], v[124:127], 0
	s_waitcnt lgkmcnt(3)
	v_mfma_f32_16x16x32_bf16 v[140:143], v[104:107], v[128:131], v[140:143]
	s_waitcnt lgkmcnt(2)
	v_mfma_f32_16x16x32_bf16 v[140:143], v[108:111], v[132:135], v[140:143]
	s_waitcnt lgkmcnt(1)
	v_mfma_f32_16x16x32_bf16 v[140:143], v[112:115], v[136:139], v[140:143]
	s_nop 9
	s_waitcnt vmcnt(9) lgkmcnt(0)
	v_add_f32_e32 v182, v176, v140
	v_add_f32_e32 v183, v177, v141
	v_add_f32_e32 v184, v178, v142
	v_add_f32_e32 v185, v179, v143
	v_lshlrev_b32_e32 v186, 16, v160
	v_and_b32_e32 v187, 0xffff0000, v160
	v_lshlrev_b32_e32 v188, 16, v161
	v_and_b32_e32 v189, 0xffff0000, v161
	v_fmac_f32_e32 v182, v164, v186
	v_fmac_f32_e32 v183, v165, v187
	v_fmac_f32_e32 v184, v166, v188
	v_fmac_f32_e32 v185, v167, v189
	v_mul_f32_e32 v186, 0x3d372713, v182
	v_mul_f32_e32 v187, 0x3d372713, v183
	v_mul_f32_e32 v188, 0x3d372713, v184
	v_mul_f32_e32 v189, 0x3d372713, v185
	v_mul_f32_e32 v186, v182, v186
	v_mul_f32_e32 v187, v183, v187
	v_mul_f32_e32 v188, v184, v188
	v_mul_f32_e32 v189, v185, v189
	v_fma_f32 v186, v182, v186, v182
	v_fma_f32 v187, v183, v187, v183
	v_fma_f32 v188, v184, v188, v184
	v_fma_f32 v189, v185, v189, v185
	v_mul_f32_e32 v186, 0xbfcc422a, v186
	v_mul_f32_e32 v187, 0xbfcc422a, v187
	v_mul_f32_e32 v188, 0xbfcc422a, v188
	v_mul_f32_e32 v189, 0xbfcc422a, v189
	v_mul_f32_e32 v186, 0x3fb8aa3b, v186
	v_mul_f32_e32 v187, 0x3fb8aa3b, v187
	v_mul_f32_e32 v188, 0x3fb8aa3b, v188
	v_mul_f32_e32 v189, 0x3fb8aa3b, v189
	v_exp_f32_e32 v186, v186
	v_exp_f32_e32 v187, v187
	v_exp_f32_e32 v188, v188
	v_exp_f32_e32 v189, v189
	v_add_f32_e32 v186, 1.0, v186
	v_add_f32_e32 v187, 1.0, v187
	v_add_f32_e32 v188, 1.0, v188
	v_add_f32_e32 v189, 1.0, v189
	v_rcp_f32_e32 v186, v186
	v_rcp_f32_e32 v187, v187
	v_rcp_f32_e32 v188, v188
	v_rcp_f32_e32 v189, v189
	v_mul_f32_e32 v182, v182, v186
	v_mul_f32_e32 v183, v183, v187
	v_mul_f32_e32 v184, v184, v188
	v_mul_f32_e32 v185, v185, v189
	v_cvt_pk_bf16_f32 v148, v182, v183
	v_cvt_pk_bf16_f32 v149, v184, v185
	global_store_dwordx2 v159, v[148:149], s[12:13]
	s_sub_u32 s12, s12, 65536
	s_subb_u32 s13, s13, 0
	s_add_u32 s14, s14, 2
	s_cmp_lt_u32 s14, 32
	s_cbranch_scc1 .Lssm_tileB_d1m0
	s_waitcnt vmcnt(0) lgkmcnt(0)

.Lssm_ctx_loop:
	s_lshl_b32 s22, s2, 3
	s_sub_u32 s21, s89, 4
	s_add_u32 s22, s22, s21
	s_lshl_b32 s21, s27, 2
	s_add_u32 s22, s22, s21
	s_lshr_b32 s23, s22, 6
	s_and_b32 s24, s22, 63
	s_lshl_b32 s25, s23, 8
	s_add_u32 s28, s24, 0
	s_lshl_b32 s29, s28, 13
	s_add_u32 s29, s29, 0x200000
	s_add_u32 s10, s62, s29
	s_addc_u32 s11, s63, 0
	global_load_dwordx4 v[84:87], v177, s[10:11]
	global_load_dwordx4 v[88:91], v177, s[10:11] offset:2048
	s_add_u32 s12, s10, 0x1000
	s_addc_u32 s13, s11, 0
	global_load_dwordx4 v[92:95], v177, s[12:13]
	global_load_dwordx4 v[96:99], v177, s[12:13] offset:2048
	s_lshl_b32 s29, s28, 12
	s_add_u32 s29, s29, 0x300000
	s_add_u32 s16, s62, s29
	s_addc_u32 s17, s63, 0
	global_load_dwordx2 v[20:21], v178, s[16:17]
	global_load_dwordx2 v[22:23], v178, s[16:17] offset:1024
	global_load_dwordx2 v[24:25], v178, s[16:17] offset:512
	global_load_dwordx2 v[26:27], v178, s[16:17] offset:1536
	global_load_dwordx2 v[28:29], v178, s[16:17] offset:2048
	global_load_dwordx2 v[30:31], v178, s[16:17] offset:3072
	global_load_dwordx2 v[32:33], v178, s[16:17] offset:2560
	global_load_dwordx2 v[34:35], v178, s[16:17] offset:3584
	s_lshl_b32 s29, s28, 9
	s_add_u32 s29, s29, 0x100000
	s_add_u32 s18, s62, s29
	s_addc_u32 s19, s63, 0
	global_load_dwordx2 v[116:117], v179, s[18:19]
	global_load_dwordx2 v[118:119], v179, s[18:19] offset:128
	s_lshl_b32 s30, s23, 1
	s_lshl_b32 s30, s30, 15
	s_lshl_b32 s31, s24, 8
	s_add_u32 s30, s30, s31
	v_mov_b32_e32 v120, 0
	v_mov_b32_e32 v121, 0
	s_lshl_b32 s31, s25, 5
	s_lshl_b32 s29, s24, 19
	s_add_u32 s31, s31, s29
	s_add_u32 s31, s31, 0x16800000
	s_add_u32 s4, s62, s31
	s_addc_u32 s5, s63, 0
	s_add_u32 s34, s4, 0
	s_addc_u32 s35, s5, 0
	global_load_dwordx4 v[80:83], v150, s[34:35]
	global_load_dwordx4 v[194:197], v193, s[34:35]
	s_mov_b64 s[10:11], s[34:35]
	s_add_u32 s10, s10, 1024
	s_addc_u32 s11, s11, 0
	global_load_dwordx4 v[144:147], v150, s[10:11]
	global_load_dwordx4 v[6:9], v193, s[10:11]
	s_mov_b64 s[34:35], s[10:11]
	s_add_u32 s10, s10, 1024
	s_addc_u32 s11, s11, 0
	s_mov_b32 s36, 0
	s_mov_b32 s14, 0
	s_mov_b32 s40, 0xffff0000
	s_waitcnt vmcnt(0)
	v_and_b32_e32 v182, 0xffff, v20
	v_lshrrev_b32_e32 v183, 16, v20
	v_and_b32_e32 v184, 0xffff, v21
	v_lshrrev_b32_e32 v185, 16, v21
	v_lshl_or_b32 v100, v22, 16, v182
	v_and_or_b32 v101, v22, s40, v183
	v_lshl_or_b32 v102, v23, 16, v184
	v_and_or_b32 v103, v23, s40, v185
	v_and_b32_e32 v182, 0xffff, v24
	v_lshrrev_b32_e32 v183, 16, v24
	v_and_b32_e32 v184, 0xffff, v25
	v_lshrrev_b32_e32 v185, 16, v25
	v_lshl_or_b32 v104, v26, 16, v182
	v_and_or_b32 v105, v26, s40, v183
	v_lshl_or_b32 v106, v27, 16, v184
	v_and_or_b32 v107, v27, s40, v185
	v_and_b32_e32 v182, 0xffff, v28
	v_lshrrev_b32_e32 v183, 16, v28
	v_and_b32_e32 v184, 0xffff, v29
	v_lshrrev_b32_e32 v185, 16, v29
	v_lshl_or_b32 v108, v30, 16, v182
	v_and_or_b32 v109, v30, s40, v183
	v_lshl_or_b32 v110, v31, 16, v184
	v_and_or_b32 v111, v31, s40, v185
	v_and_b32_e32 v182, 0xffff, v32
	v_lshrrev_b32_e32 v183, 16, v32
	v_and_b32_e32 v184, 0xffff, v33
	v_lshrrev_b32_e32 v185, 16, v33
	v_lshl_or_b32 v112, v34, 16, v182
	v_and_or_b32 v113, v34, s40, v183
	v_lshl_or_b32 v114, v35, 16, v184
	v_and_or_b32 v115, v35, s40, v185
	v_cmp_eq_u32_e32 vcc, 1, v174
	v_xor_b32_e32 v182, 0x80000000, v117
	v_xor_b32_e32 v183, 0x80000000, v119
	s_nop 1
	v_cndmask_b32_e32 v122, v182, v117, vcc
	v_cndmask_b32_e32 v123, v183, v119, vcc
.Lssm_tile_d0m1:
	s_waitcnt vmcnt(2)
	v_cndmask_b32_e64 v124, 0, v80, s[66:67]
	v_cndmask_b32_e64 v125, 0, v81, s[66:67]
	v_cndmask_b32_e64 v126, 0, v82, s[66:67]
	v_cndmask_b32_e64 v127, 0, v83, s[66:67]
	v_cndmask_b32_e64 v132, 0, v194, s[66:67]
	v_cndmask_b32_e64 v133, 0, v195, s[66:67]
	v_cndmask_b32_e64 v134, 0, v196, s[66:67]
	v_cndmask_b32_e64 v135, 0, v197, s[66:67]
	v_mfma_f32_32x32x16_bf16 v[16:31], v[124:127], v[84:87], 0
	v_cndmask_b32_e64 v128, 0, v194, s[68:69]
	v_cndmask_b32_e64 v129, 0, v195, s[68:69]
	v_cndmask_b32_e64 v130, 0, v196, s[68:69]
	v_cndmask_b32_e64 v131, 0, v197, s[68:69]
	v_mfma_f32_32x32x16_bf16 v[32:47], v[124:127], v[88:91], 0
	v_cndmask_b32_e64 v136, 0, v80, s[68:69]
	v_cndmask_b32_e64 v137, 0, v81, s[68:69]
	v_cndmask_b32_e64 v138, 0, v82, s[68:69]
	v_cndmask_b32_e64 v139, 0, v83, s[68:69]
	v_mfma_f32_32x32x16_bf16 v[48:63], v[132:135], v[84:87], 0
	v_mfma_f32_32x32x16_bf16 v[64:79], v[132:135], v[88:91], 0
	v_mfma_f32_32x32x16_bf16 v[16:31], v[128:131], v[92:95], v[16:31]
	v_mfma_f32_32x32x16_bf16 v[32:47], v[128:131], v[96:99], v[32:47]
	v_mfma_f32_32x32x16_bf16 v[48:63], v[136:139], v[92:95], v[48:63]
	v_mfma_f32_32x32x16_bf16 v[64:79], v[136:139], v[96:99], v[64:79]
	v_add_u32_e32 v171, s36, v155
	s_nop 11
	global_load_dwordx4 v[80:83], v150, s[10:11]
	global_load_dwordx4 v[194:197], v193, s[10:11]
	s_add_u32 s34, s34, 1024
	s_addc_u32 s35, s35, 0
	s_add_u32 s10, s10, 1024
	s_addc_u32 s11, s11, 0
	v_fmac_f32_e32 v16, v116, v120
	v_fmac_f32_e32 v32, v118, v121
	v_fmac_f32_dpp v16, v120, v122 quad_perm:[1,0,3,2] row_mask:0xf bank_mask:0xf
	v_fmac_f32_dpp v32, v121, v123 quad_perm:[1,0,3,2] row_mask:0xf bank_mask:0xf
	v_cvt_pk_bf16_f32 v148, v16, v32
	ds_write_b32 v151, v148
	v_fmac_f32_e32 v17, v116, v16
	v_fmac_f32_e32 v33, v118, v32
	v_fmac_f32_dpp v17, v16, v122 quad_perm:[1,0,3,2] row_mask:0xf bank_mask:0xf
	v_fmac_f32_dpp v33, v32, v123 quad_perm:[1,0,3,2] row_mask:0xf bank_mask:0xf
	v_cvt_pk_bf16_f32 v149, v17, v33
	ds_write_b32 v151, v149 offset:272
	v_fmac_f32_e32 v18, v116, v17
	v_fmac_f32_e32 v34, v118, v33
	v_fmac_f32_dpp v18, v17, v122 quad_perm:[1,0,3,2] row_mask:0xf bank_mask:0xf
	v_fmac_f32_dpp v34, v33, v123 quad_perm:[1,0,3,2] row_mask:0xf bank_mask:0xf
	v_cvt_pk_bf16_f32 v148, v18, v34
	ds_write_b32 v151, v148 offset:544
	v_fmac_f32_e32 v19, v116, v18
	v_fmac_f32_e32 v35, v118, v34
	v_fmac_f32_dpp v19, v18, v122 quad_perm:[1,0,3,2] row_mask:0xf bank_mask:0xf
	v_fmac_f32_dpp v35, v34, v123 quad_perm:[1,0,3,2] row_mask:0xf bank_mask:0xf
	v_cvt_pk_bf16_f32 v149, v19, v35
	ds_write_b32 v151, v149 offset:816
	v_fmac_f32_e32 v48, v116, v19
	v_fmac_f32_e32 v64, v118, v35
	v_fmac_f32_dpp v48, v19, v122 quad_perm:[1,0,3,2] row_mask:0xf bank_mask:0xf
	v_fmac_f32_dpp v64, v35, v123 quad_perm:[1,0,3,2] row_mask:0xf bank_mask:0xf
	v_cvt_pk_bf16_f32 v148, v48, v64
	ds_write_b32 v151, v148 offset:1088
	v_fmac_f32_e32 v49, v116, v48
	v_fmac_f32_e32 v65, v118, v64
	v_fmac_f32_dpp v49, v48, v122 quad_perm:[1,0,3,2] row_mask:0xf bank_mask:0xf
	v_fmac_f32_dpp v65, v64, v123 quad_perm:[1,0,3,2] row_mask:0xf bank_mask:0xf
	v_cvt_pk_bf16_f32 v149, v49, v65
	ds_write_b32 v151, v149 offset:1360
	v_fmac_f32_e32 v50, v116, v49
	v_fmac_f32_e32 v66, v118, v65
	v_fmac_f32_dpp v50, v49, v122 quad_perm:[1,0,3,2] row_mask:0xf bank_mask:0xf
	v_fmac_f32_dpp v66, v65, v123 quad_perm:[1,0,3,2] row_mask:0xf bank_mask:0xf
	v_cvt_pk_bf16_f32 v148, v50, v66
	ds_write_b32 v151, v148 offset:1632
	v_fmac_f32_e32 v51, v116, v50
	v_fmac_f32_e32 v67, v118, v66
	v_fmac_f32_dpp v51, v50, v122 quad_perm:[1,0,3,2] row_mask:0xf bank_mask:0xf
	v_fmac_f32_dpp v67, v66, v123 quad_perm:[1,0,3,2] row_mask:0xf bank_mask:0xf
	v_cvt_pk_bf16_f32 v149, v51, v67
	ds_write_b32 v151, v149 offset:1904
	v_fmac_f32_e32 v20, v116, v51
	v_fmac_f32_e32 v36, v118, v67
	v_fmac_f32_dpp v20, v51, v122 quad_perm:[1,0,3,2] row_mask:0xf bank_mask:0xf
	v_fmac_f32_dpp v36, v67, v123 quad_perm:[1,0,3,2] row_mask:0xf bank_mask:0xf
	v_cvt_pk_bf16_f32 v148, v20, v36
	ds_write_b32 v151, v148 offset:2176
	v_fmac_f32_e32 v21, v116, v20
	v_fmac_f32_e32 v37, v118, v36
	v_fmac_f32_dpp v21, v20, v122 quad_perm:[1,0,3,2] row_mask:0xf bank_mask:0xf
	v_fmac_f32_dpp v37, v36, v123 quad_perm:[1,0,3,2] row_mask:0xf bank_mask:0xf
	v_cvt_pk_bf16_f32 v149, v21, v37
	ds_write_b32 v151, v149 offset:2448
	v_fmac_f32_e32 v22, v116, v21
	v_fmac_f32_e32 v38, v118, v37
	v_fmac_f32_dpp v22, v21, v122 quad_perm:[1,0,3,2] row_mask:0xf bank_mask:0xf
	v_fmac_f32_dpp v38, v37, v123 quad_perm:[1,0,3,2] row_mask:0xf bank_mask:0xf
	v_cvt_pk_bf16_f32 v148, v22, v38
	ds_write_b32 v151, v148 offset:2720
	v_fmac_f32_e32 v23, v116, v22
	v_fmac_f32_e32 v39, v118, v38
	v_fmac_f32_dpp v23, v22, v122 quad_perm:[1,0,3,2] row_mask:0xf bank_mask:0xf
	v_fmac_f32_dpp v39, v38, v123 quad_perm:[1,0,3,2] row_mask:0xf bank_mask:0xf
	v_cvt_pk_bf16_f32 v149, v23, v39
	ds_write_b32 v151, v149 offset:2992
	v_fmac_f32_e32 v52, v116, v23
	v_fmac_f32_e32 v68, v118, v39
	v_fmac_f32_dpp v52, v23, v122 quad_perm:[1,0,3,2] row_mask:0xf bank_mask:0xf
	v_fmac_f32_dpp v68, v39, v123 quad_perm:[1,0,3,2] row_mask:0xf bank_mask:0xf
	v_cvt_pk_bf16_f32 v148, v52, v68
	ds_write_b32 v151, v148 offset:3264
	v_fmac_f32_e32 v53, v116, v52
	v_fmac_f32_e32 v69, v118, v68
	v_fmac_f32_dpp v53, v52, v122 quad_perm:[1,0,3,2] row_mask:0xf bank_mask:0xf
	v_fmac_f32_dpp v69, v68, v123 quad_perm:[1,0,3,2] row_mask:0xf bank_mask:0xf
	v_cvt_pk_bf16_f32 v149, v53, v69
	ds_write_b32 v151, v149 offset:3536
	v_fmac_f32_e32 v54, v116, v53
	v_fmac_f32_e32 v70, v118, v69
	v_fmac_f32_dpp v54, v53, v122 quad_perm:[1,0,3,2] row_mask:0xf bank_mask:0xf
	v_fmac_f32_dpp v70, v69, v123 quad_perm:[1,0,3,2] row_mask:0xf bank_mask:0xf
	v_cvt_pk_bf16_f32 v148, v54, v70
	ds_write_b32 v151, v148 offset:3808
	v_fmac_f32_e32 v55, v116, v54
	v_fmac_f32_e32 v71, v118, v70
	v_fmac_f32_dpp v55, v54, v122 quad_perm:[1,0,3,2] row_mask:0xf bank_mask:0xf
	v_fmac_f32_dpp v71, v70, v123 quad_perm:[1,0,3,2] row_mask:0xf bank_mask:0xf
	v_cvt_pk_bf16_f32 v149, v55, v71
	ds_write_b32 v151, v149 offset:4080
	v_fmac_f32_e32 v24, v116, v55
	v_fmac_f32_e32 v40, v118, v71
	v_fmac_f32_dpp v24, v55, v122 quad_perm:[1,0,3,2] row_mask:0xf bank_mask:0xf
	v_fmac_f32_dpp v40, v71, v123 quad_perm:[1,0,3,2] row_mask:0xf bank_mask:0xf
	v_cvt_pk_bf16_f32 v148, v24, v40
	ds_write_b32 v151, v148 offset:4352
	v_fmac_f32_e32 v25, v116, v24
	v_fmac_f32_e32 v41, v118, v40
	v_fmac_f32_dpp v25, v24, v122 quad_perm:[1,0,3,2] row_mask:0xf bank_mask:0xf
	v_fmac_f32_dpp v41, v40, v123 quad_perm:[1,0,3,2] row_mask:0xf bank_mask:0xf
	v_cvt_pk_bf16_f32 v149, v25, v41
	ds_write_b32 v151, v149 offset:4624
	v_fmac_f32_e32 v26, v116, v25
	v_fmac_f32_e32 v42, v118, v41
	v_fmac_f32_dpp v26, v25, v122 quad_perm:[1,0,3,2] row_mask:0xf bank_mask:0xf
	v_fmac_f32_dpp v42, v41, v123 quad_perm:[1,0,3,2] row_mask:0xf bank_mask:0xf
	v_cvt_pk_bf16_f32 v148, v26, v42
	ds_write_b32 v151, v148 offset:4896
	v_fmac_f32_e32 v27, v116, v26
	v_fmac_f32_e32 v43, v118, v42
	v_fmac_f32_dpp v27, v26, v122 quad_perm:[1,0,3,2] row_mask:0xf bank_mask:0xf
	v_fmac_f32_dpp v43, v42, v123 quad_perm:[1,0,3,2] row_mask:0xf bank_mask:0xf
	v_cvt_pk_bf16_f32 v149, v27, v43
	ds_write_b32 v151, v149 offset:5168
	v_fmac_f32_e32 v56, v116, v27
	v_fmac_f32_e32 v72, v118, v43
	v_fmac_f32_dpp v56, v27, v122 quad_perm:[1,0,3,2] row_mask:0xf bank_mask:0xf
	v_fmac_f32_dpp v72, v43, v123 quad_perm:[1,0,3,2] row_mask:0xf bank_mask:0xf
	v_cvt_pk_bf16_f32 v148, v56, v72
	ds_write_b32 v151, v148 offset:5440
	v_fmac_f32_e32 v57, v116, v56
	v_fmac_f32_e32 v73, v118, v72
	v_fmac_f32_dpp v57, v56, v122 quad_perm:[1,0,3,2] row_mask:0xf bank_mask:0xf
	v_fmac_f32_dpp v73, v72, v123 quad_perm:[1,0,3,2] row_mask:0xf bank_mask:0xf
	v_cvt_pk_bf16_f32 v149, v57, v73
	ds_write_b32 v151, v149 offset:5712
	v_fmac_f32_e32 v58, v116, v57
	v_fmac_f32_e32 v74, v118, v73
	v_fmac_f32_dpp v58, v57, v122 quad_perm:[1,0,3,2] row_mask:0xf bank_mask:0xf
	v_fmac_f32_dpp v74, v73, v123 quad_perm:[1,0,3,2] row_mask:0xf bank_mask:0xf
	v_cvt_pk_bf16_f32 v148, v58, v74
	ds_write_b32 v151, v148 offset:5984
	v_fmac_f32_e32 v59, v116, v58
	v_fmac_f32_e32 v75, v118, v74
	v_fmac_f32_dpp v59, v58, v122 quad_perm:[1,0,3,2] row_mask:0xf bank_mask:0xf
	v_fmac_f32_dpp v75, v74, v123 quad_perm:[1,0,3,2] row_mask:0xf bank_mask:0xf
	v_cvt_pk_bf16_f32 v149, v59, v75
	ds_write_b32 v151, v149 offset:6256
	v_fmac_f32_e32 v28, v116, v59
	v_fmac_f32_e32 v44, v118, v75
	v_fmac_f32_dpp v28, v59, v122 quad_perm:[1,0,3,2] row_mask:0xf bank_mask:0xf
	v_fmac_f32_dpp v44, v75, v123 quad_perm:[1,0,3,2] row_mask:0xf bank_mask:0xf
	v_cvt_pk_bf16_f32 v148, v28, v44
	ds_write_b32 v151, v148 offset:6528
	v_fmac_f32_e32 v29, v116, v28
	v_fmac_f32_e32 v45, v118, v44
	v_fmac_f32_dpp v29, v28, v122 quad_perm:[1,0,3,2] row_mask:0xf bank_mask:0xf
	v_fmac_f32_dpp v45, v44, v123 quad_perm:[1,0,3,2] row_mask:0xf bank_mask:0xf
	v_cvt_pk_bf16_f32 v149, v29, v45
	ds_write_b32 v151, v149 offset:6800
	v_fmac_f32_e32 v30, v116, v29
	v_fmac_f32_e32 v46, v118, v45
	v_fmac_f32_dpp v30, v29, v122 quad_perm:[1,0,3,2] row_mask:0xf bank_mask:0xf
	v_fmac_f32_dpp v46, v45, v123 quad_perm:[1,0,3,2] row_mask:0xf bank_mask:0xf
	v_cvt_pk_bf16_f32 v148, v30, v46
	ds_write_b32 v151, v148 offset:7072
	v_fmac_f32_e32 v31, v116, v30
	v_fmac_f32_e32 v47, v118, v46
	v_fmac_f32_dpp v31, v30, v122 quad_perm:[1,0,3,2] row_mask:0xf bank_mask:0xf
	v_fmac_f32_dpp v47, v46, v123 quad_perm:[1,0,3,2] row_mask:0xf bank_mask:0xf
	v_cvt_pk_bf16_f32 v149, v31, v47
	ds_write_b32 v151, v149 offset:7344
	v_fmac_f32_e32 v60, v116, v31
	v_fmac_f32_e32 v76, v118, v47
	v_fmac_f32_dpp v60, v31, v122 quad_perm:[1,0,3,2] row_mask:0xf bank_mask:0xf
	v_fmac_f32_dpp v76, v47, v123 quad_perm:[1,0,3,2] row_mask:0xf bank_mask:0xf
	v_cvt_pk_bf16_f32 v148, v60, v76
	ds_write_b32 v151, v148 offset:7616
	v_fmac_f32_e32 v61, v116, v60
	v_fmac_f32_e32 v77, v118, v76
	v_fmac_f32_dpp v61, v60, v122 quad_perm:[1,0,3,2] row_mask:0xf bank_mask:0xf
	v_fmac_f32_dpp v77, v76, v123 quad_perm:[1,0,3,2] row_mask:0xf bank_mask:0xf
	v_cvt_pk_bf16_f32 v149, v61, v77
	ds_write_b32 v151, v149 offset:7888
	v_fmac_f32_e32 v62, v116, v61
	v_fmac_f32_e32 v78, v118, v77
	v_fmac_f32_dpp v62, v61, v122 quad_perm:[1,0,3,2] row_mask:0xf bank_mask:0xf
	v_fmac_f32_dpp v78, v77, v123 quad_perm:[1,0,3,2] row_mask:0xf bank_mask:0xf
	v_cvt_pk_bf16_f32 v148, v62, v78
	ds_write_b32 v151, v148 offset:8160
	v_fmac_f32_e32 v63, v116, v62
	v_fmac_f32_e32 v79, v118, v78
	v_fmac_f32_dpp v63, v62, v122 quad_perm:[1,0,3,2] row_mask:0xf bank_mask:0xf
	v_fmac_f32_dpp v79, v78, v123 quad_perm:[1,0,3,2] row_mask:0xf bank_mask:0xf
	v_cvt_pk_bf16_f32 v149, v63, v79
	ds_write_b32 v151, v149 offset:8432
	v_mov_b32_e32 v120, v63
	v_mov_b32_e32 v121, v79
	ds_read_b128 v[124:127], v152
	ds_read_b128 v[128:131], v152 offset:64
	ds_read_b128 v[132:135], v152 offset:128
	ds_read_b128 v[136:139], v152 offset:192
	s_waitcnt lgkmcnt(3)
	v_mfma_f32_16x16x32_bf16 v[140:143], v[100:103], v[124:127], 0
	s_waitcnt lgkmcnt(2)
	v_mfma_f32_16x16x32_bf16 v[140:143], v[104:107], v[128:131], v[140:143]
	s_waitcnt lgkmcnt(1)
	v_mfma_f32_16x16x32_bf16 v[140:143], v[108:111], v[132:135], v[140:143]
	s_waitcnt lgkmcnt(0)
	v_mfma_f32_16x16x32_bf16 v[140:143], v[112:115], v[136:139], v[140:143]
	s_nop 9
	v_cvt_pk_bf16_f32 v182, v140, v141
	v_cvt_pk_bf16_f32 v183, v142, v143
	ds_write_b64 v171, v[182:183]
	ds_read_b128 v[124:127], v152 offset:4352
	ds_read_b128 v[128:131], v152 offset:4416
	ds_read_b128 v[132:135], v152 offset:4480
	ds_read_b128 v[136:139], v152 offset:4544
	s_waitcnt lgkmcnt(3)
	v_mfma_f32_16x16x32_bf16 v[140:143], v[100:103], v[124:127], 0
	s_waitcnt lgkmcnt(2)
	v_mfma_f32_16x16x32_bf16 v[140:143], v[104:107], v[128:131], v[140:143]
	s_waitcnt lgkmcnt(1)
	v_mfma_f32_16x16x32_bf16 v[140:143], v[108:111], v[132:135], v[140:143]
	s_waitcnt lgkmcnt(0)
	v_mfma_f32_16x16x32_bf16 v[140:143], v[112:115], v[136:139], v[140:143]
	s_nop 9
	v_cvt_pk_bf16_f32 v182, v140, v141
	v_cvt_pk_bf16_f32 v183, v142, v143
	ds_write_b64 v171, v[182:183] offset:512
	s_add_u32 s36, s36, 1024
	s_waitcnt vmcnt(2)
	v_cndmask_b32_e64 v124, 0, v144, s[66:67]
	v_cndmask_b32_e64 v125, 0, v145, s[66:67]
	v_cndmask_b32_e64 v126, 0, v146, s[66:67]
	v_cndmask_b32_e64 v127, 0, v147, s[66:67]
	v_cndmask_b32_e64 v132, 0, v6, s[66:67]
	v_cndmask_b32_e64 v133, 0, v7, s[66:67]
	v_cndmask_b32_e64 v134, 0, v8, s[66:67]
	v_cndmask_b32_e64 v135, 0, v9, s[66:67]
	v_mfma_f32_32x32x16_bf16 v[16:31], v[124:127], v[84:87], 0
	v_cndmask_b32_e64 v128, 0, v6, s[68:69]
	v_cndmask_b32_e64 v129, 0, v7, s[68:69]
	v_cndmask_b32_e64 v130, 0, v8, s[68:69]
	v_cndmask_b32_e64 v131, 0, v9, s[68:69]
	v_mfma_f32_32x32x16_bf16 v[32:47], v[124:127], v[88:91], 0
	v_cndmask_b32_e64 v136, 0, v144, s[68:69]
	v_cndmask_b32_e64 v137, 0, v145, s[68:69]
	v_cndmask_b32_e64 v138, 0, v146, s[68:69]
	v_cndmask_b32_e64 v139, 0, v147, s[68:69]
	v_mfma_f32_32x32x16_bf16 v[48:63], v[132:135], v[84:87], 0
	v_mfma_f32_32x32x16_bf16 v[64:79], v[132:135], v[88:91], 0
	v_mfma_f32_32x32x16_bf16 v[16:31], v[128:131], v[92:95], v[16:31]
	v_mfma_f32_32x32x16_bf16 v[32:47], v[128:131], v[96:99], v[32:47]
	v_mfma_f32_32x32x16_bf16 v[48:63], v[136:139], v[92:95], v[48:63]
	v_mfma_f32_32x32x16_bf16 v[64:79], v[136:139], v[96:99], v[64:79]
	v_add_u32_e32 v171, s36, v155
	s_nop 11
	global_load_dwordx4 v[144:147], v150, s[10:11]
	global_load_dwordx4 v[6:9], v193, s[10:11]
	s_add_u32 s34, s34, 1024
	s_addc_u32 s35, s35, 0
	s_add_u32 s10, s10, 1024
	s_addc_u32 s11, s11, 0
	v_fmac_f32_e32 v16, v116, v120
	v_fmac_f32_e32 v32, v118, v121
	v_fmac_f32_dpp v16, v120, v122 quad_perm:[1,0,3,2] row_mask:0xf bank_mask:0xf
	v_fmac_f32_dpp v32, v121, v123 quad_perm:[1,0,3,2] row_mask:0xf bank_mask:0xf
	v_cvt_pk_bf16_f32 v148, v16, v32
	ds_write_b32 v151, v148
	v_fmac_f32_e32 v17, v116, v16
	v_fmac_f32_e32 v33, v118, v32
	v_fmac_f32_dpp v17, v16, v122 quad_perm:[1,0,3,2] row_mask:0xf bank_mask:0xf
	v_fmac_f32_dpp v33, v32, v123 quad_perm:[1,0,3,2] row_mask:0xf bank_mask:0xf
	v_cvt_pk_bf16_f32 v149, v17, v33
	ds_write_b32 v151, v149 offset:272
	v_fmac_f32_e32 v18, v116, v17
	v_fmac_f32_e32 v34, v118, v33
	v_fmac_f32_dpp v18, v17, v122 quad_perm:[1,0,3,2] row_mask:0xf bank_mask:0xf
	v_fmac_f32_dpp v34, v33, v123 quad_perm:[1,0,3,2] row_mask:0xf bank_mask:0xf
	v_cvt_pk_bf16_f32 v148, v18, v34
	ds_write_b32 v151, v148 offset:544
	v_fmac_f32_e32 v19, v116, v18
	v_fmac_f32_e32 v35, v118, v34
	v_fmac_f32_dpp v19, v18, v122 quad_perm:[1,0,3,2] row_mask:0xf bank_mask:0xf
	v_fmac_f32_dpp v35, v34, v123 quad_perm:[1,0,3,2] row_mask:0xf bank_mask:0xf
	v_cvt_pk_bf16_f32 v149, v19, v35
	ds_write_b32 v151, v149 offset:816
	v_fmac_f32_e32 v48, v116, v19
	v_fmac_f32_e32 v64, v118, v35
	v_fmac_f32_dpp v48, v19, v122 quad_perm:[1,0,3,2] row_mask:0xf bank_mask:0xf
	v_fmac_f32_dpp v64, v35, v123 quad_perm:[1,0,3,2] row_mask:0xf bank_mask:0xf
	v_cvt_pk_bf16_f32 v148, v48, v64
	ds_write_b32 v151, v148 offset:1088
	v_fmac_f32_e32 v49, v116, v48
	v_fmac_f32_e32 v65, v118, v64
	v_fmac_f32_dpp v49, v48, v122 quad_perm:[1,0,3,2] row_mask:0xf bank_mask:0xf
	v_fmac_f32_dpp v65, v64, v123 quad_perm:[1,0,3,2] row_mask:0xf bank_mask:0xf
	v_cvt_pk_bf16_f32 v149, v49, v65
	ds_write_b32 v151, v149 offset:1360
	v_fmac_f32_e32 v50, v116, v49
	v_fmac_f32_e32 v66, v118, v65
	v_fmac_f32_dpp v50, v49, v122 quad_perm:[1,0,3,2] row_mask:0xf bank_mask:0xf
	v_fmac_f32_dpp v66, v65, v123 quad_perm:[1,0,3,2] row_mask:0xf bank_mask:0xf
	v_cvt_pk_bf16_f32 v148, v50, v66
	ds_write_b32 v151, v148 offset:1632
	v_fmac_f32_e32 v51, v116, v50
	v_fmac_f32_e32 v67, v118, v66
	v_fmac_f32_dpp v51, v50, v122 quad_perm:[1,0,3,2] row_mask:0xf bank_mask:0xf
	v_fmac_f32_dpp v67, v66, v123 quad_perm:[1,0,3,2] row_mask:0xf bank_mask:0xf
	v_cvt_pk_bf16_f32 v149, v51, v67
	ds_write_b32 v151, v149 offset:1904
	v_fmac_f32_e32 v20, v116, v51
	v_fmac_f32_e32 v36, v118, v67
	v_fmac_f32_dpp v20, v51, v122 quad_perm:[1,0,3,2] row_mask:0xf bank_mask:0xf
	v_fmac_f32_dpp v36, v67, v123 quad_perm:[1,0,3,2] row_mask:0xf bank_mask:0xf
	v_cvt_pk_bf16_f32 v148, v20, v36
	ds_write_b32 v151, v148 offset:2176
	v_fmac_f32_e32 v21, v116, v20
	v_fmac_f32_e32 v37, v118, v36
	v_fmac_f32_dpp v21, v20, v122 quad_perm:[1,0,3,2] row_mask:0xf bank_mask:0xf
	v_fmac_f32_dpp v37, v36, v123 quad_perm:[1,0,3,2] row_mask:0xf bank_mask:0xf
	v_cvt_pk_bf16_f32 v149, v21, v37
	ds_write_b32 v151, v149 offset:2448
	v_fmac_f32_e32 v22, v116, v21
	v_fmac_f32_e32 v38, v118, v37
	v_fmac_f32_dpp v22, v21, v122 quad_perm:[1,0,3,2] row_mask:0xf bank_mask:0xf
	v_fmac_f32_dpp v38, v37, v123 quad_perm:[1,0,3,2] row_mask:0xf bank_mask:0xf
	v_cvt_pk_bf16_f32 v148, v22, v38
	ds_write_b32 v151, v148 offset:2720
	v_fmac_f32_e32 v23, v116, v22
	v_fmac_f32_e32 v39, v118, v38
	v_fmac_f32_dpp v23, v22, v122 quad_perm:[1,0,3,2] row_mask:0xf bank_mask:0xf
	v_fmac_f32_dpp v39, v38, v123 quad_perm:[1,0,3,2] row_mask:0xf bank_mask:0xf
	v_cvt_pk_bf16_f32 v149, v23, v39
	ds_write_b32 v151, v149 offset:2992
	v_fmac_f32_e32 v52, v116, v23
	v_fmac_f32_e32 v68, v118, v39
	v_fmac_f32_dpp v52, v23, v122 quad_perm:[1,0,3,2] row_mask:0xf bank_mask:0xf
	v_fmac_f32_dpp v68, v39, v123 quad_perm:[1,0,3,2] row_mask:0xf bank_mask:0xf
	v_cvt_pk_bf16_f32 v148, v52, v68
	ds_write_b32 v151, v148 offset:3264
	v_fmac_f32_e32 v53, v116, v52
	v_fmac_f32_e32 v69, v118, v68
	v_fmac_f32_dpp v53, v52, v122 quad_perm:[1,0,3,2] row_mask:0xf bank_mask:0xf
	v_fmac_f32_dpp v69, v68, v123 quad_perm:[1,0,3,2] row_mask:0xf bank_mask:0xf
	v_cvt_pk_bf16_f32 v149, v53, v69
	ds_write_b32 v151, v149 offset:3536
	v_fmac_f32_e32 v54, v116, v53
	v_fmac_f32_e32 v70, v118, v69
	v_fmac_f32_dpp v54, v53, v122 quad_perm:[1,0,3,2] row_mask:0xf bank_mask:0xf
	v_fmac_f32_dpp v70, v69, v123 quad_perm:[1,0,3,2] row_mask:0xf bank_mask:0xf
	v_cvt_pk_bf16_f32 v148, v54, v70
	ds_write_b32 v151, v148 offset:3808
	v_fmac_f32_e32 v55, v116, v54
	v_fmac_f32_e32 v71, v118, v70
	v_fmac_f32_dpp v55, v54, v122 quad_perm:[1,0,3,2] row_mask:0xf bank_mask:0xf
	v_fmac_f32_dpp v71, v70, v123 quad_perm:[1,0,3,2] row_mask:0xf bank_mask:0xf
	v_cvt_pk_bf16_f32 v149, v55, v71
	ds_write_b32 v151, v149 offset:4080
	v_fmac_f32_e32 v24, v116, v55
	v_fmac_f32_e32 v40, v118, v71
	v_fmac_f32_dpp v24, v55, v122 quad_perm:[1,0,3,2] row_mask:0xf bank_mask:0xf
	v_fmac_f32_dpp v40, v71, v123 quad_perm:[1,0,3,2] row_mask:0xf bank_mask:0xf
	v_cvt_pk_bf16_f32 v148, v24, v40
	ds_write_b32 v151, v148 offset:4352
	v_fmac_f32_e32 v25, v116, v24
	v_fmac_f32_e32 v41, v118, v40
	v_fmac_f32_dpp v25, v24, v122 quad_perm:[1,0,3,2] row_mask:0xf bank_mask:0xf
	v_fmac_f32_dpp v41, v40, v123 quad_perm:[1,0,3,2] row_mask:0xf bank_mask:0xf
	v_cvt_pk_bf16_f32 v149, v25, v41
	ds_write_b32 v151, v149 offset:4624
	v_fmac_f32_e32 v26, v116, v25
	v_fmac_f32_e32 v42, v118, v41
	v_fmac_f32_dpp v26, v25, v122 quad_perm:[1,0,3,2] row_mask:0xf bank_mask:0xf
	v_fmac_f32_dpp v42, v41, v123 quad_perm:[1,0,3,2] row_mask:0xf bank_mask:0xf
	v_cvt_pk_bf16_f32 v148, v26, v42
	ds_write_b32 v151, v148 offset:4896
	v_fmac_f32_e32 v27, v116, v26
	v_fmac_f32_e32 v43, v118, v42
	v_fmac_f32_dpp v27, v26, v122 quad_perm:[1,0,3,2] row_mask:0xf bank_mask:0xf
	v_fmac_f32_dpp v43, v42, v123 quad_perm:[1,0,3,2] row_mask:0xf bank_mask:0xf
	v_cvt_pk_bf16_f32 v149, v27, v43
	ds_write_b32 v151, v149 offset:5168
	v_fmac_f32_e32 v56, v116, v27
	v_fmac_f32_e32 v72, v118, v43
	v_fmac_f32_dpp v56, v27, v122 quad_perm:[1,0,3,2] row_mask:0xf bank_mask:0xf
	v_fmac_f32_dpp v72, v43, v123 quad_perm:[1,0,3,2] row_mask:0xf bank_mask:0xf
	v_cvt_pk_bf16_f32 v148, v56, v72
	ds_write_b32 v151, v148 offset:5440
	v_fmac_f32_e32 v57, v116, v56
	v_fmac_f32_e32 v73, v118, v72
	v_fmac_f32_dpp v57, v56, v122 quad_perm:[1,0,3,2] row_mask:0xf bank_mask:0xf
	v_fmac_f32_dpp v73, v72, v123 quad_perm:[1,0,3,2] row_mask:0xf bank_mask:0xf
	v_cvt_pk_bf16_f32 v149, v57, v73
	ds_write_b32 v151, v149 offset:5712
	v_fmac_f32_e32 v58, v116, v57
	v_fmac_f32_e32 v74, v118, v73
	v_fmac_f32_dpp v58, v57, v122 quad_perm:[1,0,3,2] row_mask:0xf bank_mask:0xf
	v_fmac_f32_dpp v74, v73, v123 quad_perm:[1,0,3,2] row_mask:0xf bank_mask:0xf
	v_cvt_pk_bf16_f32 v148, v58, v74
	ds_write_b32 v151, v148 offset:5984
	v_fmac_f32_e32 v59, v116, v58
	v_fmac_f32_e32 v75, v118, v74
	v_fmac_f32_dpp v59, v58, v122 quad_perm:[1,0,3,2] row_mask:0xf bank_mask:0xf
	v_fmac_f32_dpp v75, v74, v123 quad_perm:[1,0,3,2] row_mask:0xf bank_mask:0xf
	v_cvt_pk_bf16_f32 v149, v59, v75
	ds_write_b32 v151, v149 offset:6256
	v_fmac_f32_e32 v28, v116, v59
	v_fmac_f32_e32 v44, v118, v75
	v_fmac_f32_dpp v28, v59, v122 quad_perm:[1,0,3,2] row_mask:0xf bank_mask:0xf
	v_fmac_f32_dpp v44, v75, v123 quad_perm:[1,0,3,2] row_mask:0xf bank_mask:0xf
	v_cvt_pk_bf16_f32 v148, v28, v44
	ds_write_b32 v151, v148 offset:6528
	v_fmac_f32_e32 v29, v116, v28
	v_fmac_f32_e32 v45, v118, v44
	v_fmac_f32_dpp v29, v28, v122 quad_perm:[1,0,3,2] row_mask:0xf bank_mask:0xf
	v_fmac_f32_dpp v45, v44, v123 quad_perm:[1,0,3,2] row_mask:0xf bank_mask:0xf
	v_cvt_pk_bf16_f32 v149, v29, v45
	ds_write_b32 v151, v149 offset:6800
	v_fmac_f32_e32 v30, v116, v29
	v_fmac_f32_e32 v46, v118, v45
	v_fmac_f32_dpp v30, v29, v122 quad_perm:[1,0,3,2] row_mask:0xf bank_mask:0xf
	v_fmac_f32_dpp v46, v45, v123 quad_perm:[1,0,3,2] row_mask:0xf bank_mask:0xf
	v_cvt_pk_bf16_f32 v148, v30, v46
	ds_write_b32 v151, v148 offset:7072
	v_fmac_f32_e32 v31, v116, v30
	v_fmac_f32_e32 v47, v118, v46
	v_fmac_f32_dpp v31, v30, v122 quad_perm:[1,0,3,2] row_mask:0xf bank_mask:0xf
	v_fmac_f32_dpp v47, v46, v123 quad_perm:[1,0,3,2] row_mask:0xf bank_mask:0xf
	v_cvt_pk_bf16_f32 v149, v31, v47
	ds_write_b32 v151, v149 offset:7344
	v_fmac_f32_e32 v60, v116, v31
	v_fmac_f32_e32 v76, v118, v47
	v_fmac_f32_dpp v60, v31, v122 quad_perm:[1,0,3,2] row_mask:0xf bank_mask:0xf
	v_fmac_f32_dpp v76, v47, v123 quad_perm:[1,0,3,2] row_mask:0xf bank_mask:0xf
	v_cvt_pk_bf16_f32 v148, v60, v76
	ds_write_b32 v151, v148 offset:7616
	v_fmac_f32_e32 v61, v116, v60
	v_fmac_f32_e32 v77, v118, v76
	v_fmac_f32_dpp v61, v60, v122 quad_perm:[1,0,3,2] row_mask:0xf bank_mask:0xf
	v_fmac_f32_dpp v77, v76, v123 quad_perm:[1,0,3,2] row_mask:0xf bank_mask:0xf
	v_cvt_pk_bf16_f32 v149, v61, v77
	ds_write_b32 v151, v149 offset:7888
	v_fmac_f32_e32 v62, v116, v61
	v_fmac_f32_e32 v78, v118, v77
	v_fmac_f32_dpp v62, v61, v122 quad_perm:[1,0,3,2] row_mask:0xf bank_mask:0xf
	v_fmac_f32_dpp v78, v77, v123 quad_perm:[1,0,3,2] row_mask:0xf bank_mask:0xf
	v_cvt_pk_bf16_f32 v148, v62, v78
	ds_write_b32 v151, v148 offset:8160
	v_fmac_f32_e32 v63, v116, v62
	v_fmac_f32_e32 v79, v118, v78
	v_fmac_f32_dpp v63, v62, v122 quad_perm:[1,0,3,2] row_mask:0xf bank_mask:0xf
	v_fmac_f32_dpp v79, v78, v123 quad_perm:[1,0,3,2] row_mask:0xf bank_mask:0xf
	v_cvt_pk_bf16_f32 v149, v63, v79
	ds_write_b32 v151, v149 offset:8432
	v_mov_b32_e32 v120, v63
	v_mov_b32_e32 v121, v79
	ds_read_b128 v[124:127], v152
	ds_read_b128 v[128:131], v152 offset:64
	ds_read_b128 v[132:135], v152 offset:128
	ds_read_b128 v[136:139], v152 offset:192
	s_waitcnt lgkmcnt(3)
	v_mfma_f32_16x16x32_bf16 v[140:143], v[100:103], v[124:127], 0
	s_waitcnt lgkmcnt(2)
	v_mfma_f32_16x16x32_bf16 v[140:143], v[104:107], v[128:131], v[140:143]
	s_waitcnt lgkmcnt(1)
	v_mfma_f32_16x16x32_bf16 v[140:143], v[108:111], v[132:135], v[140:143]
	s_waitcnt lgkmcnt(0)
	v_mfma_f32_16x16x32_bf16 v[140:143], v[112:115], v[136:139], v[140:143]
	s_nop 9
	v_cvt_pk_bf16_f32 v182, v140, v141
	v_cvt_pk_bf16_f32 v183, v142, v143
	ds_write_b64 v171, v[182:183]
	ds_read_b128 v[124:127], v152 offset:4352
	ds_read_b128 v[128:131], v152 offset:4416
	ds_read_b128 v[132:135], v152 offset:4480
	ds_read_b128 v[136:139], v152 offset:4544
	s_waitcnt lgkmcnt(3)
	v_mfma_f32_16x16x32_bf16 v[140:143], v[100:103], v[124:127], 0
	s_waitcnt lgkmcnt(2)
	v_mfma_f32_16x16x32_bf16 v[140:143], v[104:107], v[128:131], v[140:143]
	s_waitcnt lgkmcnt(1)
	v_mfma_f32_16x16x32_bf16 v[140:143], v[108:111], v[132:135], v[140:143]
	s_waitcnt lgkmcnt(0)
	v_mfma_f32_16x16x32_bf16 v[140:143], v[112:115], v[136:139], v[140:143]
	s_nop 9
	v_cvt_pk_bf16_f32 v182, v140, v141
	v_cvt_pk_bf16_f32 v183, v142, v143
	ds_write_b64 v171, v[182:183] offset:512
	s_add_u32 s36, s36, 1024
	s_add_u32 s14, s14, 2
	s_cmp_lt_u32 s14, 8
	s_cbranch_scc1 .Lssm_tile_d0m1
	s_add_u32 s30, s30, 0x8000000
	s_add_u32 s16, s60, s30
	s_addc_u32 s17, s61, 0
	global_store_dword v180, v120, s[16:17]
	global_store_dword v180, v121, s[16:17] offset:64
	s_waitcnt vmcnt(0) lgkmcnt(0)
	s_add_u32 s28, s24, 64
	s_lshl_b32 s29, s28, 13
	s_add_u32 s29, s29, 0x200000
	s_add_u32 s10, s62, s29
	s_addc_u32 s11, s63, 0
	global_load_dwordx4 v[84:87], v177, s[10:11]
	global_load_dwordx4 v[88:91], v177, s[10:11] offset:2048
	s_add_u32 s12, s10, 0x1000
	s_addc_u32 s13, s11, 0
	global_load_dwordx4 v[92:95], v177, s[12:13]
	global_load_dwordx4 v[96:99], v177, s[12:13] offset:2048
	s_lshl_b32 s29, s28, 12
	s_add_u32 s29, s29, 0x300000
	s_add_u32 s16, s62, s29
	s_addc_u32 s17, s63, 0
	global_load_dwordx2 v[20:21], v178, s[16:17]
	global_load_dwordx2 v[22:23], v178, s[16:17] offset:1024
	global_load_dwordx2 v[24:25], v178, s[16:17] offset:512
	global_load_dwordx2 v[26:27], v178, s[16:17] offset:1536
	global_load_dwordx2 v[28:29], v178, s[16:17] offset:2048
	global_load_dwordx2 v[30:31], v178, s[16:17] offset:3072
	global_load_dwordx2 v[32:33], v178, s[16:17] offset:2560
	global_load_dwordx2 v[34:35], v178, s[16:17] offset:3584
	s_lshl_b32 s29, s28, 9
	s_add_u32 s29, s29, 0x100000
	s_add_u32 s18, s62, s29
	s_addc_u32 s19, s63, 0
	global_load_dwordx2 v[116:117], v179, s[18:19]
	global_load_dwordx2 v[118:119], v179, s[18:19] offset:128
	s_lshl_b32 s30, s23, 1
	s_add_u32 s30, s30, 1
	s_lshl_b32 s30, s30, 15
	s_lshl_b32 s31, s24, 8
	s_add_u32 s30, s30, s31
	v_mov_b32_e32 v120, 0
	v_mov_b32_e32 v121, 0
	v_readlane_b32 s34, v254, 28
	v_readlane_b32 s35, v254, 29
	s_nop 3
	s_lshl_b32 s31, s24, 6
	s_add_u32 s34, s34, s31
	s_addc_u32 s35, s35, 0
	global_load_dwordx4 v[164:167], v181, s[34:35]
	s_lshl_b32 s31, s25, 5
	s_lshl_b32 s29, s24, 19
	s_add_u32 s31, s31, s29
	s_add_u32 s31, s31, 0x16800000
	s_add_u32 s4, s62, s31
	s_addc_u32 s5, s63, 0
	s_lshl_b32 s31, s25, 11
	s_lshl_b32 s29, s24, 5
	s_add_u32 s31, s31, s29
	s_add_u32 s31, s31, 0x14800000
	s_add_u32 s6, s62, s31
	s_addc_u32 s7, s63, 0
	s_add_u32 s34, s4, 7168
	s_addc_u32 s35, s5, 0
	global_load_dwordx4 v[80:83], v150, s[34:35]
	global_load_dwordx4 v[194:197], v193, s[34:35]
	s_mov_b64 s[10:11], s[34:35]
	s_sub_u32 s10, s10, 1024
	s_subb_u32 s11, s11, 0
	global_load_dwordx4 v[144:147], v150, s[10:11]
	global_load_dwordx4 v[6:9], v193, s[10:11]
	s_mov_b64 s[34:35], s[10:11]
	s_sub_u32 s10, s10, 1024
	s_subb_u32 s11, s11, 0
	s_add_u32 s12, s6, 458752
	s_addc_u32 s13, s7, 0
	s_mov_b32 s36, 7168
	s_mov_b32 s14, 0
	s_mov_b32 s40, 0xffff0000
	s_waitcnt vmcnt(0)
	v_and_b32_e32 v182, 0xffff, v20
	v_lshrrev_b32_e32 v183, 16, v20
	v_and_b32_e32 v184, 0xffff, v21
	v_lshrrev_b32_e32 v185, 16, v21
	v_lshl_or_b32 v100, v22, 16, v182
	v_and_or_b32 v101, v22, s40, v183
	v_lshl_or_b32 v102, v23, 16, v184
	v_and_or_b32 v103, v23, s40, v185
	v_and_b32_e32 v182, 0xffff, v24
	v_lshrrev_b32_e32 v183, 16, v24
	v_and_b32_e32 v184, 0xffff, v25
	v_lshrrev_b32_e32 v185, 16, v25
	v_lshl_or_b32 v104, v26, 16, v182
	v_and_or_b32 v105, v26, s40, v183
	v_lshl_or_b32 v106, v27, 16, v184
	v_and_or_b32 v107, v27, s40, v185
	v_and_b32_e32 v182, 0xffff, v28
	v_lshrrev_b32_e32 v183, 16, v28
	v_and_b32_e32 v184, 0xffff, v29
	v_lshrrev_b32_e32 v185, 16, v29
	v_lshl_or_b32 v108, v30, 16, v182
	v_and_or_b32 v109, v30, s40, v183
	v_lshl_or_b32 v110, v31, 16, v184
	v_and_or_b32 v111, v31, s40, v185
	v_and_b32_e32 v182, 0xffff, v32
	v_lshrrev_b32_e32 v183, 16, v32
	v_and_b32_e32 v184, 0xffff, v33
	v_lshrrev_b32_e32 v185, 16, v33
	v_lshl_or_b32 v112, v34, 16, v182
	v_and_or_b32 v113, v34, s40, v183
	v_lshl_or_b32 v114, v35, 16, v184
	v_and_or_b32 v115, v35, s40, v185
	v_cmp_eq_u32_e32 vcc, 1, v174
	v_xor_b32_e32 v182, 0x80000000, v117
	v_xor_b32_e32 v183, 0x80000000, v119
	s_nop 1
	v_cndmask_b32_e32 v122, v182, v117, vcc
	v_cndmask_b32_e32 v123, v183, v119, vcc
.Lssm_tile_d1m2:
	s_waitcnt vmcnt(6)
	v_cndmask_b32_e64 v124, 0, v80, s[66:67]
	v_cndmask_b32_e64 v125, 0, v81, s[66:67]
	v_cndmask_b32_e64 v126, 0, v82, s[66:67]
	v_cndmask_b32_e64 v127, 0, v83, s[66:67]
	v_cndmask_b32_e64 v132, 0, v194, s[66:67]
	v_cndmask_b32_e64 v133, 0, v195, s[66:67]
	v_cndmask_b32_e64 v134, 0, v196, s[66:67]
	v_cndmask_b32_e64 v135, 0, v197, s[66:67]
	v_mfma_f32_32x32x16_bf16 v[16:31], v[124:127], v[84:87], 0
	v_cndmask_b32_e64 v128, 0, v194, s[68:69]
	v_cndmask_b32_e64 v129, 0, v195, s[68:69]
	v_cndmask_b32_e64 v130, 0, v196, s[68:69]
	v_cndmask_b32_e64 v131, 0, v197, s[68:69]
	v_mfma_f32_32x32x16_bf16 v[32:47], v[124:127], v[88:91], 0
	v_cndmask_b32_e64 v136, 0, v80, s[68:69]
	v_cndmask_b32_e64 v137, 0, v81, s[68:69]
	v_cndmask_b32_e64 v138, 0, v82, s[68:69]
	v_cndmask_b32_e64 v139, 0, v83, s[68:69]
	v_mfma_f32_32x32x16_bf16 v[48:63], v[132:135], v[84:87], 0
	v_mfma_f32_32x32x16_bf16 v[64:79], v[132:135], v[88:91], 0
	v_mfma_f32_32x32x16_bf16 v[16:31], v[128:131], v[92:95], v[16:31]
	v_mfma_f32_32x32x16_bf16 v[32:47], v[128:131], v[96:99], v[32:47]
	v_mfma_f32_32x32x16_bf16 v[48:63], v[136:139], v[92:95], v[48:63]
	v_mfma_f32_32x32x16_bf16 v[64:79], v[136:139], v[96:99], v[64:79]
	v_add_u32_e32 v171, s36, v155
	ds_write_b128 v162, v[80:83]
	s_nop 11
	global_load_dwordx4 v[80:83], v150, s[10:11]
	global_load_dwordx4 v[194:197], v193, s[10:11]
	s_sub_u32 s34, s34, 1024
	s_subb_u32 s35, s35, 0
	s_sub_u32 s10, s10, 1024
	s_subb_u32 s11, s11, 0
	v_fmac_f32_e32 v63, v116, v120
	v_fmac_f32_e32 v79, v118, v121
	v_fmac_f32_dpp v63, v120, v122 quad_perm:[1,0,3,2] row_mask:0xf bank_mask:0xf
	v_fmac_f32_dpp v79, v121, v123 quad_perm:[1,0,3,2] row_mask:0xf bank_mask:0xf
	v_cvt_pk_bf16_f32 v148, v63, v79
	ds_write_b32 v151, v148 offset:8432
	v_fmac_f32_e32 v62, v116, v63
	v_fmac_f32_e32 v78, v118, v79
	v_fmac_f32_dpp v62, v63, v122 quad_perm:[1,0,3,2] row_mask:0xf bank_mask:0xf
	v_fmac_f32_dpp v78, v79, v123 quad_perm:[1,0,3,2] row_mask:0xf bank_mask:0xf
	v_cvt_pk_bf16_f32 v149, v62, v78
	ds_write_b32 v151, v149 offset:8160
	v_fmac_f32_e32 v61, v116, v62
	v_fmac_f32_e32 v77, v118, v78
	v_fmac_f32_dpp v61, v62, v122 quad_perm:[1,0,3,2] row_mask:0xf bank_mask:0xf
	v_fmac_f32_dpp v77, v78, v123 quad_perm:[1,0,3,2] row_mask:0xf bank_mask:0xf
	v_cvt_pk_bf16_f32 v148, v61, v77
	ds_write_b32 v151, v148 offset:7888
	v_fmac_f32_e32 v60, v116, v61
	v_fmac_f32_e32 v76, v118, v77
	v_fmac_f32_dpp v60, v61, v122 quad_perm:[1,0,3,2] row_mask:0xf bank_mask:0xf
	v_fmac_f32_dpp v76, v77, v123 quad_perm:[1,0,3,2] row_mask:0xf bank_mask:0xf
	v_cvt_pk_bf16_f32 v149, v60, v76
	ds_write_b32 v151, v149 offset:7616
	v_fmac_f32_e32 v31, v116, v60
	v_fmac_f32_e32 v47, v118, v76
	v_fmac_f32_dpp v31, v60, v122 quad_perm:[1,0,3,2] row_mask:0xf bank_mask:0xf
	v_fmac_f32_dpp v47, v76, v123 quad_perm:[1,0,3,2] row_mask:0xf bank_mask:0xf
	v_cvt_pk_bf16_f32 v148, v31, v47
	ds_write_b32 v151, v148 offset:7344
	v_fmac_f32_e32 v30, v116, v31
	v_fmac_f32_e32 v46, v118, v47
	v_fmac_f32_dpp v30, v31, v122 quad_perm:[1,0,3,2] row_mask:0xf bank_mask:0xf
	v_fmac_f32_dpp v46, v47, v123 quad_perm:[1,0,3,2] row_mask:0xf bank_mask:0xf
	v_cvt_pk_bf16_f32 v149, v30, v46
	ds_write_b32 v151, v149 offset:7072
	v_fmac_f32_e32 v29, v116, v30
	v_fmac_f32_e32 v45, v118, v46
	v_fmac_f32_dpp v29, v30, v122 quad_perm:[1,0,3,2] row_mask:0xf bank_mask:0xf
	v_fmac_f32_dpp v45, v46, v123 quad_perm:[1,0,3,2] row_mask:0xf bank_mask:0xf
	v_cvt_pk_bf16_f32 v148, v29, v45
	ds_write_b32 v151, v148 offset:6800
	v_fmac_f32_e32 v28, v116, v29
	v_fmac_f32_e32 v44, v118, v45
	v_fmac_f32_dpp v28, v29, v122 quad_perm:[1,0,3,2] row_mask:0xf bank_mask:0xf
	v_fmac_f32_dpp v44, v45, v123 quad_perm:[1,0,3,2] row_mask:0xf bank_mask:0xf
	v_cvt_pk_bf16_f32 v149, v28, v44
	ds_write_b32 v151, v149 offset:6528
	v_fmac_f32_e32 v59, v116, v28
	v_fmac_f32_e32 v75, v118, v44
	v_fmac_f32_dpp v59, v28, v122 quad_perm:[1,0,3,2] row_mask:0xf bank_mask:0xf
	v_fmac_f32_dpp v75, v44, v123 quad_perm:[1,0,3,2] row_mask:0xf bank_mask:0xf
	v_cvt_pk_bf16_f32 v148, v59, v75
	ds_write_b32 v151, v148 offset:6256
	v_fmac_f32_e32 v58, v116, v59
	v_fmac_f32_e32 v74, v118, v75
	v_fmac_f32_dpp v58, v59, v122 quad_perm:[1,0,3,2] row_mask:0xf bank_mask:0xf
	v_fmac_f32_dpp v74, v75, v123 quad_perm:[1,0,3,2] row_mask:0xf bank_mask:0xf
	v_cvt_pk_bf16_f32 v149, v58, v74
	ds_write_b32 v151, v149 offset:5984
	v_fmac_f32_e32 v57, v116, v58
	v_fmac_f32_e32 v73, v118, v74
	v_fmac_f32_dpp v57, v58, v122 quad_perm:[1,0,3,2] row_mask:0xf bank_mask:0xf
	v_fmac_f32_dpp v73, v74, v123 quad_perm:[1,0,3,2] row_mask:0xf bank_mask:0xf
	v_cvt_pk_bf16_f32 v148, v57, v73
	ds_write_b32 v151, v148 offset:5712
	v_fmac_f32_e32 v56, v116, v57
	v_fmac_f32_e32 v72, v118, v73
	v_fmac_f32_dpp v56, v57, v122 quad_perm:[1,0,3,2] row_mask:0xf bank_mask:0xf
	v_fmac_f32_dpp v72, v73, v123 quad_perm:[1,0,3,2] row_mask:0xf bank_mask:0xf
	v_cvt_pk_bf16_f32 v149, v56, v72
	ds_write_b32 v151, v149 offset:5440
	v_fmac_f32_e32 v27, v116, v56
	v_fmac_f32_e32 v43, v118, v72
	v_fmac_f32_dpp v27, v56, v122 quad_perm:[1,0,3,2] row_mask:0xf bank_mask:0xf
	v_fmac_f32_dpp v43, v72, v123 quad_perm:[1,0,3,2] row_mask:0xf bank_mask:0xf
	v_cvt_pk_bf16_f32 v148, v27, v43
	ds_write_b32 v151, v148 offset:5168
	v_fmac_f32_e32 v26, v116, v27
	v_fmac_f32_e32 v42, v118, v43
	v_fmac_f32_dpp v26, v27, v122 quad_perm:[1,0,3,2] row_mask:0xf bank_mask:0xf
	v_fmac_f32_dpp v42, v43, v123 quad_perm:[1,0,3,2] row_mask:0xf bank_mask:0xf
	v_cvt_pk_bf16_f32 v149, v26, v42
	ds_write_b32 v151, v149 offset:4896
	v_fmac_f32_e32 v25, v116, v26
	v_fmac_f32_e32 v41, v118, v42
	v_fmac_f32_dpp v25, v26, v122 quad_perm:[1,0,3,2] row_mask:0xf bank_mask:0xf
	v_fmac_f32_dpp v41, v42, v123 quad_perm:[1,0,3,2] row_mask:0xf bank_mask:0xf
	v_cvt_pk_bf16_f32 v148, v25, v41
	ds_write_b32 v151, v148 offset:4624
	v_fmac_f32_e32 v24, v116, v25
	v_fmac_f32_e32 v40, v118, v41
	v_fmac_f32_dpp v24, v25, v122 quad_perm:[1,0,3,2] row_mask:0xf bank_mask:0xf
	v_fmac_f32_dpp v40, v41, v123 quad_perm:[1,0,3,2] row_mask:0xf bank_mask:0xf
	v_cvt_pk_bf16_f32 v149, v24, v40
	ds_write_b32 v151, v149 offset:4352
	v_fmac_f32_e32 v55, v116, v24
	v_fmac_f32_e32 v71, v118, v40
	v_fmac_f32_dpp v55, v24, v122 quad_perm:[1,0,3,2] row_mask:0xf bank_mask:0xf
	v_fmac_f32_dpp v71, v40, v123 quad_perm:[1,0,3,2] row_mask:0xf bank_mask:0xf
	v_cvt_pk_bf16_f32 v148, v55, v71
	ds_write_b32 v151, v148 offset:4080
	v_fmac_f32_e32 v54, v116, v55
	v_fmac_f32_e32 v70, v118, v71
	v_fmac_f32_dpp v54, v55, v122 quad_perm:[1,0,3,2] row_mask:0xf bank_mask:0xf
	v_fmac_f32_dpp v70, v71, v123 quad_perm:[1,0,3,2] row_mask:0xf bank_mask:0xf
	v_cvt_pk_bf16_f32 v149, v54, v70
	ds_write_b32 v151, v149 offset:3808
	v_fmac_f32_e32 v53, v116, v54
	v_fmac_f32_e32 v69, v118, v70
	v_fmac_f32_dpp v53, v54, v122 quad_perm:[1,0,3,2] row_mask:0xf bank_mask:0xf
	v_fmac_f32_dpp v69, v70, v123 quad_perm:[1,0,3,2] row_mask:0xf bank_mask:0xf
	v_cvt_pk_bf16_f32 v148, v53, v69
	ds_write_b32 v151, v148 offset:3536
	v_fmac_f32_e32 v52, v116, v53
	v_fmac_f32_e32 v68, v118, v69
	v_fmac_f32_dpp v52, v53, v122 quad_perm:[1,0,3,2] row_mask:0xf bank_mask:0xf
	v_fmac_f32_dpp v68, v69, v123 quad_perm:[1,0,3,2] row_mask:0xf bank_mask:0xf
	v_cvt_pk_bf16_f32 v149, v52, v68
	ds_write_b32 v151, v149 offset:3264
	v_fmac_f32_e32 v23, v116, v52
	v_fmac_f32_e32 v39, v118, v68
	v_fmac_f32_dpp v23, v52, v122 quad_perm:[1,0,3,2] row_mask:0xf bank_mask:0xf
	v_fmac_f32_dpp v39, v68, v123 quad_perm:[1,0,3,2] row_mask:0xf bank_mask:0xf
	v_cvt_pk_bf16_f32 v148, v23, v39
	ds_write_b32 v151, v148 offset:2992
	v_fmac_f32_e32 v22, v116, v23
	v_fmac_f32_e32 v38, v118, v39
	v_fmac_f32_dpp v22, v23, v122 quad_perm:[1,0,3,2] row_mask:0xf bank_mask:0xf
	v_fmac_f32_dpp v38, v39, v123 quad_perm:[1,0,3,2] row_mask:0xf bank_mask:0xf
	v_cvt_pk_bf16_f32 v149, v22, v38
	ds_write_b32 v151, v149 offset:2720
	v_fmac_f32_e32 v21, v116, v22
	v_fmac_f32_e32 v37, v118, v38
	v_fmac_f32_dpp v21, v22, v122 quad_perm:[1,0,3,2] row_mask:0xf bank_mask:0xf
	v_fmac_f32_dpp v37, v38, v123 quad_perm:[1,0,3,2] row_mask:0xf bank_mask:0xf
	v_cvt_pk_bf16_f32 v148, v21, v37
	ds_write_b32 v151, v148 offset:2448
	v_fmac_f32_e32 v20, v116, v21
	v_fmac_f32_e32 v36, v118, v37
	v_fmac_f32_dpp v20, v21, v122 quad_perm:[1,0,3,2] row_mask:0xf bank_mask:0xf
	v_fmac_f32_dpp v36, v37, v123 quad_perm:[1,0,3,2] row_mask:0xf bank_mask:0xf
	v_cvt_pk_bf16_f32 v149, v20, v36
	ds_write_b32 v151, v149 offset:2176
	v_fmac_f32_e32 v51, v116, v20
	v_fmac_f32_e32 v67, v118, v36
	v_fmac_f32_dpp v51, v20, v122 quad_perm:[1,0,3,2] row_mask:0xf bank_mask:0xf
	v_fmac_f32_dpp v67, v36, v123 quad_perm:[1,0,3,2] row_mask:0xf bank_mask:0xf
	v_cvt_pk_bf16_f32 v148, v51, v67
	ds_write_b32 v151, v148 offset:1904
	v_fmac_f32_e32 v50, v116, v51
	v_fmac_f32_e32 v66, v118, v67
	v_fmac_f32_dpp v50, v51, v122 quad_perm:[1,0,3,2] row_mask:0xf bank_mask:0xf
	v_fmac_f32_dpp v66, v67, v123 quad_perm:[1,0,3,2] row_mask:0xf bank_mask:0xf
	v_cvt_pk_bf16_f32 v149, v50, v66
	ds_write_b32 v151, v149 offset:1632
	v_fmac_f32_e32 v49, v116, v50
	v_fmac_f32_e32 v65, v118, v66
	v_fmac_f32_dpp v49, v50, v122 quad_perm:[1,0,3,2] row_mask:0xf bank_mask:0xf
	v_fmac_f32_dpp v65, v66, v123 quad_perm:[1,0,3,2] row_mask:0xf bank_mask:0xf
	v_cvt_pk_bf16_f32 v148, v49, v65
	ds_write_b32 v151, v148 offset:1360
	v_fmac_f32_e32 v48, v116, v49
	v_fmac_f32_e32 v64, v118, v65
	v_fmac_f32_dpp v48, v49, v122 quad_perm:[1,0,3,2] row_mask:0xf bank_mask:0xf
	v_fmac_f32_dpp v64, v65, v123 quad_perm:[1,0,3,2] row_mask:0xf bank_mask:0xf
	v_cvt_pk_bf16_f32 v149, v48, v64
	ds_write_b32 v151, v149 offset:1088
	v_fmac_f32_e32 v19, v116, v48
	v_fmac_f32_e32 v35, v118, v64
	v_fmac_f32_dpp v19, v48, v122 quad_perm:[1,0,3,2] row_mask:0xf bank_mask:0xf
	v_fmac_f32_dpp v35, v64, v123 quad_perm:[1,0,3,2] row_mask:0xf bank_mask:0xf
	v_cvt_pk_bf16_f32 v148, v19, v35
	ds_write_b32 v151, v148 offset:816
	v_fmac_f32_e32 v18, v116, v19
	v_fmac_f32_e32 v34, v118, v35
	v_fmac_f32_dpp v18, v19, v122 quad_perm:[1,0,3,2] row_mask:0xf bank_mask:0xf
	v_fmac_f32_dpp v34, v35, v123 quad_perm:[1,0,3,2] row_mask:0xf bank_mask:0xf
	v_cvt_pk_bf16_f32 v149, v18, v34
	ds_write_b32 v151, v149 offset:544
	v_fmac_f32_e32 v17, v116, v18
	v_fmac_f32_e32 v33, v118, v34
	v_fmac_f32_dpp v17, v18, v122 quad_perm:[1,0,3,2] row_mask:0xf bank_mask:0xf
	v_fmac_f32_dpp v33, v34, v123 quad_perm:[1,0,3,2] row_mask:0xf bank_mask:0xf
	v_cvt_pk_bf16_f32 v148, v17, v33
	ds_write_b32 v151, v148 offset:272
	v_fmac_f32_e32 v16, v116, v17
	v_fmac_f32_e32 v32, v118, v33
	v_fmac_f32_dpp v16, v17, v122 quad_perm:[1,0,3,2] row_mask:0xf bank_mask:0xf
	v_fmac_f32_dpp v32, v33, v123 quad_perm:[1,0,3,2] row_mask:0xf bank_mask:0xf
	v_cvt_pk_bf16_f32 v149, v16, v32
	ds_write_b32 v151, v149
	v_mov_b32_e32 v120, v16
	v_mov_b32_e32 v121, v32
	ds_read_b128 v[124:127], v152
	ds_read_b128 v[128:131], v152 offset:64
	ds_read_b128 v[132:135], v152 offset:128
	ds_read_b128 v[136:139], v152 offset:192
	ds_read_b64 v[168:169], v171
	ds_read_b64 v[160:161], v163
	s_waitcnt lgkmcnt(5)
	v_mfma_f32_16x16x32_bf16 v[140:143], v[100:103], v[124:127], 0
	s_waitcnt lgkmcnt(4)
	v_mfma_f32_16x16x32_bf16 v[140:143], v[104:107], v[128:131], v[140:143]
	s_waitcnt lgkmcnt(3)
	v_mfma_f32_16x16x32_bf16 v[140:143], v[108:111], v[132:135], v[140:143]
	s_waitcnt lgkmcnt(2)
	v_mfma_f32_16x16x32_bf16 v[140:143], v[112:115], v[136:139], v[140:143]
	s_nop 9
	s_waitcnt lgkmcnt(0)
	v_lshlrev_b32_e32 v182, 16, v168
	v_and_b32_e32 v183, 0xffff0000, v168
	v_lshlrev_b32_e32 v184, 16, v169
	v_and_b32_e32 v185, 0xffff0000, v169
	v_add_f32_e32 v182, v182, v140
	v_add_f32_e32 v183, v183, v141
	v_add_f32_e32 v184, v184, v142
	v_add_f32_e32 v185, v185, v143
	v_lshlrev_b32_e32 v186, 16, v160
	v_and_b32_e32 v187, 0xffff0000, v160
	v_lshlrev_b32_e32 v188, 16, v161
	v_and_b32_e32 v189, 0xffff0000, v161
	v_fmac_f32_e32 v182, v164, v186
	v_fmac_f32_e32 v183, v165, v187
	v_fmac_f32_e32 v184, v166, v188
	v_fmac_f32_e32 v185, v167, v189
	v_mul_f32_e32 v186, 0x3d372713, v182
	v_mul_f32_e32 v187, 0x3d372713, v183
	v_mul_f32_e32 v188, 0x3d372713, v184
	v_mul_f32_e32 v189, 0x3d372713, v185
	v_mul_f32_e32 v186, v182, v186
	v_mul_f32_e32 v187, v183, v187
	v_mul_f32_e32 v188, v184, v188
	v_mul_f32_e32 v189, v185, v189
	v_fma_f32 v186, v182, v186, v182
	v_fma_f32 v187, v183, v187, v183
	v_fma_f32 v188, v184, v188, v184
	v_fma_f32 v189, v185, v189, v185
	v_mul_f32_e32 v186, 0xbfcc422a, v186
	v_mul_f32_e32 v187, 0xbfcc422a, v187
	v_mul_f32_e32 v188, 0xbfcc422a, v188
	v_mul_f32_e32 v189, 0xbfcc422a, v189
	v_mul_f32_e32 v186, 0x3fb8aa3b, v186
	v_mul_f32_e32 v187, 0x3fb8aa3b, v187
	v_mul_f32_e32 v188, 0x3fb8aa3b, v188
	v_mul_f32_e32 v189, 0x3fb8aa3b, v189
	v_exp_f32_e32 v186, v186
	v_exp_f32_e32 v187, v187
	v_exp_f32_e32 v188, v188
	v_exp_f32_e32 v189, v189
	v_add_f32_e32 v186, 1.0, v186
	v_add_f32_e32 v187, 1.0, v187
	v_add_f32_e32 v188, 1.0, v188
	v_add_f32_e32 v189, 1.0, v189
	v_rcp_f32_e32 v186, v186
	v_rcp_f32_e32 v187, v187
	v_rcp_f32_e32 v188, v188
	v_rcp_f32_e32 v189, v189
	v_mul_f32_e32 v182, v182, v186
	v_mul_f32_e32 v183, v183, v187
	v_mul_f32_e32 v184, v184, v188
	v_mul_f32_e32 v185, v185, v189
	v_cvt_pk_bf16_f32 v148, v182, v183
	v_cvt_pk_bf16_f32 v149, v184, v185
	global_store_dwordx2 v156, v[148:149], s[12:13]
	ds_read_b128 v[124:127], v152 offset:4352
	ds_read_b128 v[128:131], v152 offset:4416
	ds_read_b128 v[132:135], v152 offset:4480
	ds_read_b128 v[136:139], v152 offset:4544
	ds_read_b64 v[168:169], v171 offset:512
	ds_read_b64 v[160:161], v163 offset:512
	s_waitcnt lgkmcnt(5)
	v_mfma_f32_16x16x32_bf16 v[140:143], v[100:103], v[124:127], 0
	s_waitcnt lgkmcnt(4)
	v_mfma_f32_16x16x32_bf16 v[140:143], v[104:107], v[128:131], v[140:143]
	s_waitcnt lgkmcnt(3)
	v_mfma_f32_16x16x32_bf16 v[140:143], v[108:111], v[132:135], v[140:143]
	s_waitcnt lgkmcnt(2)
	v_mfma_f32_16x16x32_bf16 v[140:143], v[112:115], v[136:139], v[140:143]
	s_nop 9
	s_waitcnt lgkmcnt(0)
	v_lshlrev_b32_e32 v182, 16, v168
	v_and_b32_e32 v183, 0xffff0000, v168
	v_lshlrev_b32_e32 v184, 16, v169
	v_and_b32_e32 v185, 0xffff0000, v169
	v_add_f32_e32 v182, v182, v140
	v_add_f32_e32 v183, v183, v141
	v_add_f32_e32 v184, v184, v142
	v_add_f32_e32 v185, v185, v143
	v_lshlrev_b32_e32 v186, 16, v160
	v_and_b32_e32 v187, 0xffff0000, v160
	v_lshlrev_b32_e32 v188, 16, v161
	v_and_b32_e32 v189, 0xffff0000, v161
	v_fmac_f32_e32 v182, v164, v186
	v_fmac_f32_e32 v183, v165, v187
	v_fmac_f32_e32 v184, v166, v188
	v_fmac_f32_e32 v185, v167, v189
	v_mul_f32_e32 v186, 0x3d372713, v182
	v_mul_f32_e32 v187, 0x3d372713, v183
	v_mul_f32_e32 v188, 0x3d372713, v184
	v_mul_f32_e32 v189, 0x3d372713, v185
	v_mul_f32_e32 v186, v182, v186
	v_mul_f32_e32 v187, v183, v187
	v_mul_f32_e32 v188, v184, v188
	v_mul_f32_e32 v189, v185, v189
	v_fma_f32 v186, v182, v186, v182
	v_fma_f32 v187, v183, v187, v183
	v_fma_f32 v188, v184, v188, v184
	v_fma_f32 v189, v185, v189, v185
	v_mul_f32_e32 v186, 0xbfcc422a, v186
	v_mul_f32_e32 v187, 0xbfcc422a, v187
	v_mul_f32_e32 v188, 0xbfcc422a, v188
	v_mul_f32_e32 v189, 0xbfcc422a, v189
	v_mul_f32_e32 v186, 0x3fb8aa3b, v186
	v_mul_f32_e32 v187, 0x3fb8aa3b, v187
	v_mul_f32_e32 v188, 0x3fb8aa3b, v188
	v_mul_f32_e32 v189, 0x3fb8aa3b, v189
	v_exp_f32_e32 v186, v186
	v_exp_f32_e32 v187, v187
	v_exp_f32_e32 v188, v188
	v_exp_f32_e32 v189, v189
	v_add_f32_e32 v186, 1.0, v186
	v_add_f32_e32 v187, 1.0, v187
	v_add_f32_e32 v188, 1.0, v188
	v_add_f32_e32 v189, 1.0, v189
	v_rcp_f32_e32 v186, v186
	v_rcp_f32_e32 v187, v187
	v_rcp_f32_e32 v188, v188
	v_rcp_f32_e32 v189, v189
	v_mul_f32_e32 v182, v182, v186
	v_mul_f32_e32 v183, v183, v187
	v_mul_f32_e32 v184, v184, v188
	v_mul_f32_e32 v185, v185, v189
	v_cvt_pk_bf16_f32 v148, v182, v183
	v_cvt_pk_bf16_f32 v149, v184, v185
	global_store_dwordx2 v159, v[148:149], s[12:13]
	s_sub_u32 s12, s12, 65536
	s_subb_u32 s13, s13, 0
	s_sub_u32 s36, s36, 1024
	s_waitcnt vmcnt(6)
	v_cndmask_b32_e64 v124, 0, v144, s[66:67]
	v_cndmask_b32_e64 v125, 0, v145, s[66:67]
	v_cndmask_b32_e64 v126, 0, v146, s[66:67]
	v_cndmask_b32_e64 v127, 0, v147, s[66:67]
	v_cndmask_b32_e64 v132, 0, v6, s[66:67]
	v_cndmask_b32_e64 v133, 0, v7, s[66:67]
	v_cndmask_b32_e64 v134, 0, v8, s[66:67]
	v_cndmask_b32_e64 v135, 0, v9, s[66:67]
	v_mfma_f32_32x32x16_bf16 v[16:31], v[124:127], v[84:87], 0
	v_cndmask_b32_e64 v128, 0, v6, s[68:69]
	v_cndmask_b32_e64 v129, 0, v7, s[68:69]
	v_cndmask_b32_e64 v130, 0, v8, s[68:69]
	v_cndmask_b32_e64 v131, 0, v9, s[68:69]
	v_mfma_f32_32x32x16_bf16 v[32:47], v[124:127], v[88:91], 0
	v_cndmask_b32_e64 v136, 0, v144, s[68:69]
	v_cndmask_b32_e64 v137, 0, v145, s[68:69]
	v_cndmask_b32_e64 v138, 0, v146, s[68:69]
	v_cndmask_b32_e64 v139, 0, v147, s[68:69]
	v_mfma_f32_32x32x16_bf16 v[48:63], v[132:135], v[84:87], 0
	v_mfma_f32_32x32x16_bf16 v[64:79], v[132:135], v[88:91], 0
	v_mfma_f32_32x32x16_bf16 v[16:31], v[128:131], v[92:95], v[16:31]
	v_mfma_f32_32x32x16_bf16 v[32:47], v[128:131], v[96:99], v[32:47]
	v_mfma_f32_32x32x16_bf16 v[48:63], v[136:139], v[92:95], v[48:63]
	v_mfma_f32_32x32x16_bf16 v[64:79], v[136:139], v[96:99], v[64:79]
	v_add_u32_e32 v171, s36, v155
	ds_write_b128 v162, v[144:147]
	s_nop 11
	global_load_dwordx4 v[144:147], v150, s[10:11]
	global_load_dwordx4 v[6:9], v193, s[10:11]
	s_sub_u32 s34, s34, 1024
	s_subb_u32 s35, s35, 0
	s_sub_u32 s10, s10, 1024
	s_subb_u32 s11, s11, 0
	v_fmac_f32_e32 v63, v116, v120
	v_fmac_f32_e32 v79, v118, v121
	v_fmac_f32_dpp v63, v120, v122 quad_perm:[1,0,3,2] row_mask:0xf bank_mask:0xf
	v_fmac_f32_dpp v79, v121, v123 quad_perm:[1,0,3,2] row_mask:0xf bank_mask:0xf
	v_cvt_pk_bf16_f32 v148, v63, v79
	ds_write_b32 v151, v148 offset:8432
	v_fmac_f32_e32 v62, v116, v63
	v_fmac_f32_e32 v78, v118, v79
	v_fmac_f32_dpp v62, v63, v122 quad_perm:[1,0,3,2] row_mask:0xf bank_mask:0xf
	v_fmac_f32_dpp v78, v79, v123 quad_perm:[1,0,3,2] row_mask:0xf bank_mask:0xf
	v_cvt_pk_bf16_f32 v149, v62, v78
	ds_write_b32 v151, v149 offset:8160
	v_fmac_f32_e32 v61, v116, v62
	v_fmac_f32_e32 v77, v118, v78
	v_fmac_f32_dpp v61, v62, v122 quad_perm:[1,0,3,2] row_mask:0xf bank_mask:0xf
	v_fmac_f32_dpp v77, v78, v123 quad_perm:[1,0,3,2] row_mask:0xf bank_mask:0xf
	v_cvt_pk_bf16_f32 v148, v61, v77
	ds_write_b32 v151, v148 offset:7888
	v_fmac_f32_e32 v60, v116, v61
	v_fmac_f32_e32 v76, v118, v77
	v_fmac_f32_dpp v60, v61, v122 quad_perm:[1,0,3,2] row_mask:0xf bank_mask:0xf
	v_fmac_f32_dpp v76, v77, v123 quad_perm:[1,0,3,2] row_mask:0xf bank_mask:0xf
	v_cvt_pk_bf16_f32 v149, v60, v76
	ds_write_b32 v151, v149 offset:7616
	v_fmac_f32_e32 v31, v116, v60
	v_fmac_f32_e32 v47, v118, v76
	v_fmac_f32_dpp v31, v60, v122 quad_perm:[1,0,3,2] row_mask:0xf bank_mask:0xf
	v_fmac_f32_dpp v47, v76, v123 quad_perm:[1,0,3,2] row_mask:0xf bank_mask:0xf
	v_cvt_pk_bf16_f32 v148, v31, v47
	ds_write_b32 v151, v148 offset:7344
	v_fmac_f32_e32 v30, v116, v31
	v_fmac_f32_e32 v46, v118, v47
	v_fmac_f32_dpp v30, v31, v122 quad_perm:[1,0,3,2] row_mask:0xf bank_mask:0xf
	v_fmac_f32_dpp v46, v47, v123 quad_perm:[1,0,3,2] row_mask:0xf bank_mask:0xf
	v_cvt_pk_bf16_f32 v149, v30, v46
	ds_write_b32 v151, v149 offset:7072
	v_fmac_f32_e32 v29, v116, v30
	v_fmac_f32_e32 v45, v118, v46
	v_fmac_f32_dpp v29, v30, v122 quad_perm:[1,0,3,2] row_mask:0xf bank_mask:0xf
	v_fmac_f32_dpp v45, v46, v123 quad_perm:[1,0,3,2] row_mask:0xf bank_mask:0xf
	v_cvt_pk_bf16_f32 v148, v29, v45
	ds_write_b32 v151, v148 offset:6800
	v_fmac_f32_e32 v28, v116, v29
	v_fmac_f32_e32 v44, v118, v45
	v_fmac_f32_dpp v28, v29, v122 quad_perm:[1,0,3,2] row_mask:0xf bank_mask:0xf
	v_fmac_f32_dpp v44, v45, v123 quad_perm:[1,0,3,2] row_mask:0xf bank_mask:0xf
	v_cvt_pk_bf16_f32 v149, v28, v44
	ds_write_b32 v151, v149 offset:6528
	v_fmac_f32_e32 v59, v116, v28
	v_fmac_f32_e32 v75, v118, v44
	v_fmac_f32_dpp v59, v28, v122 quad_perm:[1,0,3,2] row_mask:0xf bank_mask:0xf
	v_fmac_f32_dpp v75, v44, v123 quad_perm:[1,0,3,2] row_mask:0xf bank_mask:0xf
	v_cvt_pk_bf16_f32 v148, v59, v75
	ds_write_b32 v151, v148 offset:6256
	v_fmac_f32_e32 v58, v116, v59
	v_fmac_f32_e32 v74, v118, v75
	v_fmac_f32_dpp v58, v59, v122 quad_perm:[1,0,3,2] row_mask:0xf bank_mask:0xf
	v_fmac_f32_dpp v74, v75, v123 quad_perm:[1,0,3,2] row_mask:0xf bank_mask:0xf
	v_cvt_pk_bf16_f32 v149, v58, v74
	ds_write_b32 v151, v149 offset:5984
	v_fmac_f32_e32 v57, v116, v58
	v_fmac_f32_e32 v73, v118, v74
	v_fmac_f32_dpp v57, v58, v122 quad_perm:[1,0,3,2] row_mask:0xf bank_mask:0xf
	v_fmac_f32_dpp v73, v74, v123 quad_perm:[1,0,3,2] row_mask:0xf bank_mask:0xf
	v_cvt_pk_bf16_f32 v148, v57, v73
	ds_write_b32 v151, v148 offset:5712
	v_fmac_f32_e32 v56, v116, v57
	v_fmac_f32_e32 v72, v118, v73
	v_fmac_f32_dpp v56, v57, v122 quad_perm:[1,0,3,2] row_mask:0xf bank_mask:0xf
	v_fmac_f32_dpp v72, v73, v123 quad_perm:[1,0,3,2] row_mask:0xf bank_mask:0xf
	v_cvt_pk_bf16_f32 v149, v56, v72
	ds_write_b32 v151, v149 offset:5440
	v_fmac_f32_e32 v27, v116, v56
	v_fmac_f32_e32 v43, v118, v72
	v_fmac_f32_dpp v27, v56, v122 quad_perm:[1,0,3,2] row_mask:0xf bank_mask:0xf
	v_fmac_f32_dpp v43, v72, v123 quad_perm:[1,0,3,2] row_mask:0xf bank_mask:0xf
	v_cvt_pk_bf16_f32 v148, v27, v43
	ds_write_b32 v151, v148 offset:5168
	v_fmac_f32_e32 v26, v116, v27
	v_fmac_f32_e32 v42, v118, v43
	v_fmac_f32_dpp v26, v27, v122 quad_perm:[1,0,3,2] row_mask:0xf bank_mask:0xf
	v_fmac_f32_dpp v42, v43, v123 quad_perm:[1,0,3,2] row_mask:0xf bank_mask:0xf
	v_cvt_pk_bf16_f32 v149, v26, v42
	ds_write_b32 v151, v149 offset:4896
	v_fmac_f32_e32 v25, v116, v26
	v_fmac_f32_e32 v41, v118, v42
	v_fmac_f32_dpp v25, v26, v122 quad_perm:[1,0,3,2] row_mask:0xf bank_mask:0xf
	v_fmac_f32_dpp v41, v42, v123 quad_perm:[1,0,3,2] row_mask:0xf bank_mask:0xf
	v_cvt_pk_bf16_f32 v148, v25, v41
	ds_write_b32 v151, v148 offset:4624
	v_fmac_f32_e32 v24, v116, v25
	v_fmac_f32_e32 v40, v118, v41
	v_fmac_f32_dpp v24, v25, v122 quad_perm:[1,0,3,2] row_mask:0xf bank_mask:0xf
	v_fmac_f32_dpp v40, v41, v123 quad_perm:[1,0,3,2] row_mask:0xf bank_mask:0xf
	v_cvt_pk_bf16_f32 v149, v24, v40
	ds_write_b32 v151, v149 offset:4352
	v_fmac_f32_e32 v55, v116, v24
	v_fmac_f32_e32 v71, v118, v40
	v_fmac_f32_dpp v55, v24, v122 quad_perm:[1,0,3,2] row_mask:0xf bank_mask:0xf
	v_fmac_f32_dpp v71, v40, v123 quad_perm:[1,0,3,2] row_mask:0xf bank_mask:0xf
	v_cvt_pk_bf16_f32 v148, v55, v71
	ds_write_b32 v151, v148 offset:4080
	v_fmac_f32_e32 v54, v116, v55
	v_fmac_f32_e32 v70, v118, v71
	v_fmac_f32_dpp v54, v55, v122 quad_perm:[1,0,3,2] row_mask:0xf bank_mask:0xf
	v_fmac_f32_dpp v70, v71, v123 quad_perm:[1,0,3,2] row_mask:0xf bank_mask:0xf
	v_cvt_pk_bf16_f32 v149, v54, v70
	ds_write_b32 v151, v149 offset:3808
	v_fmac_f32_e32 v53, v116, v54
	v_fmac_f32_e32 v69, v118, v70
	v_fmac_f32_dpp v53, v54, v122 quad_perm:[1,0,3,2] row_mask:0xf bank_mask:0xf
	v_fmac_f32_dpp v69, v70, v123 quad_perm:[1,0,3,2] row_mask:0xf bank_mask:0xf
	v_cvt_pk_bf16_f32 v148, v53, v69
	ds_write_b32 v151, v148 offset:3536
	v_fmac_f32_e32 v52, v116, v53
	v_fmac_f32_e32 v68, v118, v69
	v_fmac_f32_dpp v52, v53, v122 quad_perm:[1,0,3,2] row_mask:0xf bank_mask:0xf
	v_fmac_f32_dpp v68, v69, v123 quad_perm:[1,0,3,2] row_mask:0xf bank_mask:0xf
	v_cvt_pk_bf16_f32 v149, v52, v68
	ds_write_b32 v151, v149 offset:3264
	v_fmac_f32_e32 v23, v116, v52
	v_fmac_f32_e32 v39, v118, v68
	v_fmac_f32_dpp v23, v52, v122 quad_perm:[1,0,3,2] row_mask:0xf bank_mask:0xf
	v_fmac_f32_dpp v39, v68, v123 quad_perm:[1,0,3,2] row_mask:0xf bank_mask:0xf
	v_cvt_pk_bf16_f32 v148, v23, v39
	ds_write_b32 v151, v148 offset:2992
	v_fmac_f32_e32 v22, v116, v23
	v_fmac_f32_e32 v38, v118, v39
	v_fmac_f32_dpp v22, v23, v122 quad_perm:[1,0,3,2] row_mask:0xf bank_mask:0xf
	v_fmac_f32_dpp v38, v39, v123 quad_perm:[1,0,3,2] row_mask:0xf bank_mask:0xf
	v_cvt_pk_bf16_f32 v149, v22, v38
	ds_write_b32 v151, v149 offset:2720
	v_fmac_f32_e32 v21, v116, v22
	v_fmac_f32_e32 v37, v118, v38
	v_fmac_f32_dpp v21, v22, v122 quad_perm:[1,0,3,2] row_mask:0xf bank_mask:0xf
	v_fmac_f32_dpp v37, v38, v123 quad_perm:[1,0,3,2] row_mask:0xf bank_mask:0xf
	v_cvt_pk_bf16_f32 v148, v21, v37
	ds_write_b32 v151, v148 offset:2448
	v_fmac_f32_e32 v20, v116, v21
	v_fmac_f32_e32 v36, v118, v37
	v_fmac_f32_dpp v20, v21, v122 quad_perm:[1,0,3,2] row_mask:0xf bank_mask:0xf
	v_fmac_f32_dpp v36, v37, v123 quad_perm:[1,0,3,2] row_mask:0xf bank_mask:0xf
	v_cvt_pk_bf16_f32 v149, v20, v36
	ds_write_b32 v151, v149 offset:2176
	v_fmac_f32_e32 v51, v116, v20
	v_fmac_f32_e32 v67, v118, v36
	v_fmac_f32_dpp v51, v20, v122 quad_perm:[1,0,3,2] row_mask:0xf bank_mask:0xf
	v_fmac_f32_dpp v67, v36, v123 quad_perm:[1,0,3,2] row_mask:0xf bank_mask:0xf
	v_cvt_pk_bf16_f32 v148, v51, v67
	ds_write_b32 v151, v148 offset:1904
	v_fmac_f32_e32 v50, v116, v51
	v_fmac_f32_e32 v66, v118, v67
	v_fmac_f32_dpp v50, v51, v122 quad_perm:[1,0,3,2] row_mask:0xf bank_mask:0xf
	v_fmac_f32_dpp v66, v67, v123 quad_perm:[1,0,3,2] row_mask:0xf bank_mask:0xf
	v_cvt_pk_bf16_f32 v149, v50, v66
	ds_write_b32 v151, v149 offset:1632
	v_fmac_f32_e32 v49, v116, v50
	v_fmac_f32_e32 v65, v118, v66
	v_fmac_f32_dpp v49, v50, v122 quad_perm:[1,0,3,2] row_mask:0xf bank_mask:0xf
	v_fmac_f32_dpp v65, v66, v123 quad_perm:[1,0,3,2] row_mask:0xf bank_mask:0xf
	v_cvt_pk_bf16_f32 v148, v49, v65
	ds_write_b32 v151, v148 offset:1360
	v_fmac_f32_e32 v48, v116, v49
	v_fmac_f32_e32 v64, v118, v65
	v_fmac_f32_dpp v48, v49, v122 quad_perm:[1,0,3,2] row_mask:0xf bank_mask:0xf
	v_fmac_f32_dpp v64, v65, v123 quad_perm:[1,0,3,2] row_mask:0xf bank_mask:0xf
	v_cvt_pk_bf16_f32 v149, v48, v64
	ds_write_b32 v151, v149 offset:1088
	v_fmac_f32_e32 v19, v116, v48
	v_fmac_f32_e32 v35, v118, v64
	v_fmac_f32_dpp v19, v48, v122 quad_perm:[1,0,3,2] row_mask:0xf bank_mask:0xf
	v_fmac_f32_dpp v35, v64, v123 quad_perm:[1,0,3,2] row_mask:0xf bank_mask:0xf
	v_cvt_pk_bf16_f32 v148, v19, v35
	ds_write_b32 v151, v148 offset:816
	v_fmac_f32_e32 v18, v116, v19
	v_fmac_f32_e32 v34, v118, v35
	v_fmac_f32_dpp v18, v19, v122 quad_perm:[1,0,3,2] row_mask:0xf bank_mask:0xf
	v_fmac_f32_dpp v34, v35, v123 quad_perm:[1,0,3,2] row_mask:0xf bank_mask:0xf
	v_cvt_pk_bf16_f32 v149, v18, v34
	ds_write_b32 v151, v149 offset:544
	v_fmac_f32_e32 v17, v116, v18
	v_fmac_f32_e32 v33, v118, v34
	v_fmac_f32_dpp v17, v18, v122 quad_perm:[1,0,3,2] row_mask:0xf bank_mask:0xf
	v_fmac_f32_dpp v33, v34, v123 quad_perm:[1,0,3,2] row_mask:0xf bank_mask:0xf
	v_cvt_pk_bf16_f32 v148, v17, v33
	ds_write_b32 v151, v148 offset:272
	v_fmac_f32_e32 v16, v116, v17
	v_fmac_f32_e32 v32, v118, v33
	v_fmac_f32_dpp v16, v17, v122 quad_perm:[1,0,3,2] row_mask:0xf bank_mask:0xf
	v_fmac_f32_dpp v32, v33, v123 quad_perm:[1,0,3,2] row_mask:0xf bank_mask:0xf
	v_cvt_pk_bf16_f32 v149, v16, v32
	ds_write_b32 v151, v149
	v_mov_b32_e32 v120, v16
	v_mov_b32_e32 v121, v32
	ds_read_b128 v[124:127], v152
	ds_read_b128 v[128:131], v152 offset:64
	ds_read_b128 v[132:135], v152 offset:128
	ds_read_b128 v[136:139], v152 offset:192
	ds_read_b64 v[168:169], v171
	ds_read_b64 v[160:161], v163
	s_waitcnt lgkmcnt(5)
	v_mfma_f32_16x16x32_bf16 v[140:143], v[100:103], v[124:127], 0
	s_waitcnt lgkmcnt(4)
	v_mfma_f32_16x16x32_bf16 v[140:143], v[104:107], v[128:131], v[140:143]
	s_waitcnt lgkmcnt(3)
	v_mfma_f32_16x16x32_bf16 v[140:143], v[108:111], v[132:135], v[140:143]
	s_waitcnt lgkmcnt(2)
	v_mfma_f32_16x16x32_bf16 v[140:143], v[112:115], v[136:139], v[140:143]
	s_nop 9
	s_waitcnt lgkmcnt(0)
	v_lshlrev_b32_e32 v182, 16, v168
	v_and_b32_e32 v183, 0xffff0000, v168
	v_lshlrev_b32_e32 v184, 16, v169
	v_and_b32_e32 v185, 0xffff0000, v169
	v_add_f32_e32 v182, v182, v140
	v_add_f32_e32 v183, v183, v141
	v_add_f32_e32 v184, v184, v142
	v_add_f32_e32 v185, v185, v143
	v_lshlrev_b32_e32 v186, 16, v160
	v_and_b32_e32 v187, 0xffff0000, v160
	v_lshlrev_b32_e32 v188, 16, v161
	v_and_b32_e32 v189, 0xffff0000, v161
	v_fmac_f32_e32 v182, v164, v186
	v_fmac_f32_e32 v183, v165, v187
	v_fmac_f32_e32 v184, v166, v188
	v_fmac_f32_e32 v185, v167, v189
	v_mul_f32_e32 v186, 0x3d372713, v182
	v_mul_f32_e32 v187, 0x3d372713, v183
	v_mul_f32_e32 v188, 0x3d372713, v184
	v_mul_f32_e32 v189, 0x3d372713, v185
	v_mul_f32_e32 v186, v182, v186
	v_mul_f32_e32 v187, v183, v187
	v_mul_f32_e32 v188, v184, v188
	v_mul_f32_e32 v189, v185, v189
	v_fma_f32 v186, v182, v186, v182
	v_fma_f32 v187, v183, v187, v183
	v_fma_f32 v188, v184, v188, v184
	v_fma_f32 v189, v185, v189, v185
	v_mul_f32_e32 v186, 0xbfcc422a, v186
	v_mul_f32_e32 v187, 0xbfcc422a, v187
	v_mul_f32_e32 v188, 0xbfcc422a, v188
	v_mul_f32_e32 v189, 0xbfcc422a, v189
	v_mul_f32_e32 v186, 0x3fb8aa3b, v186
	v_mul_f32_e32 v187, 0x3fb8aa3b, v187
	v_mul_f32_e32 v188, 0x3fb8aa3b, v188
	v_mul_f32_e32 v189, 0x3fb8aa3b, v189
	v_exp_f32_e32 v186, v186
	v_exp_f32_e32 v187, v187
	v_exp_f32_e32 v188, v188
	v_exp_f32_e32 v189, v189
	v_add_f32_e32 v186, 1.0, v186
	v_add_f32_e32 v187, 1.0, v187
	v_add_f32_e32 v188, 1.0, v188
	v_add_f32_e32 v189, 1.0, v189
	v_rcp_f32_e32 v186, v186
	v_rcp_f32_e32 v187, v187
	v_rcp_f32_e32 v188, v188
	v_rcp_f32_e32 v189, v189
	v_mul_f32_e32 v182, v182, v186
	v_mul_f32_e32 v183, v183, v187
	v_mul_f32_e32 v184, v184, v188
	v_mul_f32_e32 v185, v185, v189
	v_cvt_pk_bf16_f32 v148, v182, v183
	v_cvt_pk_bf16_f32 v149, v184, v185
	global_store_dwordx2 v156, v[148:149], s[12:13]
	ds_read_b128 v[124:127], v152 offset:4352
	ds_read_b128 v[128:131], v152 offset:4416
	ds_read_b128 v[132:135], v152 offset:4480
	ds_read_b128 v[136:139], v152 offset:4544
	ds_read_b64 v[168:169], v171 offset:512
	ds_read_b64 v[160:161], v163 offset:512
	s_waitcnt lgkmcnt(5)
	v_mfma_f32_16x16x32_bf16 v[140:143], v[100:103], v[124:127], 0
	s_waitcnt lgkmcnt(4)
	v_mfma_f32_16x16x32_bf16 v[140:143], v[104:107], v[128:131], v[140:143]
	s_waitcnt lgkmcnt(3)
	v_mfma_f32_16x16x32_bf16 v[140:143], v[108:111], v[132:135], v[140:143]
	s_waitcnt lgkmcnt(2)
	v_mfma_f32_16x16x32_bf16 v[140:143], v[112:115], v[136:139], v[140:143]
	s_nop 9
	s_waitcnt lgkmcnt(0)
	v_lshlrev_b32_e32 v182, 16, v168
	v_and_b32_e32 v183, 0xffff0000, v168
	v_lshlrev_b32_e32 v184, 16, v169
	v_and_b32_e32 v185, 0xffff0000, v169
	v_add_f32_e32 v182, v182, v140
	v_add_f32_e32 v183, v183, v141
	v_add_f32_e32 v184, v184, v142
	v_add_f32_e32 v185, v185, v143
	v_lshlrev_b32_e32 v186, 16, v160
	v_and_b32_e32 v187, 0xffff0000, v160
	v_lshlrev_b32_e32 v188, 16, v161
	v_and_b32_e32 v189, 0xffff0000, v161
	v_fmac_f32_e32 v182, v164, v186
	v_fmac_f32_e32 v183, v165, v187
	v_fmac_f32_e32 v184, v166, v188
	v_fmac_f32_e32 v185, v167, v189
	v_mul_f32_e32 v186, 0x3d372713, v182
	v_mul_f32_e32 v187, 0x3d372713, v183
	v_mul_f32_e32 v188, 0x3d372713, v184
	v_mul_f32_e32 v189, 0x3d372713, v185
	v_mul_f32_e32 v186, v182, v186
	v_mul_f32_e32 v187, v183, v187
	v_mul_f32_e32 v188, v184, v188
	v_mul_f32_e32 v189, v185, v189
	v_fma_f32 v186, v182, v186, v182
	v_fma_f32 v187, v183, v187, v183
	v_fma_f32 v188, v184, v188, v184
	v_fma_f32 v189, v185, v189, v185
	v_mul_f32_e32 v186, 0xbfcc422a, v186
	v_mul_f32_e32 v187, 0xbfcc422a, v187
	v_mul_f32_e32 v188, 0xbfcc422a, v188
	v_mul_f32_e32 v189, 0xbfcc422a, v189
	v_mul_f32_e32 v186, 0x3fb8aa3b, v186
	v_mul_f32_e32 v187, 0x3fb8aa3b, v187
	v_mul_f32_e32 v188, 0x3fb8aa3b, v188
	v_mul_f32_e32 v189, 0x3fb8aa3b, v189
	v_exp_f32_e32 v186, v186
	v_exp_f32_e32 v187, v187
	v_exp_f32_e32 v188, v188
	v_exp_f32_e32 v189, v189
	v_add_f32_e32 v186, 1.0, v186
	v_add_f32_e32 v187, 1.0, v187
	v_add_f32_e32 v188, 1.0, v188
	v_add_f32_e32 v189, 1.0, v189
	v_rcp_f32_e32 v186, v186
	v_rcp_f32_e32 v187, v187
	v_rcp_f32_e32 v188, v188
	v_rcp_f32_e32 v189, v189
	v_mul_f32_e32 v182, v182, v186
	v_mul_f32_e32 v183, v183, v187
	v_mul_f32_e32 v184, v184, v188
	v_mul_f32_e32 v185, v185, v189
	v_cvt_pk_bf16_f32 v148, v182, v183
	v_cvt_pk_bf16_f32 v149, v184, v185
	global_store_dwordx2 v159, v[148:149], s[12:13]
	s_sub_u32 s12, s12, 65536
	s_subb_u32 s13, s13, 0
	s_sub_u32 s36, s36, 1024
	s_add_u32 s14, s14, 2
	s_cmp_lt_u32 s14, 8
	s_cbranch_scc1 .Lssm_tile_d1m2
	s_add_u32 s30, s30, 0x8000000
	s_add_u32 s16, s60, s30
	s_addc_u32 s17, s61, 0
	global_store_dword v180, v120, s[16:17]
	global_store_dword v180, v121, s[16:17] offset:64
	s_waitcnt vmcnt(0) lgkmcnt(0)
	s_add_u32 s27, s27, 1
	s_cmp_lt_u32 s27, 2
	s_cbranch_scc1 .Lssm_ctx_loop
